# GEMM priorities inverted: K-loop body at s_setprio 1, unit transition/epilogue at 0 (was 0 / 2); scan and ffn_conv keep waves 0-3 above waves 4-7
# baseline (speedup 1.0000x reference)
; #define PG8_STAGE(bufoff, gbase, voff) do { _Pragma("unroll") for (int _i = 0; _i < 2; ++_i) \
;         __builtin_amdgcn_global_load_lds((const unsigned*)((const char*)(gbase) + (voff)[_i]), (LAS unsigned*)(lds + (bufoff) + ldsw + _i * 8192), 16, 0, 0); } while (0)
; #define PG8_LDA(dst, b, h) do { _Pragma("unroll") for (int m = 0; m < 4; ++m) _Pragma("unroll") for (int k = 0; k < 2; ++k) dst[m][k] = *(const LAS bf16x8*)(lds + PG8_SA(b, h) + aoff + m * 2048 + k * 1024); } while (0)
; #define PG8_LDB(dst, b, h) do { _Pragma("unroll") for (int n = 0; n < 2; ++n) _Pragma("unroll") for (int k = 0; k < 2; ++k) dst[n][k] = *(const LAS bf16x8*)(lds + PG8_SB(b, h) + boff + n * 2048 + k * 1024); } while (0)
; #define PG8_MMA(ai, bj, At, Bt) do { __builtin_amdgcn_s_setprio(1); _Pragma("unroll") for (int m = 0; m < 4; ++m) _Pragma("unroll") for (int n = 0; n < 2; ++n) _Pragma("unroll") for (int k = 0; k < 2; ++k) \
;         acc[ai][bj][m][n] = __builtin_amdgcn_mfma_f32_16x16x32_bf16(Bt[n][k], At[m][k], acc[ai][bj][m][n], 0, 0, 0); __builtin_amdgcn_s_setprio(0); } while (0)
; #define PG8_WAIT_V(n) asm volatile("s_waitcnt vmcnt(" #n ")" ::: "memory")
; #define PG8_WAIT_L(n) asm volatile("s_waitcnt lgkmcnt(" #n ")" ::: "memory")
; #define PG8_BAR __builtin_amdgcn_s_barrier()
; #define PG8_SCHED __builtin_amdgcn_sched_barrier(0)
; template <class Epi, class Sched, bool ALIGN_EPI>
; __device__ __forceinline__ void gemm_phase(LAS unsigned char* lds, const int wid, const int lda_, const int ldb_, const int K_, const Sched& S, const Epi& E) {
;     ...
;         const bool has_next = S.next(ui + 1, nxt);
;         const int nt = S.nt(cur);
;         const char* nA = has_next ? S.a(nxt) : cA; const char* nB = has_next ? S.b(nxt) : cB;
; #pragma unroll 1
;         for (int t = 0; t < nt; t += 2) {
;             const bool last = (t == nt - 2);
;             const char* a1 = cA + (size_t)(t + 1) * kstep;
;             const char* a2 = last ? nA : cA + (size_t)(t + 2) * kstep; const char* b2 = last ? nB : cB + (size_t)(t + 2) * kstep;
;             const char* a3 = a2 + kstep; const char* b3 = b2 + kstep;
;             PG8_LDB(B0, 0, 0); PG8_LDB(B1, 0, 1); PG8_SCHED; PG8_LDA(At, 0, 0); PG8_STAGE(PG8_SA(1, 1), a1 + hstepA, voffA);
;             PG8_WAIT_V(8); PG8_WAIT_L(0); PG8_BAR; PG8_MMA(0, 0, At, B0); PG8_MMA(0, 1, At, B1); PG8_BAR; PG8_SCHED;
.LBB0_298:
	s_ashr_i32 s37, s36, 31
	s_xor_b64 s[40:41], s[4:5], -1
	s_lshl_b64 s[38:39], s[36:37], 20
	v_readlane_b32 s42, v253, 52
	v_readlane_b32 s43, v253, 53
	s_add_u32 s38, s42, s38
	s_addc_u32 s39, s43, s39
	s_and_b64 s[42:43], s[4:5], exec
	s_cselect_b32 s31, s39, s47
	s_cselect_b32 s37, s38, s46
	s_ashr_i32 s35, s34, 31
	s_lshl_b64 s[42:43], s[34:35], 20
	s_add_u32 s42, s7, s42
	s_addc_u32 s43, s14, s43
	s_and_b64 s[4:5], s[4:5], exec
	s_cselect_b32 s4, s43, s49
	s_cselect_b32 s5, s42, s48
	s_add_u32 s50, s46, 0x80
	s_addc_u32 s51, s47, 0
	s_add_u32 s35, s48, 0x100
	v_lshl_add_u64 v[156:157], s[50:51], 0, v[152:153]
	v_lshl_add_u64 v[158:159], s[50:51], 0, v[154:155]
	s_addc_u32 s45, s49, 0
	s_mov_b32 s76, -2
	s_mov_b64 s[48:49], 0
	s_add_u32 s17, s46, s48
	s_addc_u32 s27, s47, s49
	s_add_u32 s17, s17, 0x100
	s_addc_u32 s27, s27, 0
	s_add_u32 s77, s35, s48
	s_addc_u32 s78, s45, s49
	s_add_i32 s80, 0, 0x10000
	s_cmpk_eq_i32 s48, 0xf00
	s_cselect_b32 s51, s31, s27
	s_cselect_b32 s50, s37, s17
	v_add_u32_e32 v141, s80, v135
	s_cselect_b32 s79, s4, s78
	s_cselect_b32 s78, s5, s77
	s_add_i32 s17, 0, 0x14000
	ds_read_b128 v[160:163], v141
	ds_read_b128 v[164:167], v141 offset:1024
	ds_read_b128 v[168:171], v141 offset:2048
	ds_read_b128 v[172:175], v141 offset:3072
	v_add_u32_e32 v141, s17, v135
	ds_read_b128 v[180:183], v141
	ds_read_b128 v[184:187], v141 offset:1024
	ds_read_b128 v[188:191], v141 offset:2048
	ds_read_b128 v[192:195], v141 offset:3072
	v_lshl_add_u64 v[228:229], v[158:159], 0, s[48:49]
	s_add_i32 m0, s16, 0xc000
	ds_read_b128 v[196:199], v139
	ds_read_b128 v[200:203], v139 offset:1024
	ds_read_b128 v[204:207], v139 offset:2048
	ds_read_b128 v[208:211], v139 offset:3072
	ds_read_b128 v[212:215], v139 offset:4096
	ds_read_b128 v[216:219], v139 offset:5120
	ds_read_b128 v[220:223], v139 offset:6144
	ds_read_b128 v[224:227], v139 offset:7168
	global_load_lds_dwordx4 v[228:229], off
	v_lshl_add_u64 v[228:229], v[156:157], 0, s[48:49]
	s_add_i32 m0, s16, 0xe000
	s_nop 0
	global_load_lds_dwordx4 v[228:229], off
	s_waitcnt vmcnt(8)
	s_waitcnt lgkmcnt(0)
	s_barrier
	s_setprio 1
	s_waitcnt lgkmcnt(0)
	v_mfma_f32_16x16x32_bf16 v[124:127], v[160:163], v[196:199], 0
	v_mfma_f32_16x16x32_bf16 v[120:123], v[168:171], v[196:199], 0
	v_mfma_f32_16x16x32_bf16 v[116:119], v[160:163], v[204:207], 0
	v_mfma_f32_16x16x32_bf16 v[112:115], v[168:171], v[204:207], 0
	v_mfma_f32_16x16x32_bf16 v[100:103], v[160:163], v[212:215], 0
	v_mfma_f32_16x16x32_bf16 v[96:99], v[168:171], v[212:215], 0
	v_mfma_f32_16x16x32_bf16 v[84:87], v[160:163], v[220:223], 0
	v_mfma_f32_16x16x32_bf16 v[80:83], v[168:171], v[220:223], 0
	v_mfma_f32_16x16x32_bf16 v[124:127], v[164:167], v[200:203], v[124:127]
	v_mfma_f32_16x16x32_bf16 v[120:123], v[172:175], v[200:203], v[120:123]
	v_mfma_f32_16x16x32_bf16 v[116:119], v[164:167], v[208:211], v[116:119]
	v_mfma_f32_16x16x32_bf16 v[112:115], v[172:175], v[208:211], v[112:115]
	v_mfma_f32_16x16x32_bf16 v[100:103], v[164:167], v[216:219], v[100:103]
	v_mfma_f32_16x16x32_bf16 v[96:99], v[172:175], v[216:219], v[96:99]
	v_mfma_f32_16x16x32_bf16 v[84:87], v[164:167], v[224:227], v[84:87]
	v_mfma_f32_16x16x32_bf16 v[80:83], v[172:175], v[224:227], v[80:83]
	v_mfma_f32_16x16x32_bf16 v[108:111], v[180:183], v[196:199], 0
	v_mfma_f32_16x16x32_bf16 v[104:107], v[188:191], v[196:199], 0
	v_mfma_f32_16x16x32_bf16 v[92:95], v[180:183], v[204:207], 0
	v_mfma_f32_16x16x32_bf16 v[88:91], v[188:191], v[204:207], 0
	v_mfma_f32_16x16x32_bf16 v[76:79], v[180:183], v[212:215], 0
	v_mfma_f32_16x16x32_bf16 v[72:75], v[188:191], v[212:215], 0
	v_mfma_f32_16x16x32_bf16 v[68:71], v[180:183], v[220:223], 0
	v_mfma_f32_16x16x32_bf16 v[64:67], v[188:191], v[220:223], 0
	v_mfma_f32_16x16x32_bf16 v[108:111], v[184:187], v[200:203], v[108:111]
	v_mfma_f32_16x16x32_bf16 v[104:107], v[192:195], v[200:203], v[104:107]
	v_mfma_f32_16x16x32_bf16 v[92:95], v[184:187], v[208:211], v[92:95]
	v_mfma_f32_16x16x32_bf16 v[88:91], v[192:195], v[208:211], v[88:91]
	v_mfma_f32_16x16x32_bf16 v[76:79], v[184:187], v[216:219], v[76:79]
	v_mfma_f32_16x16x32_bf16 v[72:75], v[192:195], v[216:219], v[72:75]
	v_mfma_f32_16x16x32_bf16 v[68:71], v[184:187], v[224:227], v[68:71]
	v_mfma_f32_16x16x32_bf16 v[64:67], v[192:195], v[224:227], v[64:67]
	s_barrier
; #define PG8_STAGE(bufoff, gbase, voff) do { _Pragma("unroll") for (int _i = 0; _i < 2; ++_i) \
;         __builtin_amdgcn_global_load_lds((const unsigned*)((const char*)(gbase) + (voff)[_i]), (LAS unsigned*)(lds + (bufoff) + ldsw + _i * 8192), 16, 0, 0); } while (0)
; #define PG8_LDA(dst, b, h) do { _Pragma("unroll") for (int m = 0; m < 4; ++m) _Pragma("unroll") for (int k = 0; k < 2; ++k) dst[m][k] = *(const LAS bf16x8*)(lds + PG8_SA(b, h) + aoff + m * 2048 + k * 1024); } while (0)
; #define PG8_MMA(ai, bj, At, Bt) do { __builtin_amdgcn_s_setprio(1); _Pragma("unroll") for (int m = 0; m < 4; ++m) _Pragma("unroll") for (int n = 0; n < 2; ++n) _Pragma("unroll") for (int k = 0; k < 2; ++k) \
;         acc[ai][bj][m][n] = __builtin_amdgcn_mfma_f32_16x16x32_bf16(Bt[n][k], At[m][k], acc[ai][bj][m][n], 0, 0, 0); __builtin_amdgcn_s_setprio(0); } while (0)
; #define PG8_WAIT_V(n) asm volatile("s_waitcnt vmcnt(" #n ")" ::: "memory")
; #define PG8_WAIT_L(n) asm volatile("s_waitcnt lgkmcnt(" #n ")" ::: "memory")
; #define PG8_BAR __builtin_amdgcn_s_barrier()
; #define PG8_SCHED __builtin_amdgcn_sched_barrier(0)
; template <class Epi, class Sched, bool ALIGN_EPI>
; __device__ __forceinline__ void gemm_phase(LAS unsigned char* lds, const int wid, const int lda_, const int ldb_, const int K_, const Sched& S, const Epi& E) {
;     ...
;             PG8_LDA(At, 0, 1); PG8_STAGE(PG8_SB(0, 0), b2, voffB); PG8_STAGE(PG8_SB(0, 1), b2 + hstepB, voffB); PG8_STAGE(PG8_SA(0, 0), a2, voffA);
;             PG8_WAIT_V(8); PG8_WAIT_L(0); PG8_BAR; PG8_MMA(1, 0, At, B0); PG8_MMA(1, 1, At, B1); PG8_BAR; PG8_SCHED;
	s_add_i32 s27, s80, s3
	v_lshl_add_u64 v[228:229], s[78:79], 0, v[176:177]
	s_mov_b32 m0, s27
	ds_read_b128 v[196:199], v139 offset:16384
	ds_read_b128 v[200:203], v139 offset:17408
	ds_read_b128 v[204:207], v139 offset:18432
	ds_read_b128 v[208:211], v139 offset:19456
	ds_read_b128 v[212:215], v139 offset:20480
	ds_read_b128 v[216:219], v139 offset:21504
	ds_read_b128 v[220:223], v139 offset:22528
	ds_read_b128 v[224:227], v139 offset:23552
	global_load_lds_dwordx4 v[228:229], off
	s_add_i32 m0, s27, 0x2000
	v_lshl_add_u64 v[230:231], s[78:79], 0, v[128:129]
	s_add_u32 s78, s78, s10
	s_addc_u32 s79, s79, s11
	s_add_i32 s17, s17, s3
	global_load_lds_dwordx4 v[230:231], off
	v_lshl_add_u64 v[232:233], s[78:79], 0, v[176:177]
	s_mov_b32 m0, s17
	v_lshl_add_u64 v[234:235], s[78:79], 0, v[128:129]
	global_load_lds_dwordx4 v[232:233], off
	s_add_i32 m0, s17, 0x2000
	v_lshl_add_u64 v[236:237], s[50:51], 0, v[132:133]
	global_load_lds_dwordx4 v[234:235], off
	s_mov_b32 m0, s16
	v_lshl_add_u64 v[246:247], s[50:51], 0, v[130:131]
	global_load_lds_dwordx4 v[236:237], off
	s_mov_b32 m0, s15
	s_nop 0
	global_load_lds_dwordx4 v[246:247], off
	s_waitcnt vmcnt(8)
	s_waitcnt lgkmcnt(0)
	s_barrier
	s_waitcnt lgkmcnt(0)
	v_mfma_f32_16x16x32_bf16 v[60:63], v[160:163], v[196:199], 0
	v_mfma_f32_16x16x32_bf16 v[56:59], v[168:171], v[196:199], 0
	v_mfma_f32_16x16x32_bf16 v[52:55], v[160:163], v[204:207], 0
	v_mfma_f32_16x16x32_bf16 v[48:51], v[168:171], v[204:207], 0
	v_mfma_f32_16x16x32_bf16 v[36:39], v[160:163], v[212:215], 0
	v_mfma_f32_16x16x32_bf16 v[32:35], v[168:171], v[212:215], 0
	v_mfma_f32_16x16x32_bf16 v[20:23], v[160:163], v[220:223], 0
	v_mfma_f32_16x16x32_bf16 v[16:19], v[168:171], v[220:223], 0
	v_mfma_f32_16x16x32_bf16 v[60:63], v[164:167], v[200:203], v[60:63]
	v_mfma_f32_16x16x32_bf16 v[56:59], v[172:175], v[200:203], v[56:59]
	v_mfma_f32_16x16x32_bf16 v[52:55], v[164:167], v[208:211], v[52:55]
	v_mfma_f32_16x16x32_bf16 v[48:51], v[172:175], v[208:211], v[48:51]
	v_mfma_f32_16x16x32_bf16 v[36:39], v[164:167], v[216:219], v[36:39]
	v_mfma_f32_16x16x32_bf16 v[32:35], v[172:175], v[216:219], v[32:35]
	v_mfma_f32_16x16x32_bf16 v[20:23], v[164:167], v[224:227], v[20:23]
	v_mfma_f32_16x16x32_bf16 v[16:19], v[172:175], v[224:227], v[16:19]
	v_mfma_f32_16x16x32_bf16 v[44:47], v[180:183], v[196:199], 0
	v_mfma_f32_16x16x32_bf16 v[40:43], v[188:191], v[196:199], 0
	v_mfma_f32_16x16x32_bf16 v[28:31], v[180:183], v[204:207], 0
	v_mfma_f32_16x16x32_bf16 v[24:27], v[188:191], v[204:207], 0
	v_mfma_f32_16x16x32_bf16 v[12:15], v[180:183], v[212:215], 0
	v_mfma_f32_16x16x32_bf16 v[8:11], v[188:191], v[212:215], 0
	v_mfma_f32_16x16x32_bf16 v[4:7], v[180:183], v[220:223], 0
	v_mfma_f32_16x16x32_bf16 v[0:3], v[188:191], v[220:223], 0
	v_mfma_f32_16x16x32_bf16 v[44:47], v[184:187], v[200:203], v[44:47]
	v_mfma_f32_16x16x32_bf16 v[40:43], v[192:195], v[200:203], v[40:43]
	v_mfma_f32_16x16x32_bf16 v[28:31], v[184:187], v[208:211], v[28:31]
	v_mfma_f32_16x16x32_bf16 v[24:27], v[192:195], v[208:211], v[24:27]
	v_mfma_f32_16x16x32_bf16 v[12:15], v[184:187], v[216:219], v[12:15]
	v_mfma_f32_16x16x32_bf16 v[8:11], v[192:195], v[216:219], v[8:11]
	v_mfma_f32_16x16x32_bf16 v[4:7], v[184:187], v[224:227], v[4:7]
	v_mfma_f32_16x16x32_bf16 v[0:3], v[192:195], v[224:227], v[0:3]
	s_barrier
	s_branch .Lgemm_join_299

; #define PG8_STAGE(bufoff, gbase, voff) do { _Pragma("unroll") for (int _i = 0; _i < 2; ++_i) \
;         __builtin_amdgcn_global_load_lds((const unsigned*)((const char*)(gbase) + (voff)[_i]), (LAS unsigned*)(lds + (bufoff) + ldsw + _i * 8192), 16, 0, 0); } while (0)
; #define PG8_LDA(dst, b, h) do { _Pragma("unroll") for (int m = 0; m < 4; ++m) _Pragma("unroll") for (int k = 0; k < 2; ++k) dst[m][k] = *(const LAS bf16x8*)(lds + PG8_SA(b, h) + aoff + m * 2048 + k * 1024); } while (0)
; #define PG8_LDB(dst, b, h) do { _Pragma("unroll") for (int n = 0; n < 2; ++n) _Pragma("unroll") for (int k = 0; k < 2; ++k) dst[n][k] = *(const LAS bf16x8*)(lds + PG8_SB(b, h) + boff + n * 2048 + k * 1024); } while (0)
; #define PG8_MMA(ai, bj, At, Bt) do { __builtin_amdgcn_s_setprio(1); _Pragma("unroll") for (int m = 0; m < 4; ++m) _Pragma("unroll") for (int n = 0; n < 2; ++n) _Pragma("unroll") for (int k = 0; k < 2; ++k) \
;         acc[ai][bj][m][n] = __builtin_amdgcn_mfma_f32_16x16x32_bf16(Bt[n][k], At[m][k], acc[ai][bj][m][n], 0, 0, 0); __builtin_amdgcn_s_setprio(0); } while (0)
; #define PG8_WAIT_V(n) asm volatile("s_waitcnt vmcnt(" #n ")" ::: "memory")
; #define PG8_WAIT_L(n) asm volatile("s_waitcnt lgkmcnt(" #n ")" ::: "memory")
; #define PG8_BAR __builtin_amdgcn_s_barrier()
; #define PG8_SCHED __builtin_amdgcn_sched_barrier(0)
; template <class Epi, class Sched, bool ALIGN_EPI>
; __device__ __forceinline__ void gemm_phase(LAS unsigned char* lds, const int wid, const int lda_, const int ldb_, const int K_, const Sched& S, const Epi& E) {
;     ...
;             PG8_LDB(B0, 1, 0); PG8_LDB(B1, 1, 1); PG8_SCHED; PG8_LDA(At, 1, 0); PG8_STAGE(PG8_SA(0, 1), a2 + hstepA, voffA);
;             PG8_WAIT_V(8); PG8_WAIT_L(0); PG8_BAR; PG8_MMA(0, 0, At, B0); PG8_MMA(0, 1, At, B1); PG8_BAR; PG8_SCHED;
.Lgemm_join_299:
	s_add_i32 s17, 0, 0x18000
	v_add_u32_e32 v141, s17, v135
	s_add_i32 s27, 0, 0x1c000
	ds_read_b128 v[160:163], v141
	ds_read_b128 v[164:167], v141 offset:1024
	ds_read_b128 v[168:171], v141 offset:2048
	ds_read_b128 v[172:175], v141 offset:3072
	v_add_u32_e32 v141, s27, v135
	ds_read_b128 v[180:183], v141
	ds_read_b128 v[184:187], v141 offset:1024
	ds_read_b128 v[188:191], v141 offset:2048
	ds_read_b128 v[192:195], v141 offset:3072
	s_add_u32 s50, s50, s0
	s_addc_u32 s51, s51, s1
	s_mov_b32 m0, s26
	v_lshl_add_u64 v[248:249], s[50:51], 0, v[132:133]
	ds_read_b128 v[196:199], v139 offset:32768
	ds_read_b128 v[200:203], v139 offset:33792
	ds_read_b128 v[204:207], v139 offset:34816
	ds_read_b128 v[208:211], v139 offset:35840
	ds_read_b128 v[212:215], v139 offset:36864
	ds_read_b128 v[216:219], v139 offset:37888
	ds_read_b128 v[220:223], v139 offset:38912
	ds_read_b128 v[224:227], v139 offset:39936
	global_load_lds_dwordx4 v[248:249], off
	v_lshl_add_u64 v[248:249], s[50:51], 0, v[130:131]
	s_mov_b32 m0, s72
	s_nop 0
	global_load_lds_dwordx4 v[248:249], off
	s_waitcnt vmcnt(8)
	s_waitcnt lgkmcnt(0)
	s_barrier
	s_waitcnt lgkmcnt(0)
	v_mfma_f32_16x16x32_bf16 v[124:127], v[160:163], v[196:199], v[124:127]
	v_mfma_f32_16x16x32_bf16 v[120:123], v[168:171], v[196:199], v[120:123]
	v_mfma_f32_16x16x32_bf16 v[116:119], v[160:163], v[204:207], v[116:119]
	v_mfma_f32_16x16x32_bf16 v[112:115], v[168:171], v[204:207], v[112:115]
	v_mfma_f32_16x16x32_bf16 v[100:103], v[160:163], v[212:215], v[100:103]
	v_mfma_f32_16x16x32_bf16 v[96:99], v[168:171], v[212:215], v[96:99]
	v_mfma_f32_16x16x32_bf16 v[84:87], v[160:163], v[220:223], v[84:87]
	v_mfma_f32_16x16x32_bf16 v[80:83], v[168:171], v[220:223], v[80:83]
	v_mfma_f32_16x16x32_bf16 v[124:127], v[164:167], v[200:203], v[124:127]
	v_mfma_f32_16x16x32_bf16 v[120:123], v[172:175], v[200:203], v[120:123]
	v_mfma_f32_16x16x32_bf16 v[116:119], v[164:167], v[208:211], v[116:119]
	v_mfma_f32_16x16x32_bf16 v[112:115], v[172:175], v[208:211], v[112:115]
	v_mfma_f32_16x16x32_bf16 v[100:103], v[164:167], v[216:219], v[100:103]
	v_mfma_f32_16x16x32_bf16 v[96:99], v[172:175], v[216:219], v[96:99]
	v_mfma_f32_16x16x32_bf16 v[84:87], v[164:167], v[224:227], v[84:87]
	v_mfma_f32_16x16x32_bf16 v[80:83], v[172:175], v[224:227], v[80:83]
	v_mfma_f32_16x16x32_bf16 v[108:111], v[180:183], v[196:199], v[108:111]
	v_mfma_f32_16x16x32_bf16 v[104:107], v[188:191], v[196:199], v[104:107]
	v_mfma_f32_16x16x32_bf16 v[92:95], v[180:183], v[204:207], v[92:95]
	v_mfma_f32_16x16x32_bf16 v[88:91], v[188:191], v[204:207], v[88:91]
	v_mfma_f32_16x16x32_bf16 v[76:79], v[180:183], v[212:215], v[76:79]
	v_mfma_f32_16x16x32_bf16 v[72:75], v[188:191], v[212:215], v[72:75]
	v_mfma_f32_16x16x32_bf16 v[68:71], v[180:183], v[220:223], v[68:71]
	v_mfma_f32_16x16x32_bf16 v[64:67], v[188:191], v[220:223], v[64:67]
	v_mfma_f32_16x16x32_bf16 v[108:111], v[184:187], v[200:203], v[108:111]
	v_mfma_f32_16x16x32_bf16 v[104:107], v[192:195], v[200:203], v[104:107]
	v_mfma_f32_16x16x32_bf16 v[92:95], v[184:187], v[208:211], v[92:95]
	v_mfma_f32_16x16x32_bf16 v[88:91], v[192:195], v[208:211], v[88:91]
	v_mfma_f32_16x16x32_bf16 v[76:79], v[184:187], v[216:219], v[76:79]
	v_mfma_f32_16x16x32_bf16 v[72:75], v[192:195], v[216:219], v[72:75]
	v_mfma_f32_16x16x32_bf16 v[68:71], v[184:187], v[224:227], v[68:71]
	v_mfma_f32_16x16x32_bf16 v[64:67], v[192:195], v[224:227], v[64:67]
	s_barrier
; #define PG8_STAGE(bufoff, gbase, voff) do { _Pragma("unroll") for (int _i = 0; _i < 2; ++_i) \
;         __builtin_amdgcn_global_load_lds((const unsigned*)((const char*)(gbase) + (voff)[_i]), (LAS unsigned*)(lds + (bufoff) + ldsw + _i * 8192), 16, 0, 0); } while (0)
; #define PG8_LDA(dst, b, h) do { _Pragma("unroll") for (int m = 0; m < 4; ++m) _Pragma("unroll") for (int k = 0; k < 2; ++k) dst[m][k] = *(const LAS bf16x8*)(lds + PG8_SA(b, h) + aoff + m * 2048 + k * 1024); } while (0)
; #define PG8_MMA(ai, bj, At, Bt) do { __builtin_amdgcn_s_setprio(1); _Pragma("unroll") for (int m = 0; m < 4; ++m) _Pragma("unroll") for (int n = 0; n < 2; ++n) _Pragma("unroll") for (int k = 0; k < 2; ++k) \
;         acc[ai][bj][m][n] = __builtin_amdgcn_mfma_f32_16x16x32_bf16(Bt[n][k], At[m][k], acc[ai][bj][m][n], 0, 0, 0); __builtin_amdgcn_s_setprio(0); } while (0)
; #define PG8_WAIT_V(n) asm volatile("s_waitcnt vmcnt(" #n ")" ::: "memory")
; #define PG8_WAIT_L(n) asm volatile("s_waitcnt lgkmcnt(" #n ")" ::: "memory")
; #define PG8_BAR __builtin_amdgcn_s_barrier()
; #define PG8_SCHED __builtin_amdgcn_sched_barrier(0)
; template <class Epi, class Sched, bool ALIGN_EPI>
; __device__ __forceinline__ void gemm_phase(LAS unsigned char* lds, const int wid, const int lda_, const int ldb_, const int K_, const Sched& S, const Epi& E) {
;     ...
;             PG8_LDA(At, 1, 1); PG8_STAGE(PG8_SB(1, 0), b3, voffB); PG8_STAGE(PG8_SB(1, 1), b3 + hstepB, voffB); PG8_STAGE(PG8_SA(1, 0), a3, voffA);
;             PG8_WAIT_V(8); PG8_WAIT_L(0); PG8_BAR; PG8_MMA(1, 0, At, B0); PG8_MMA(1, 1, At, B1); PG8_BAR; PG8_SCHED;
;         }
;         if constexpr (ALIGN_EPI) { if (wr == 0) PG8_BAR; }
;         E(acc, cur, S, wr, wc, fr, fq);
;     __device__ __forceinline__ void out(const pg8::Unit& u, char*& o, int& ldo, int& kind) const {
;         if (u.pn < 24) { o = (char*)ws + WS_XBCP + ((size_t)u.pm * 256 * XBC + (size_t)u.pn * 256) * 2; ldo = XBC; kind = 0; }
;         else if (u.pn < 40) { o = (char*)ws + WS_Z + ((size_t)u.pm * 256 * DI + (size_t)(u.pn - 24) * 256) * 2; ldo = DI; kind = 0; }
;         else { o = (char*)ws + WS_DT + (size_t)u.pm * 256 * 128 * 4; ldo = 128; kind = 1; } }
	s_add_i32 s17, s17, s3
	v_lshl_add_u64 v[228:229], v[228:229], 0, s[24:25]
	s_mov_b32 m0, s17
	ds_read_b128 v[196:199], v139 offset:49152
	ds_read_b128 v[200:203], v139 offset:50176
	ds_read_b128 v[204:207], v139 offset:51200
	ds_read_b128 v[208:211], v139 offset:52224
	ds_read_b128 v[212:215], v139 offset:53248
	ds_read_b128 v[216:219], v139 offset:54272
	ds_read_b128 v[220:223], v139 offset:55296
	ds_read_b128 v[224:227], v139 offset:56320
	global_load_lds_dwordx4 v[228:229], off
	v_lshl_add_u64 v[228:229], v[230:231], 0, s[24:25]
	s_add_i32 m0, s17, 0x2000
	s_add_i32 s17, s27, s3
	global_load_lds_dwordx4 v[228:229], off
	v_lshl_add_u64 v[228:229], v[232:233], 0, s[24:25]
	s_mov_b32 m0, s17
	s_nop 0
	global_load_lds_dwordx4 v[228:229], off
	v_lshl_add_u64 v[228:229], v[234:235], 0, s[24:25]
	s_add_i32 m0, s17, 0x2000
	s_nop 0
	global_load_lds_dwordx4 v[228:229], off
	v_lshl_add_u64 v[228:229], v[236:237], 0, s[24:25]
	s_mov_b32 m0, s73
	s_nop 0
	global_load_lds_dwordx4 v[228:229], off
	v_lshl_add_u64 v[228:229], v[246:247], 0, s[24:25]
	s_mov_b32 m0, s74
	s_nop 0
	global_load_lds_dwordx4 v[228:229], off
	s_waitcnt vmcnt(8)
	s_waitcnt lgkmcnt(0)
	s_barrier
	s_waitcnt lgkmcnt(0)
	v_mfma_f32_16x16x32_bf16 v[60:63], v[160:163], v[196:199], v[60:63]
	v_mfma_f32_16x16x32_bf16 v[56:59], v[168:171], v[196:199], v[56:59]
	v_mfma_f32_16x16x32_bf16 v[52:55], v[160:163], v[204:207], v[52:55]
	v_mfma_f32_16x16x32_bf16 v[48:51], v[168:171], v[204:207], v[48:51]
	v_mfma_f32_16x16x32_bf16 v[36:39], v[160:163], v[212:215], v[36:39]
	v_mfma_f32_16x16x32_bf16 v[32:35], v[168:171], v[212:215], v[32:35]
	v_mfma_f32_16x16x32_bf16 v[20:23], v[160:163], v[220:223], v[20:23]
	v_mfma_f32_16x16x32_bf16 v[16:19], v[168:171], v[220:223], v[16:19]
	v_mfma_f32_16x16x32_bf16 v[60:63], v[164:167], v[200:203], v[60:63]
	v_mfma_f32_16x16x32_bf16 v[56:59], v[172:175], v[200:203], v[56:59]
	v_mfma_f32_16x16x32_bf16 v[52:55], v[164:167], v[208:211], v[52:55]
	v_mfma_f32_16x16x32_bf16 v[48:51], v[172:175], v[208:211], v[48:51]
	v_mfma_f32_16x16x32_bf16 v[36:39], v[164:167], v[216:219], v[36:39]
	v_mfma_f32_16x16x32_bf16 v[32:35], v[172:175], v[216:219], v[32:35]
	v_mfma_f32_16x16x32_bf16 v[20:23], v[164:167], v[224:227], v[20:23]
	v_mfma_f32_16x16x32_bf16 v[16:19], v[172:175], v[224:227], v[16:19]
	v_mfma_f32_16x16x32_bf16 v[44:47], v[180:183], v[196:199], v[44:47]
	v_mfma_f32_16x16x32_bf16 v[40:43], v[188:191], v[196:199], v[40:43]
	v_mfma_f32_16x16x32_bf16 v[28:31], v[180:183], v[204:207], v[28:31]
	v_mfma_f32_16x16x32_bf16 v[24:27], v[188:191], v[204:207], v[24:27]
	v_mfma_f32_16x16x32_bf16 v[12:15], v[180:183], v[212:215], v[12:15]
	v_mfma_f32_16x16x32_bf16 v[8:11], v[188:191], v[212:215], v[8:11]
	v_mfma_f32_16x16x32_bf16 v[4:7], v[180:183], v[220:223], v[4:7]
	v_mfma_f32_16x16x32_bf16 v[0:3], v[188:191], v[220:223], v[0:3]
	v_mfma_f32_16x16x32_bf16 v[44:47], v[184:187], v[200:203], v[44:47]
	v_mfma_f32_16x16x32_bf16 v[40:43], v[192:195], v[200:203], v[40:43]
	v_mfma_f32_16x16x32_bf16 v[28:31], v[184:187], v[208:211], v[28:31]
	v_mfma_f32_16x16x32_bf16 v[24:27], v[192:195], v[208:211], v[24:27]
	v_mfma_f32_16x16x32_bf16 v[12:15], v[184:187], v[216:219], v[12:15]
	v_mfma_f32_16x16x32_bf16 v[8:11], v[192:195], v[216:219], v[8:11]
	v_mfma_f32_16x16x32_bf16 v[4:7], v[184:187], v[224:227], v[4:7]
	v_mfma_f32_16x16x32_bf16 v[0:3], v[192:195], v[224:227], v[0:3]
	s_barrier
	s_add_i32 s76, s76, 2
	s_add_u32 s48, s48, 0x100
	s_addc_u32 s49, s49, 0
	s_cmp_gt_u32 s76, 29
	s_cbranch_scc0 .LBB0_299
	s_setprio 0
	s_sub_u32 s100, s30, 24
	s_cmp_lt_u32 s100, 16
	s_cselect_b32 s100, 1, 0
	s_ashr_i32 s45, s44, 31
	s_cmp_gt_i32 s30, 23
	s_mov_b64 s[48:49], -1
	s_cbranch_scc0 .LBB0_305
	s_cmp_gt_u32 s30, 39
	s_mov_b64 s[4:5], -1
	s_cbranch_scc0 .LBB0_303
	s_lshl_b64 s[4:5], s[44:45], 17
	v_readlane_b32 s46, v252, 60
	v_readlane_b32 s47, v252, 61
	s_add_u32 s46, s46, s4
	s_addc_u32 s47, s47, s5
	s_mov_b64 s[4:5], 0

;     __device__ __forceinline__ const char* b(const pg8::Unit& u) const { return (const char*)ws + boff + (size_t)u.pn * 256 * K_ * 2 + (u.kq < 0 ? 0 : u.kq * (K_ / 4) * 2); }
;     __device__ __forceinline__ const char* b(const pg8::Unit& u) const { return (const char*)ws + boff + (size_t)u.pn * 256 * D * 2; }
;     __device__ __forceinline__ const char* b(const pg8::Unit& u) const { return (const char*)ws + boff + (size_t)u.pn * 256 * D * 2; }
;     __device__ __forceinline__ const char* b(const pg8::Unit& u) const { return (const char*)ws + WS_A + ((size_t)u.pn * 256 * D + (size_t)(u.pm >> 1) * 256) * 2; }
; template <int MODE> __device__ __forceinline__ void ssd_scan_phase(Frame& F, int j, bool ctx_out) {
;     ...
;     for (int item = blockIdx.x; item < 256; item += F.G) {
;         const int ph = item & 1, dir = (item >> 1) & 1, g = (item >> 2) & 7, b = item >> 5, h = g * 8 + w;
.LBB0_472:
	s_cmp_ge_u32 s33, 0x100
	s_cbranch_scc1 .Lscan_prio_skip
	s_setprio 1

; #define PG8_STAGE(bufoff, gbase, voff) do { _Pragma("unroll") for (int _i = 0; _i < 2; ++_i) \
;         __builtin_amdgcn_global_load_lds((const unsigned*)((const char*)(gbase) + (voff)[_i]), (LAS unsigned*)(lds + (bufoff) + ldsw + _i * 8192), 16, 0, 0); } while (0)
; #define PG8_LDA(dst, b, h) do { _Pragma("unroll") for (int m = 0; m < 4; ++m) _Pragma("unroll") for (int k = 0; k < 2; ++k) dst[m][k] = *(const LAS bf16x8*)(lds + PG8_SA(b, h) + aoff + m * 2048 + k * 1024); } while (0)
; #define PG8_LDB(dst, b, h) do { _Pragma("unroll") for (int n = 0; n < 2; ++n) _Pragma("unroll") for (int k = 0; k < 2; ++k) dst[n][k] = *(const LAS bf16x8*)(lds + PG8_SB(b, h) + boff + n * 2048 + k * 1024); } while (0)
; #define PG8_MMA(ai, bj, At, Bt) do { __builtin_amdgcn_s_setprio(1); _Pragma("unroll") for (int m = 0; m < 4; ++m) _Pragma("unroll") for (int n = 0; n < 2; ++n) _Pragma("unroll") for (int k = 0; k < 2; ++k) \
;         acc[ai][bj][m][n] = __builtin_amdgcn_mfma_f32_16x16x32_bf16(Bt[n][k], At[m][k], acc[ai][bj][m][n], 0, 0, 0); __builtin_amdgcn_s_setprio(0); } while (0)
; #define PG8_WAIT_V(n) asm volatile("s_waitcnt vmcnt(" #n ")" ::: "memory")
; #define PG8_WAIT_L(n) asm volatile("s_waitcnt lgkmcnt(" #n ")" ::: "memory")
; #define PG8_BAR __builtin_amdgcn_s_barrier()
; #define PG8_SCHED __builtin_amdgcn_sched_barrier(0)
; template <class Epi, class Sched, bool ALIGN_EPI>
; __device__ __forceinline__ void gemm_phase(LAS unsigned char* lds, const int wid, const int lda_, const int ldb_, const int K_, const Sched& S, const Epi& E) {
;     ...
;         const bool has_next = S.next(ui + 1, nxt);
;         const int nt = S.nt(cur);
;         const char* nA = has_next ? S.a(nxt) : cA; const char* nB = has_next ? S.b(nxt) : cB;
; #pragma unroll 1
;         for (int t = 0; t < nt; t += 2) {
;             const bool last = (t == nt - 2);
;             const char* a1 = cA + (size_t)(t + 1) * kstep;
;             const char* a2 = last ? nA : cA + (size_t)(t + 2) * kstep; const char* b2 = last ? nB : cB + (size_t)(t + 2) * kstep;
;             const char* a3 = a2 + kstep; const char* b3 = b2 + kstep;
;             PG8_LDB(B0, 0, 0); PG8_LDB(B1, 0, 1); PG8_SCHED; PG8_LDA(At, 0, 0); PG8_STAGE(PG8_SA(1, 1), a1 + hstepA, voffA);
;             PG8_WAIT_V(8); PG8_WAIT_L(0); PG8_BAR; PG8_MMA(0, 0, At, B0); PG8_MMA(0, 1, At, B1); PG8_BAR; PG8_SCHED;
.LBB0_670:
	s_xor_b64 s[44:45], s[4:5], -1
	s_cmp_gt_i32 s38, -1
	s_cselect_b64 s[50:51], -1, 0
	s_cmp_lt_i32 s38, 0
	s_cselect_b32 s35, 64, 16
	s_max_i32 s17, s75, 0
	s_ashr_i32 s43, s42, 31
	s_lshl_b32 s17, s17, 11
	s_lshl_b64 s[46:47], s[42:43], 21
	v_readlane_b32 s48, v252, 62
	v_readlane_b32 s49, v252, 63
	s_add_u32 s27, s48, s46
	s_addc_u32 s37, s49, s47
	s_add_u32 s46, s27, s17
	s_addc_u32 s47, s37, 0
	s_and_b64 s[48:49], s[4:5], exec
	s_cselect_b32 s37, s47, s95
	s_cselect_b32 s39, s46, s94
	s_ashr_i32 s41, s40, 31
	s_lshl_b64 s[48:49], s[40:41], 21
	s_add_u32 s27, s6, s48
	s_addc_u32 s41, s7, s49
	s_add_u32 s48, s27, s17
	s_addc_u32 s49, s41, 0
	s_and_b64 s[4:5], s[4:5], exec
	s_cselect_b32 s4, s49, s97
	s_cselect_b32 s5, s48, s96
	s_add_i32 s41, s35, -2
	s_add_u32 s94, s94, 0x80
	s_addc_u32 s95, s95, 0
	s_add_u32 s43, s96, 0x100
	s_mov_b32 s77, 0
	s_addc_u32 s76, s97, 0
	s_add_i32 s78, s77, 2
	s_add_u32 s17, s94, 0x80
	s_addc_u32 s27, s95, 0
	s_add_i32 s79, 0, 0x10000
	s_cmp_eq_u32 s41, s77
	s_cselect_b32 s97, s37, s27
	s_cselect_b32 s96, s39, s17
	v_add_u32_e32 v141, s79, v135
	s_cselect_b32 s81, s4, s76
	s_cselect_b32 s80, s5, s43
	s_add_i32 s17, 0, 0x14000
	ds_read_b128 v[156:159], v141
	ds_read_b128 v[160:163], v141 offset:1024
	ds_read_b128 v[164:167], v141 offset:2048
	ds_read_b128 v[168:171], v141 offset:3072
	v_add_u32_e32 v141, s17, v135
	ds_read_b128 v[172:175], v141
	ds_read_b128 v[180:183], v141 offset:1024
	ds_read_b128 v[184:187], v141 offset:2048
	ds_read_b128 v[188:191], v141 offset:3072
	v_lshl_add_u64 v[224:225], s[94:95], 0, v[152:153]
	s_add_i32 m0, s16, 0xc000
	ds_read_b128 v[192:195], v139
	ds_read_b128 v[196:199], v139 offset:1024
	ds_read_b128 v[200:203], v139 offset:2048
	ds_read_b128 v[204:207], v139 offset:3072
	ds_read_b128 v[208:211], v139 offset:4096
	ds_read_b128 v[212:215], v139 offset:5120
	ds_read_b128 v[216:219], v139 offset:6144
	ds_read_b128 v[220:223], v139 offset:7168
	global_load_lds_dwordx4 v[224:225], off
	v_lshl_add_u64 v[224:225], s[94:95], 0, v[154:155]
	s_add_i32 m0, s16, 0xe000
	s_nop 0
	global_load_lds_dwordx4 v[224:225], off
	s_waitcnt vmcnt(8)
	s_waitcnt lgkmcnt(0)
	s_barrier
	s_setprio 1
	s_waitcnt lgkmcnt(0)
	v_mfma_f32_16x16x32_bf16 v[124:127], v[156:159], v[192:195], 0
	v_mfma_f32_16x16x32_bf16 v[120:123], v[164:167], v[192:195], 0
	v_mfma_f32_16x16x32_bf16 v[116:119], v[156:159], v[200:203], 0
	v_mfma_f32_16x16x32_bf16 v[112:115], v[164:167], v[200:203], 0
	v_mfma_f32_16x16x32_bf16 v[100:103], v[156:159], v[208:211], 0
	v_mfma_f32_16x16x32_bf16 v[96:99], v[164:167], v[208:211], 0
	v_mfma_f32_16x16x32_bf16 v[84:87], v[156:159], v[216:219], 0
	v_mfma_f32_16x16x32_bf16 v[80:83], v[164:167], v[216:219], 0
	v_mfma_f32_16x16x32_bf16 v[124:127], v[160:163], v[196:199], v[124:127]
	v_mfma_f32_16x16x32_bf16 v[120:123], v[168:171], v[196:199], v[120:123]
	v_mfma_f32_16x16x32_bf16 v[116:119], v[160:163], v[204:207], v[116:119]
	v_mfma_f32_16x16x32_bf16 v[112:115], v[168:171], v[204:207], v[112:115]
	v_mfma_f32_16x16x32_bf16 v[100:103], v[160:163], v[212:215], v[100:103]
	v_mfma_f32_16x16x32_bf16 v[96:99], v[168:171], v[212:215], v[96:99]
	v_mfma_f32_16x16x32_bf16 v[84:87], v[160:163], v[220:223], v[84:87]
	v_mfma_f32_16x16x32_bf16 v[80:83], v[168:171], v[220:223], v[80:83]
	v_mfma_f32_16x16x32_bf16 v[108:111], v[172:175], v[192:195], 0
	v_mfma_f32_16x16x32_bf16 v[104:107], v[184:187], v[192:195], 0
	v_mfma_f32_16x16x32_bf16 v[92:95], v[172:175], v[200:203], 0
	v_mfma_f32_16x16x32_bf16 v[88:91], v[184:187], v[200:203], 0
	v_mfma_f32_16x16x32_bf16 v[76:79], v[172:175], v[208:211], 0
	v_mfma_f32_16x16x32_bf16 v[72:75], v[184:187], v[208:211], 0
	v_mfma_f32_16x16x32_bf16 v[68:71], v[172:175], v[216:219], 0
	v_mfma_f32_16x16x32_bf16 v[64:67], v[184:187], v[216:219], 0
	v_mfma_f32_16x16x32_bf16 v[108:111], v[180:183], v[196:199], v[108:111]
	v_mfma_f32_16x16x32_bf16 v[104:107], v[188:191], v[196:199], v[104:107]
	v_mfma_f32_16x16x32_bf16 v[92:95], v[180:183], v[204:207], v[92:95]
	v_mfma_f32_16x16x32_bf16 v[88:91], v[188:191], v[204:207], v[88:91]
	v_mfma_f32_16x16x32_bf16 v[76:79], v[180:183], v[212:215], v[76:79]
	v_mfma_f32_16x16x32_bf16 v[72:75], v[188:191], v[212:215], v[72:75]
	v_mfma_f32_16x16x32_bf16 v[68:71], v[180:183], v[220:223], v[68:71]
	v_mfma_f32_16x16x32_bf16 v[64:67], v[188:191], v[220:223], v[64:67]
	s_barrier
; #define PG8_STAGE(bufoff, gbase, voff) do { _Pragma("unroll") for (int _i = 0; _i < 2; ++_i) \
;         __builtin_amdgcn_global_load_lds((const unsigned*)((const char*)(gbase) + (voff)[_i]), (LAS unsigned*)(lds + (bufoff) + ldsw + _i * 8192), 16, 0, 0); } while (0)
; #define PG8_LDA(dst, b, h) do { _Pragma("unroll") for (int m = 0; m < 4; ++m) _Pragma("unroll") for (int k = 0; k < 2; ++k) dst[m][k] = *(const LAS bf16x8*)(lds + PG8_SA(b, h) + aoff + m * 2048 + k * 1024); } while (0)
; #define PG8_MMA(ai, bj, At, Bt) do { __builtin_amdgcn_s_setprio(1); _Pragma("unroll") for (int m = 0; m < 4; ++m) _Pragma("unroll") for (int n = 0; n < 2; ++n) _Pragma("unroll") for (int k = 0; k < 2; ++k) \
;         acc[ai][bj][m][n] = __builtin_amdgcn_mfma_f32_16x16x32_bf16(Bt[n][k], At[m][k], acc[ai][bj][m][n], 0, 0, 0); __builtin_amdgcn_s_setprio(0); } while (0)
; #define PG8_WAIT_V(n) asm volatile("s_waitcnt vmcnt(" #n ")" ::: "memory")
; #define PG8_WAIT_L(n) asm volatile("s_waitcnt lgkmcnt(" #n ")" ::: "memory")
; #define PG8_BAR __builtin_amdgcn_s_barrier()
; #define PG8_SCHED __builtin_amdgcn_sched_barrier(0)
; template <class Epi, class Sched, bool ALIGN_EPI>
; __device__ __forceinline__ void gemm_phase(LAS unsigned char* lds, const int wid, const int lda_, const int ldb_, const int K_, const Sched& S, const Epi& E) {
;     ...
;             PG8_LDA(At, 0, 1); PG8_STAGE(PG8_SB(0, 0), b2, voffB); PG8_STAGE(PG8_SB(0, 1), b2 + hstepB, voffB); PG8_STAGE(PG8_SA(0, 0), a2, voffA);
;             PG8_WAIT_V(8); PG8_WAIT_L(0); PG8_BAR; PG8_MMA(1, 0, At, B0); PG8_MMA(1, 1, At, B1); PG8_BAR; PG8_SCHED;
	s_add_i32 s27, s79, s3
	v_lshl_add_u64 v[224:225], s[80:81], 0, v[176:177]
	s_mov_b32 m0, s27
	ds_read_b128 v[192:195], v139 offset:16384
	ds_read_b128 v[196:199], v139 offset:17408
	ds_read_b128 v[200:203], v139 offset:18432
	ds_read_b128 v[204:207], v139 offset:19456
	ds_read_b128 v[208:211], v139 offset:20480
	ds_read_b128 v[212:215], v139 offset:21504
	ds_read_b128 v[216:219], v139 offset:22528
	ds_read_b128 v[220:223], v139 offset:23552
	global_load_lds_dwordx4 v[224:225], off
	s_add_i32 m0, s27, 0x2000
	v_lshl_add_u64 v[226:227], s[80:81], 0, v[132:133]
	s_add_u32 s80, s80, s30
	s_addc_u32 s81, s81, s31
	s_add_i32 s17, s17, s3
	global_load_lds_dwordx4 v[226:227], off
	v_lshl_add_u64 v[228:229], s[80:81], 0, v[176:177]
	s_mov_b32 m0, s17
	v_lshl_add_u64 v[230:231], s[80:81], 0, v[132:133]
	global_load_lds_dwordx4 v[228:229], off
	s_add_i32 m0, s17, 0x2000
	v_lshl_add_u64 v[232:233], s[96:97], 0, v[128:129]
	global_load_lds_dwordx4 v[230:231], off
	s_mov_b32 m0, s16
	v_lshl_add_u64 v[234:235], s[96:97], 0, v[130:131]
	global_load_lds_dwordx4 v[232:233], off
	s_mov_b32 m0, s14
	s_nop 0
	global_load_lds_dwordx4 v[234:235], off
	s_waitcnt vmcnt(8)
	s_waitcnt lgkmcnt(0)
	s_barrier
	s_waitcnt lgkmcnt(0)
	v_mfma_f32_16x16x32_bf16 v[60:63], v[156:159], v[192:195], 0
	v_mfma_f32_16x16x32_bf16 v[56:59], v[164:167], v[192:195], 0
	v_mfma_f32_16x16x32_bf16 v[52:55], v[156:159], v[200:203], 0
	v_mfma_f32_16x16x32_bf16 v[48:51], v[164:167], v[200:203], 0
	v_mfma_f32_16x16x32_bf16 v[36:39], v[156:159], v[208:211], 0
	v_mfma_f32_16x16x32_bf16 v[32:35], v[164:167], v[208:211], 0
	v_mfma_f32_16x16x32_bf16 v[20:23], v[156:159], v[216:219], 0
	v_mfma_f32_16x16x32_bf16 v[16:19], v[164:167], v[216:219], 0
	v_mfma_f32_16x16x32_bf16 v[60:63], v[160:163], v[196:199], v[60:63]
	v_mfma_f32_16x16x32_bf16 v[56:59], v[168:171], v[196:199], v[56:59]
	v_mfma_f32_16x16x32_bf16 v[52:55], v[160:163], v[204:207], v[52:55]
	v_mfma_f32_16x16x32_bf16 v[48:51], v[168:171], v[204:207], v[48:51]
	v_mfma_f32_16x16x32_bf16 v[36:39], v[160:163], v[212:215], v[36:39]
	v_mfma_f32_16x16x32_bf16 v[32:35], v[168:171], v[212:215], v[32:35]
	v_mfma_f32_16x16x32_bf16 v[20:23], v[160:163], v[220:223], v[20:23]
	v_mfma_f32_16x16x32_bf16 v[16:19], v[168:171], v[220:223], v[16:19]
	v_mfma_f32_16x16x32_bf16 v[44:47], v[172:175], v[192:195], 0
	v_mfma_f32_16x16x32_bf16 v[40:43], v[184:187], v[192:195], 0
	v_mfma_f32_16x16x32_bf16 v[28:31], v[172:175], v[200:203], 0
	v_mfma_f32_16x16x32_bf16 v[24:27], v[184:187], v[200:203], 0
	v_mfma_f32_16x16x32_bf16 v[12:15], v[172:175], v[208:211], 0
	v_mfma_f32_16x16x32_bf16 v[8:11], v[184:187], v[208:211], 0
	v_mfma_f32_16x16x32_bf16 v[4:7], v[172:175], v[216:219], 0
	v_mfma_f32_16x16x32_bf16 v[0:3], v[184:187], v[216:219], 0
	v_mfma_f32_16x16x32_bf16 v[44:47], v[180:183], v[196:199], v[44:47]
	v_mfma_f32_16x16x32_bf16 v[40:43], v[188:191], v[196:199], v[40:43]
	v_mfma_f32_16x16x32_bf16 v[28:31], v[180:183], v[204:207], v[28:31]
	v_mfma_f32_16x16x32_bf16 v[24:27], v[188:191], v[204:207], v[24:27]
	v_mfma_f32_16x16x32_bf16 v[12:15], v[180:183], v[212:215], v[12:15]
	v_mfma_f32_16x16x32_bf16 v[8:11], v[188:191], v[212:215], v[8:11]
	v_mfma_f32_16x16x32_bf16 v[4:7], v[180:183], v[220:223], v[4:7]
	v_mfma_f32_16x16x32_bf16 v[0:3], v[188:191], v[220:223], v[0:3]
	s_barrier
	s_branch .Lgemm_join_671

; #define PG8_STAGE(bufoff, gbase, voff) do { _Pragma("unroll") for (int _i = 0; _i < 2; ++_i) \
;         __builtin_amdgcn_global_load_lds((const unsigned*)((const char*)(gbase) + (voff)[_i]), (LAS unsigned*)(lds + (bufoff) + ldsw + _i * 8192), 16, 0, 0); } while (0)
; #define PG8_LDA(dst, b, h) do { _Pragma("unroll") for (int m = 0; m < 4; ++m) _Pragma("unroll") for (int k = 0; k < 2; ++k) dst[m][k] = *(const LAS bf16x8*)(lds + PG8_SA(b, h) + aoff + m * 2048 + k * 1024); } while (0)
; #define PG8_LDB(dst, b, h) do { _Pragma("unroll") for (int n = 0; n < 2; ++n) _Pragma("unroll") for (int k = 0; k < 2; ++k) dst[n][k] = *(const LAS bf16x8*)(lds + PG8_SB(b, h) + boff + n * 2048 + k * 1024); } while (0)
; #define PG8_MMA(ai, bj, At, Bt) do { __builtin_amdgcn_s_setprio(1); _Pragma("unroll") for (int m = 0; m < 4; ++m) _Pragma("unroll") for (int n = 0; n < 2; ++n) _Pragma("unroll") for (int k = 0; k < 2; ++k) \
;         acc[ai][bj][m][n] = __builtin_amdgcn_mfma_f32_16x16x32_bf16(Bt[n][k], At[m][k], acc[ai][bj][m][n], 0, 0, 0); __builtin_amdgcn_s_setprio(0); } while (0)
; #define PG8_WAIT_V(n) asm volatile("s_waitcnt vmcnt(" #n ")" ::: "memory")
; #define PG8_WAIT_L(n) asm volatile("s_waitcnt lgkmcnt(" #n ")" ::: "memory")
; #define PG8_BAR __builtin_amdgcn_s_barrier()
; #define PG8_SCHED __builtin_amdgcn_sched_barrier(0)
; template <class Epi, class Sched, bool ALIGN_EPI>
; __device__ __forceinline__ void gemm_phase(LAS unsigned char* lds, const int wid, const int lda_, const int ldb_, const int K_, const Sched& S, const Epi& E) {
;     ...
;             PG8_LDB(B0, 1, 0); PG8_LDB(B1, 1, 1); PG8_SCHED; PG8_LDA(At, 1, 0); PG8_STAGE(PG8_SA(0, 1), a2 + hstepA, voffA);
;             PG8_WAIT_V(8); PG8_WAIT_L(0); PG8_BAR; PG8_MMA(0, 0, At, B0); PG8_MMA(0, 1, At, B1); PG8_BAR; PG8_SCHED;
.Lgemm_join_671:
	s_add_i32 s17, 0, 0x18000
	v_add_u32_e32 v141, s17, v135
	s_add_i32 s27, 0, 0x1c000
	ds_read_b128 v[156:159], v141
	ds_read_b128 v[160:163], v141 offset:1024
	ds_read_b128 v[164:167], v141 offset:2048
	ds_read_b128 v[168:171], v141 offset:3072
	v_add_u32_e32 v141, s27, v135
	ds_read_b128 v[172:175], v141
	ds_read_b128 v[180:183], v141 offset:1024
	ds_read_b128 v[184:187], v141 offset:2048
	ds_read_b128 v[188:191], v141 offset:3072
	s_add_u32 s80, s96, s10
	s_addc_u32 s81, s97, s11
	s_mov_b32 m0, s15
	v_lshl_add_u64 v[236:237], s[80:81], 0, v[128:129]
	ds_read_b128 v[192:195], v139 offset:32768
	ds_read_b128 v[196:199], v139 offset:33792
	ds_read_b128 v[200:203], v139 offset:34816
	ds_read_b128 v[204:207], v139 offset:35840
	ds_read_b128 v[208:211], v139 offset:36864
	ds_read_b128 v[212:215], v139 offset:37888
	ds_read_b128 v[216:219], v139 offset:38912
	ds_read_b128 v[220:223], v139 offset:39936
	global_load_lds_dwordx4 v[236:237], off
	v_lshl_add_u64 v[236:237], s[80:81], 0, v[130:131]
	s_mov_b32 m0, s26
	s_nop 0
	global_load_lds_dwordx4 v[236:237], off
	s_waitcnt vmcnt(8)
	s_waitcnt lgkmcnt(0)
	s_barrier
	s_waitcnt lgkmcnt(0)
	v_mfma_f32_16x16x32_bf16 v[124:127], v[156:159], v[192:195], v[124:127]
	v_mfma_f32_16x16x32_bf16 v[120:123], v[164:167], v[192:195], v[120:123]
	v_mfma_f32_16x16x32_bf16 v[116:119], v[156:159], v[200:203], v[116:119]
	v_mfma_f32_16x16x32_bf16 v[112:115], v[164:167], v[200:203], v[112:115]
	v_mfma_f32_16x16x32_bf16 v[100:103], v[156:159], v[208:211], v[100:103]
	v_mfma_f32_16x16x32_bf16 v[96:99], v[164:167], v[208:211], v[96:99]
	v_mfma_f32_16x16x32_bf16 v[84:87], v[156:159], v[216:219], v[84:87]
	v_mfma_f32_16x16x32_bf16 v[80:83], v[164:167], v[216:219], v[80:83]
	v_mfma_f32_16x16x32_bf16 v[124:127], v[160:163], v[196:199], v[124:127]
	v_mfma_f32_16x16x32_bf16 v[120:123], v[168:171], v[196:199], v[120:123]
	v_mfma_f32_16x16x32_bf16 v[116:119], v[160:163], v[204:207], v[116:119]
	v_mfma_f32_16x16x32_bf16 v[112:115], v[168:171], v[204:207], v[112:115]
	v_mfma_f32_16x16x32_bf16 v[100:103], v[160:163], v[212:215], v[100:103]
	v_mfma_f32_16x16x32_bf16 v[96:99], v[168:171], v[212:215], v[96:99]
	v_mfma_f32_16x16x32_bf16 v[84:87], v[160:163], v[220:223], v[84:87]
	v_mfma_f32_16x16x32_bf16 v[80:83], v[168:171], v[220:223], v[80:83]
	v_mfma_f32_16x16x32_bf16 v[108:111], v[172:175], v[192:195], v[108:111]
	v_mfma_f32_16x16x32_bf16 v[104:107], v[184:187], v[192:195], v[104:107]
	v_mfma_f32_16x16x32_bf16 v[92:95], v[172:175], v[200:203], v[92:95]
	v_mfma_f32_16x16x32_bf16 v[88:91], v[184:187], v[200:203], v[88:91]
	v_mfma_f32_16x16x32_bf16 v[76:79], v[172:175], v[208:211], v[76:79]
	v_mfma_f32_16x16x32_bf16 v[72:75], v[184:187], v[208:211], v[72:75]
	v_mfma_f32_16x16x32_bf16 v[68:71], v[172:175], v[216:219], v[68:71]
	v_mfma_f32_16x16x32_bf16 v[64:67], v[184:187], v[216:219], v[64:67]
	v_mfma_f32_16x16x32_bf16 v[108:111], v[180:183], v[196:199], v[108:111]
	v_mfma_f32_16x16x32_bf16 v[104:107], v[188:191], v[196:199], v[104:107]
	v_mfma_f32_16x16x32_bf16 v[92:95], v[180:183], v[204:207], v[92:95]
	v_mfma_f32_16x16x32_bf16 v[88:91], v[188:191], v[204:207], v[88:91]
	v_mfma_f32_16x16x32_bf16 v[76:79], v[180:183], v[212:215], v[76:79]
	v_mfma_f32_16x16x32_bf16 v[72:75], v[188:191], v[212:215], v[72:75]
	v_mfma_f32_16x16x32_bf16 v[68:71], v[180:183], v[220:223], v[68:71]
	v_mfma_f32_16x16x32_bf16 v[64:67], v[188:191], v[220:223], v[64:67]
	s_barrier
; #define PG8_STAGE(bufoff, gbase, voff) do { _Pragma("unroll") for (int _i = 0; _i < 2; ++_i) \
;         __builtin_amdgcn_global_load_lds((const unsigned*)((const char*)(gbase) + (voff)[_i]), (LAS unsigned*)(lds + (bufoff) + ldsw + _i * 8192), 16, 0, 0); } while (0)
; #define PG8_LDA(dst, b, h) do { _Pragma("unroll") for (int m = 0; m < 4; ++m) _Pragma("unroll") for (int k = 0; k < 2; ++k) dst[m][k] = *(const LAS bf16x8*)(lds + PG8_SA(b, h) + aoff + m * 2048 + k * 1024); } while (0)
; #define PG8_MMA(ai, bj, At, Bt) do { __builtin_amdgcn_s_setprio(1); _Pragma("unroll") for (int m = 0; m < 4; ++m) _Pragma("unroll") for (int n = 0; n < 2; ++n) _Pragma("unroll") for (int k = 0; k < 2; ++k) \
;         acc[ai][bj][m][n] = __builtin_amdgcn_mfma_f32_16x16x32_bf16(Bt[n][k], At[m][k], acc[ai][bj][m][n], 0, 0, 0); __builtin_amdgcn_s_setprio(0); } while (0)
; #define PG8_WAIT_V(n) asm volatile("s_waitcnt vmcnt(" #n ")" ::: "memory")
; #define PG8_WAIT_L(n) asm volatile("s_waitcnt lgkmcnt(" #n ")" ::: "memory")
; #define PG8_BAR __builtin_amdgcn_s_barrier()
; #define PG8_SCHED __builtin_amdgcn_sched_barrier(0)
; template <class Epi, class Sched, bool ALIGN_EPI>
; __device__ __forceinline__ void gemm_phase(LAS unsigned char* lds, const int wid, const int lda_, const int ldb_, const int K_, const Sched& S, const Epi& E) {
;     ...
;             PG8_LDA(At, 1, 1); PG8_STAGE(PG8_SB(1, 0), b3, voffB); PG8_STAGE(PG8_SB(1, 1), b3 + hstepB, voffB); PG8_STAGE(PG8_SA(1, 0), a3, voffA);
;             PG8_WAIT_V(8); PG8_WAIT_L(0); PG8_BAR; PG8_MMA(1, 0, At, B0); PG8_MMA(1, 1, At, B1); PG8_BAR; PG8_SCHED;
;         }
;         if constexpr (ALIGN_EPI) { if (wr == 0) PG8_BAR; }
;         E(acc, cur, S, wr, wc, fr, fq);
;     __device__ __forceinline__ void out(const pg8::Unit& u, char*& o, int& ldo, int& kind) const { ldo = D;
;         if (u.kq < 0) { o = (char*)ws + YOFF + ((size_t)u.pm * 256 * D + (size_t)u.pn * 256) * 2; kind = 0; }
;         else { o = (char*)ws + WS_PART + (((size_t)u.kq * MCTX + (size_t)(u.pm - 64) * 256) * D + (size_t)u.pn * 256) * 2; kind = 0; } }
	s_add_i32 s17, s17, s3
	v_lshl_add_u64 v[224:225], v[224:225], 0, s[24:25]
	s_mov_b32 m0, s17
	ds_read_b128 v[192:195], v139 offset:49152
	ds_read_b128 v[196:199], v139 offset:50176
	ds_read_b128 v[200:203], v139 offset:51200
	ds_read_b128 v[204:207], v139 offset:52224
	ds_read_b128 v[208:211], v139 offset:53248
	ds_read_b128 v[212:215], v139 offset:54272
	ds_read_b128 v[216:219], v139 offset:55296
	ds_read_b128 v[220:223], v139 offset:56320
	global_load_lds_dwordx4 v[224:225], off
	v_lshl_add_u64 v[224:225], v[226:227], 0, s[24:25]
	s_add_i32 m0, s17, 0x2000
	s_add_i32 s17, s27, s3
	global_load_lds_dwordx4 v[224:225], off
	v_lshl_add_u64 v[224:225], v[228:229], 0, s[24:25]
	s_mov_b32 m0, s17
	s_nop 0
	global_load_lds_dwordx4 v[224:225], off
	v_lshl_add_u64 v[224:225], v[230:231], 0, s[24:25]
	s_add_i32 m0, s17, 0x2000
	s_nop 0
	global_load_lds_dwordx4 v[224:225], off
	v_lshl_add_u64 v[224:225], v[232:233], 0, s[24:25]
	s_mov_b32 m0, s72
	s_nop 0
	global_load_lds_dwordx4 v[224:225], off
	v_lshl_add_u64 v[224:225], v[234:235], 0, s[24:25]
	s_mov_b32 m0, s73
	s_nop 0
	global_load_lds_dwordx4 v[224:225], off
	s_waitcnt vmcnt(8)
	s_waitcnt lgkmcnt(0)
	s_barrier
	s_waitcnt lgkmcnt(0)
	v_mfma_f32_16x16x32_bf16 v[60:63], v[156:159], v[192:195], v[60:63]
	v_mfma_f32_16x16x32_bf16 v[56:59], v[164:167], v[192:195], v[56:59]
	v_mfma_f32_16x16x32_bf16 v[52:55], v[156:159], v[200:203], v[52:55]
	v_mfma_f32_16x16x32_bf16 v[48:51], v[164:167], v[200:203], v[48:51]
	v_mfma_f32_16x16x32_bf16 v[36:39], v[156:159], v[208:211], v[36:39]
	v_mfma_f32_16x16x32_bf16 v[32:35], v[164:167], v[208:211], v[32:35]
	v_mfma_f32_16x16x32_bf16 v[20:23], v[156:159], v[216:219], v[20:23]
	v_mfma_f32_16x16x32_bf16 v[16:19], v[164:167], v[216:219], v[16:19]
	v_mfma_f32_16x16x32_bf16 v[60:63], v[160:163], v[196:199], v[60:63]
	v_mfma_f32_16x16x32_bf16 v[56:59], v[168:171], v[196:199], v[56:59]
	v_mfma_f32_16x16x32_bf16 v[52:55], v[160:163], v[204:207], v[52:55]
	v_mfma_f32_16x16x32_bf16 v[48:51], v[168:171], v[204:207], v[48:51]
	v_mfma_f32_16x16x32_bf16 v[36:39], v[160:163], v[212:215], v[36:39]
	v_mfma_f32_16x16x32_bf16 v[32:35], v[168:171], v[212:215], v[32:35]
	v_mfma_f32_16x16x32_bf16 v[20:23], v[160:163], v[220:223], v[20:23]
	v_mfma_f32_16x16x32_bf16 v[16:19], v[168:171], v[220:223], v[16:19]
	v_mfma_f32_16x16x32_bf16 v[44:47], v[172:175], v[192:195], v[44:47]
	v_mfma_f32_16x16x32_bf16 v[40:43], v[184:187], v[192:195], v[40:43]
	v_mfma_f32_16x16x32_bf16 v[28:31], v[172:175], v[200:203], v[28:31]
	v_mfma_f32_16x16x32_bf16 v[24:27], v[184:187], v[200:203], v[24:27]
	v_mfma_f32_16x16x32_bf16 v[12:15], v[172:175], v[208:211], v[12:15]
	v_mfma_f32_16x16x32_bf16 v[8:11], v[184:187], v[208:211], v[8:11]
	v_mfma_f32_16x16x32_bf16 v[4:7], v[172:175], v[216:219], v[4:7]
	v_mfma_f32_16x16x32_bf16 v[0:3], v[184:187], v[216:219], v[0:3]
	v_mfma_f32_16x16x32_bf16 v[44:47], v[180:183], v[196:199], v[44:47]
	v_mfma_f32_16x16x32_bf16 v[40:43], v[188:191], v[196:199], v[40:43]
	v_mfma_f32_16x16x32_bf16 v[28:31], v[180:183], v[204:207], v[28:31]
	v_mfma_f32_16x16x32_bf16 v[24:27], v[188:191], v[204:207], v[24:27]
	v_mfma_f32_16x16x32_bf16 v[12:15], v[180:183], v[212:215], v[12:15]
	v_mfma_f32_16x16x32_bf16 v[8:11], v[188:191], v[212:215], v[8:11]
	v_mfma_f32_16x16x32_bf16 v[4:7], v[180:183], v[220:223], v[4:7]
	v_mfma_f32_16x16x32_bf16 v[0:3], v[188:191], v[220:223], v[0:3]
	s_barrier
	s_add_u32 s94, s94, 0x100
	s_addc_u32 s95, s95, 0
	s_add_u32 s43, s43, 0x100
	s_addc_u32 s76, s76, 0
	s_cmp_ge_u32 s78, s35
	s_mov_b32 s77, s78
	s_cbranch_scc0 .LBB0_671
	s_setprio 0
	s_mov_b64 s[94:95], -1
	s_and_b64 vcc, exec, s[50:51]
	s_cbranch_vccz .LBB0_674
	s_mov_b32 s39, s92
	s_ashr_i32 s35, s34, 31
	s_ashr_i32 s37, s36, 31
	s_lshl_b64 s[4:5], s[34:35], 20
	s_lshl_b64 s[50:51], s[36:37], 9
	s_lshl_b64 s[38:39], s[38:39], 23
	v_readlane_b32 s76, v251, 28
	v_readlane_b32 s77, v251, 29
	s_add_u32 s17, s76, s50
	s_addc_u32 s27, s77, s51
	s_add_u32 s17, s17, s38
	s_addc_u32 s27, s27, s39
	s_add_u32 s4, s17, s4
	s_addc_u32 s5, s27, s5
	s_add_u32 s4, s4, 0xfc000000
	s_addc_u32 s5, s5, -1
	s_mov_b64 s[94:95], 0

; #define PG8_STAGE(bufoff, gbase, voff) do { _Pragma("unroll") for (int _i = 0; _i < 2; ++_i) \
;         __builtin_amdgcn_global_load_lds((const unsigned*)((const char*)(gbase) + (voff)[_i]), (LAS unsigned*)(lds + (bufoff) + ldsw + _i * 8192), 16, 0, 0); } while (0)
; #define PG8_LDA(dst, b, h) do { _Pragma("unroll") for (int m = 0; m < 4; ++m) _Pragma("unroll") for (int k = 0; k < 2; ++k) dst[m][k] = *(const LAS bf16x8*)(lds + PG8_SA(b, h) + aoff + m * 2048 + k * 1024); } while (0)
; #define PG8_LDB(dst, b, h) do { _Pragma("unroll") for (int n = 0; n < 2; ++n) _Pragma("unroll") for (int k = 0; k < 2; ++k) dst[n][k] = *(const LAS bf16x8*)(lds + PG8_SB(b, h) + boff + n * 2048 + k * 1024); } while (0)
; #define PG8_MMA(ai, bj, At, Bt) do { __builtin_amdgcn_s_setprio(1); _Pragma("unroll") for (int m = 0; m < 4; ++m) _Pragma("unroll") for (int n = 0; n < 2; ++n) _Pragma("unroll") for (int k = 0; k < 2; ++k) \
;         acc[ai][bj][m][n] = __builtin_amdgcn_mfma_f32_16x16x32_bf16(Bt[n][k], At[m][k], acc[ai][bj][m][n], 0, 0, 0); __builtin_amdgcn_s_setprio(0); } while (0)
; template <int NN> __device__ __forceinline__ bool tile2d(int i, int nM, Unit& u) {
;     const long L = (long)i * (int)gridDim.x + (int)blockIdx.x; if (L >= nM * NN) return false;
;     tile_of_id<NN>((int)L, nM, u.pm, u.pn); u.kq = -1; return true;
; template <class Epi, class Sched, bool ALIGN_EPI>
; __device__ __forceinline__ void gemm_phase(LAS unsigned char* lds, const int wid, const int lda_, const int ldb_, const int K_, const Sched& S, const Epi& E) {
;     ...
;         const bool has_next = S.next(ui + 1, nxt);
;         const int nt = S.nt(cur);
;         const char* nA = has_next ? S.a(nxt) : cA; const char* nB = has_next ? S.b(nxt) : cB;
; #pragma unroll 1
;         for (int t = 0; t < nt; t += 2) {
;             const bool last = (t == nt - 2);
;             const char* a1 = cA + (size_t)(t + 1) * kstep;
;             const char* a2 = last ? nA : cA + (size_t)(t + 2) * kstep; const char* b2 = last ? nB : cB + (size_t)(t + 2) * kstep;
;             const char* a3 = a2 + kstep; const char* b3 = b2 + kstep;
;             PG8_LDB(B0, 0, 0); PG8_LDB(B1, 0, 1); PG8_SCHED; PG8_LDA(At, 0, 0); PG8_STAGE(PG8_SA(1, 1), a1 + hstepA, voffA);
;             PG8_WAIT_V(8); PG8_WAIT_L(0); PG8_BAR; PG8_MMA(0, 0, At, B0); PG8_MMA(0, 1, At, B1); PG8_BAR; PG8_SCHED;
.LBB0_696:
	v_mov_b64_e32 v[0:1], 0x480
	v_cmp_lt_i64_e32 vcc, s[4:5], v[0:1]
	s_lshl_b32 s4, s73, 17
	s_and_b32 s4, s4, 0x20000
	v_readlane_b32 s5, v253, 31
	s_add_u32 s34, s5, s4
	v_readlane_b32 s4, v253, 32
	s_addc_u32 s35, s4, 0
	s_and_b64 s[4:5], vcc, exec
	s_cselect_b32 s4, s35, s45
	s_cselect_b32 s5, s34, s44
	s_ashr_i32 s36, s73, 1
	s_ashr_i32 s31, s30, 31
	s_ashr_i32 s37, s36, 31
	s_lshl_b64 s[36:37], s[36:37], 9
	s_lshl_b64 s[42:43], s[30:31], 20
	v_readlane_b32 s46, v253, 52
	v_readlane_b32 s47, v253, 53
	s_add_u32 s31, s46, s42
	s_addc_u32 s42, s47, s43
	s_add_u32 s36, s31, s36
	s_addc_u32 s37, s42, s37
	s_and_b64 s[42:43], vcc, exec
	s_cselect_b32 s31, s37, s41
	s_cselect_b32 s76, s36, s40
	s_mov_b64 s[50:51], 0
	s_mov_b64 s[46:47], -1
	s_mov_b64 s[48:49], 0
	s_add_u32 s77, s44, s50
	s_addc_u32 s78, s45, s51
	s_add_u32 s79, s77, 0x100
	s_addc_u32 s80, s78, 0
	s_and_b64 s[42:43], s[48:49], exec
	s_cselect_b32 s95, s4, s80
	s_cselect_b32 s94, s5, s79
	s_add_u32 s42, s40, s50
	s_addc_u32 s43, s41, s51
	s_add_u32 s50, s42, 0x100
	s_addc_u32 s51, s43, 0
	s_add_i32 s93, 0, 0x10000
	s_and_b64 s[42:43], s[48:49], exec
	s_cselect_b32 s51, s31, s51
	s_cselect_b32 s50, s76, s50
	s_add_i32 s42, 0, 0x14000
	v_add_u32_e32 v141, s93, v135
	s_add_u32 vcc_lo, s77, s0
	ds_read_b128 v[152:155], v141
	ds_read_b128 v[156:159], v141 offset:1024
	ds_read_b128 v[160:163], v141 offset:2048
	ds_read_b128 v[164:167], v141 offset:3072
	v_add_u32_e32 v141, s42, v135
	s_addc_u32 vcc_hi, s78, s1
	s_add_i32 s87, s93, s3
	ds_read_b128 v[168:171], v141
	ds_read_b128 v[172:175], v141 offset:1024
	ds_read_b128 v[180:183], v141 offset:2048
	ds_read_b128 v[184:187], v141 offset:3072
	s_add_i32 m0, s16, 0xc000
	s_add_i32 s27, s16, 0xe000
	s_add_i32 s80, s87, 0x2000
	s_add_u32 s96, s50, s10
	s_addc_u32 s97, s51, s11
	s_add_i32 s86, s42, s3
	s_add_i32 s81, s86, 0x2000
	s_add_i32 s79, 0, 0x18000
	s_add_i32 s78, 0, 0x1c000
	s_add_u32 s48, s94, s0
	s_addc_u32 s49, s95, s1
	s_add_i32 s77, s79, s3
	s_add_i32 s93, s78, s3
	s_add_i32 s43, s77, 0x2000
	s_add_i32 s42, s93, 0x2000
	v_lshl_add_u64 v[220:221], vcc, 0, v[132:133]
	v_lshl_add_u64 v[220:221], v[220:221], 0, s[24:25]
	ds_read_b128 v[188:191], v139
	ds_read_b128 v[192:195], v139 offset:1024
	ds_read_b128 v[196:199], v139 offset:2048
	ds_read_b128 v[200:203], v139 offset:3072
	ds_read_b128 v[204:207], v139 offset:4096
	ds_read_b128 v[208:211], v139 offset:5120
	ds_read_b128 v[212:215], v139 offset:6144
	ds_read_b128 v[216:219], v139 offset:7168
	global_load_lds_dwordx4 v[220:221], off
	v_lshl_add_u64 v[220:221], vcc, 0, v[130:131]
	v_lshl_add_u64 v[220:221], v[220:221], 0, s[24:25]
	s_mov_b32 m0, s27
	s_nop 0
	global_load_lds_dwordx4 v[220:221], off
	s_waitcnt vmcnt(8)
	s_waitcnt lgkmcnt(0)
	s_barrier
	s_setprio 1
	s_waitcnt lgkmcnt(0)
	v_mfma_f32_16x16x32_bf16 v[124:127], v[152:155], v[188:191], 0
	v_mfma_f32_16x16x32_bf16 v[120:123], v[160:163], v[188:191], 0
	v_mfma_f32_16x16x32_bf16 v[116:119], v[152:155], v[196:199], 0
	v_mfma_f32_16x16x32_bf16 v[112:115], v[160:163], v[196:199], 0
	v_mfma_f32_16x16x32_bf16 v[100:103], v[152:155], v[204:207], 0
	v_mfma_f32_16x16x32_bf16 v[96:99], v[160:163], v[204:207], 0
	v_mfma_f32_16x16x32_bf16 v[84:87], v[152:155], v[212:215], 0
	v_mfma_f32_16x16x32_bf16 v[80:83], v[160:163], v[212:215], 0
	v_mfma_f32_16x16x32_bf16 v[124:127], v[156:159], v[192:195], v[124:127]
	v_mfma_f32_16x16x32_bf16 v[120:123], v[164:167], v[192:195], v[120:123]
	v_mfma_f32_16x16x32_bf16 v[116:119], v[156:159], v[200:203], v[116:119]
	v_mfma_f32_16x16x32_bf16 v[112:115], v[164:167], v[200:203], v[112:115]
	v_mfma_f32_16x16x32_bf16 v[100:103], v[156:159], v[208:211], v[100:103]
	v_mfma_f32_16x16x32_bf16 v[96:99], v[164:167], v[208:211], v[96:99]
	v_mfma_f32_16x16x32_bf16 v[84:87], v[156:159], v[216:219], v[84:87]
	v_mfma_f32_16x16x32_bf16 v[80:83], v[164:167], v[216:219], v[80:83]
	v_mfma_f32_16x16x32_bf16 v[108:111], v[168:171], v[188:191], 0
	v_mfma_f32_16x16x32_bf16 v[104:107], v[180:183], v[188:191], 0
	v_mfma_f32_16x16x32_bf16 v[92:95], v[168:171], v[196:199], 0
	v_mfma_f32_16x16x32_bf16 v[88:91], v[180:183], v[196:199], 0
	v_mfma_f32_16x16x32_bf16 v[76:79], v[168:171], v[204:207], 0
	v_mfma_f32_16x16x32_bf16 v[72:75], v[180:183], v[204:207], 0
	v_mfma_f32_16x16x32_bf16 v[68:71], v[168:171], v[212:215], 0
	v_mfma_f32_16x16x32_bf16 v[64:67], v[180:183], v[212:215], 0
	v_mfma_f32_16x16x32_bf16 v[108:111], v[172:175], v[192:195], v[108:111]
	v_mfma_f32_16x16x32_bf16 v[104:107], v[184:187], v[192:195], v[104:107]
	v_mfma_f32_16x16x32_bf16 v[92:95], v[172:175], v[200:203], v[92:95]
	v_mfma_f32_16x16x32_bf16 v[88:91], v[184:187], v[200:203], v[88:91]
	v_mfma_f32_16x16x32_bf16 v[76:79], v[172:175], v[208:211], v[76:79]
	v_mfma_f32_16x16x32_bf16 v[72:75], v[184:187], v[208:211], v[72:75]
	v_mfma_f32_16x16x32_bf16 v[68:71], v[172:175], v[216:219], v[68:71]
	v_mfma_f32_16x16x32_bf16 v[64:67], v[184:187], v[216:219], v[64:67]
	s_barrier
; #define PG8_STAGE(bufoff, gbase, voff) do { _Pragma("unroll") for (int _i = 0; _i < 2; ++_i) \
;         __builtin_amdgcn_global_load_lds((const unsigned*)((const char*)(gbase) + (voff)[_i]), (LAS unsigned*)(lds + (bufoff) + ldsw + _i * 8192), 16, 0, 0); } while (0)
; #define PG8_LDA(dst, b, h) do { _Pragma("unroll") for (int m = 0; m < 4; ++m) _Pragma("unroll") for (int k = 0; k < 2; ++k) dst[m][k] = *(const LAS bf16x8*)(lds + PG8_SA(b, h) + aoff + m * 2048 + k * 1024); } while (0)
; #define PG8_MMA(ai, bj, At, Bt) do { __builtin_amdgcn_s_setprio(1); _Pragma("unroll") for (int m = 0; m < 4; ++m) _Pragma("unroll") for (int n = 0; n < 2; ++n) _Pragma("unroll") for (int k = 0; k < 2; ++k) \
;         acc[ai][bj][m][n] = __builtin_amdgcn_mfma_f32_16x16x32_bf16(Bt[n][k], At[m][k], acc[ai][bj][m][n], 0, 0, 0); __builtin_amdgcn_s_setprio(0); } while (0)
; #define PG8_WAIT_V(n) asm volatile("s_waitcnt vmcnt(" #n ")" ::: "memory")
; #define PG8_WAIT_L(n) asm volatile("s_waitcnt lgkmcnt(" #n ")" ::: "memory")
; #define PG8_BAR __builtin_amdgcn_s_barrier()
; #define PG8_SCHED __builtin_amdgcn_sched_barrier(0)
; template <class Epi, class Sched, bool ALIGN_EPI>
; __device__ __forceinline__ void gemm_phase(LAS unsigned char* lds, const int wid, const int lda_, const int ldb_, const int K_, const Sched& S, const Epi& E) {
;     ...
;             PG8_LDA(At, 0, 1); PG8_STAGE(PG8_SB(0, 0), b2, voffB); PG8_STAGE(PG8_SB(0, 1), b2 + hstepB, voffB); PG8_STAGE(PG8_SA(0, 0), a2, voffA);
;             PG8_WAIT_V(8); PG8_WAIT_L(0); PG8_BAR; PG8_MMA(1, 0, At, B0); PG8_MMA(1, 1, At, B1); PG8_BAR; PG8_SCHED;
	s_mov_b32 m0, s87
	v_lshl_add_u64 v[220:221], s[50:51], 0, v[176:177]
	ds_read_b128 v[188:191], v139 offset:16384
	ds_read_b128 v[192:195], v139 offset:17408
	ds_read_b128 v[196:199], v139 offset:18432
	ds_read_b128 v[200:203], v139 offset:19456
	ds_read_b128 v[204:207], v139 offset:20480
	ds_read_b128 v[208:211], v139 offset:21504
	ds_read_b128 v[212:215], v139 offset:22528
	ds_read_b128 v[216:219], v139 offset:23552
	global_load_lds_dwordx4 v[220:221], off
	v_lshl_add_u64 v[222:223], s[50:51], 0, v[128:129]
	s_mov_b32 m0, s80
	v_lshl_add_u64 v[224:225], s[96:97], 0, v[176:177]
	global_load_lds_dwordx4 v[222:223], off
	s_mov_b32 m0, s86
	v_lshl_add_u64 v[226:227], s[96:97], 0, v[128:129]
	global_load_lds_dwordx4 v[224:225], off
	s_mov_b32 m0, s81
	v_lshl_add_u64 v[228:229], s[94:95], 0, v[132:133]
	global_load_lds_dwordx4 v[226:227], off
	s_mov_b32 m0, s16
	v_lshl_add_u64 v[230:231], s[94:95], 0, v[130:131]
	global_load_lds_dwordx4 v[228:229], off
	s_mov_b32 m0, s6
	s_nop 0
	global_load_lds_dwordx4 v[230:231], off
	s_waitcnt vmcnt(8)
	s_waitcnt lgkmcnt(0)
	s_barrier
	s_waitcnt lgkmcnt(0)
	v_mfma_f32_16x16x32_bf16 v[60:63], v[152:155], v[188:191], 0
	v_mfma_f32_16x16x32_bf16 v[56:59], v[160:163], v[188:191], 0
	v_mfma_f32_16x16x32_bf16 v[52:55], v[152:155], v[196:199], 0
	v_mfma_f32_16x16x32_bf16 v[48:51], v[160:163], v[196:199], 0
	v_mfma_f32_16x16x32_bf16 v[36:39], v[152:155], v[204:207], 0
	v_mfma_f32_16x16x32_bf16 v[32:35], v[160:163], v[204:207], 0
	v_mfma_f32_16x16x32_bf16 v[20:23], v[152:155], v[212:215], 0
	v_mfma_f32_16x16x32_bf16 v[16:19], v[160:163], v[212:215], 0
	v_mfma_f32_16x16x32_bf16 v[60:63], v[156:159], v[192:195], v[60:63]
	v_mfma_f32_16x16x32_bf16 v[56:59], v[164:167], v[192:195], v[56:59]
	v_mfma_f32_16x16x32_bf16 v[52:55], v[156:159], v[200:203], v[52:55]
	v_mfma_f32_16x16x32_bf16 v[48:51], v[164:167], v[200:203], v[48:51]
	v_mfma_f32_16x16x32_bf16 v[36:39], v[156:159], v[208:211], v[36:39]
	v_mfma_f32_16x16x32_bf16 v[32:35], v[164:167], v[208:211], v[32:35]
	v_mfma_f32_16x16x32_bf16 v[20:23], v[156:159], v[216:219], v[20:23]
	v_mfma_f32_16x16x32_bf16 v[16:19], v[164:167], v[216:219], v[16:19]
	v_mfma_f32_16x16x32_bf16 v[44:47], v[168:171], v[188:191], 0
	v_mfma_f32_16x16x32_bf16 v[40:43], v[180:183], v[188:191], 0
	v_mfma_f32_16x16x32_bf16 v[28:31], v[168:171], v[196:199], 0
	v_mfma_f32_16x16x32_bf16 v[24:27], v[180:183], v[196:199], 0
	v_mfma_f32_16x16x32_bf16 v[12:15], v[168:171], v[204:207], 0
	v_mfma_f32_16x16x32_bf16 v[8:11], v[180:183], v[204:207], 0
	v_mfma_f32_16x16x32_bf16 v[4:7], v[168:171], v[212:215], 0
	v_mfma_f32_16x16x32_bf16 v[0:3], v[180:183], v[212:215], 0
	v_mfma_f32_16x16x32_bf16 v[44:47], v[172:175], v[192:195], v[44:47]
	v_mfma_f32_16x16x32_bf16 v[40:43], v[184:187], v[192:195], v[40:43]
	v_mfma_f32_16x16x32_bf16 v[28:31], v[172:175], v[200:203], v[28:31]
	v_mfma_f32_16x16x32_bf16 v[24:27], v[184:187], v[200:203], v[24:27]
	v_mfma_f32_16x16x32_bf16 v[12:15], v[172:175], v[208:211], v[12:15]
	v_mfma_f32_16x16x32_bf16 v[8:11], v[184:187], v[208:211], v[8:11]
	v_mfma_f32_16x16x32_bf16 v[4:7], v[172:175], v[216:219], v[4:7]
	v_mfma_f32_16x16x32_bf16 v[0:3], v[184:187], v[216:219], v[0:3]
	s_barrier
	s_branch .Lgemm_join_697

; #define PG8_STAGE(bufoff, gbase, voff) do { _Pragma("unroll") for (int _i = 0; _i < 2; ++_i) \
;         __builtin_amdgcn_global_load_lds((const unsigned*)((const char*)(gbase) + (voff)[_i]), (LAS unsigned*)(lds + (bufoff) + ldsw + _i * 8192), 16, 0, 0); } while (0)
; #define PG8_LDA(dst, b, h) do { _Pragma("unroll") for (int m = 0; m < 4; ++m) _Pragma("unroll") for (int k = 0; k < 2; ++k) dst[m][k] = *(const LAS bf16x8*)(lds + PG8_SA(b, h) + aoff + m * 2048 + k * 1024); } while (0)
; #define PG8_LDB(dst, b, h) do { _Pragma("unroll") for (int n = 0; n < 2; ++n) _Pragma("unroll") for (int k = 0; k < 2; ++k) dst[n][k] = *(const LAS bf16x8*)(lds + PG8_SB(b, h) + boff + n * 2048 + k * 1024); } while (0)
; #define PG8_MMA(ai, bj, At, Bt) do { __builtin_amdgcn_s_setprio(1); _Pragma("unroll") for (int m = 0; m < 4; ++m) _Pragma("unroll") for (int n = 0; n < 2; ++n) _Pragma("unroll") for (int k = 0; k < 2; ++k) \
;         acc[ai][bj][m][n] = __builtin_amdgcn_mfma_f32_16x16x32_bf16(Bt[n][k], At[m][k], acc[ai][bj][m][n], 0, 0, 0); __builtin_amdgcn_s_setprio(0); } while (0)
; #define PG8_WAIT_V(n) asm volatile("s_waitcnt vmcnt(" #n ")" ::: "memory")
; #define PG8_WAIT_L(n) asm volatile("s_waitcnt lgkmcnt(" #n ")" ::: "memory")
; #define PG8_BAR __builtin_amdgcn_s_barrier()
; #define PG8_SCHED __builtin_amdgcn_sched_barrier(0)
; template <class Epi, class Sched, bool ALIGN_EPI>
; __device__ __forceinline__ void gemm_phase(LAS unsigned char* lds, const int wid, const int lda_, const int ldb_, const int K_, const Sched& S, const Epi& E) {
;     ...
;             PG8_LDB(B0, 1, 0); PG8_LDB(B1, 1, 1); PG8_SCHED; PG8_LDA(At, 1, 0); PG8_STAGE(PG8_SA(0, 1), a2 + hstepA, voffA);
;             PG8_WAIT_V(8); PG8_WAIT_L(0); PG8_BAR; PG8_MMA(0, 0, At, B0); PG8_MMA(0, 1, At, B1); PG8_BAR; PG8_SCHED;
.Lgemm_join_697:
	v_add_u32_e32 v141, s79, v135
	ds_read_b128 v[152:155], v141
	ds_read_b128 v[156:159], v141 offset:1024
	ds_read_b128 v[160:163], v141 offset:2048
	ds_read_b128 v[164:167], v141 offset:3072
	v_add_u32_e32 v141, s78, v135
	ds_read_b128 v[168:171], v141
	ds_read_b128 v[172:175], v141 offset:1024
	ds_read_b128 v[180:183], v141 offset:2048
	ds_read_b128 v[184:187], v141 offset:3072
	s_mov_b32 m0, s7
	v_lshl_add_u64 v[232:233], s[48:49], 0, v[132:133]
	ds_read_b128 v[188:191], v139 offset:32768
	ds_read_b128 v[192:195], v139 offset:33792
	ds_read_b128 v[196:199], v139 offset:34816
	ds_read_b128 v[200:203], v139 offset:35840
	ds_read_b128 v[204:207], v139 offset:36864
	ds_read_b128 v[208:211], v139 offset:37888
	ds_read_b128 v[212:215], v139 offset:38912
	ds_read_b128 v[216:219], v139 offset:39936
	global_load_lds_dwordx4 v[232:233], off
	v_lshl_add_u64 v[232:233], s[48:49], 0, v[130:131]
	s_mov_b32 m0, s14
	s_nop 0
	global_load_lds_dwordx4 v[232:233], off
	s_waitcnt vmcnt(8)
	s_waitcnt lgkmcnt(0)
	s_barrier
	s_waitcnt lgkmcnt(0)
	v_mfma_f32_16x16x32_bf16 v[124:127], v[152:155], v[188:191], v[124:127]
	v_mfma_f32_16x16x32_bf16 v[120:123], v[160:163], v[188:191], v[120:123]
	v_mfma_f32_16x16x32_bf16 v[116:119], v[152:155], v[196:199], v[116:119]
	v_mfma_f32_16x16x32_bf16 v[112:115], v[160:163], v[196:199], v[112:115]
	v_mfma_f32_16x16x32_bf16 v[100:103], v[152:155], v[204:207], v[100:103]
	v_mfma_f32_16x16x32_bf16 v[96:99], v[160:163], v[204:207], v[96:99]
	v_mfma_f32_16x16x32_bf16 v[84:87], v[152:155], v[212:215], v[84:87]
	v_mfma_f32_16x16x32_bf16 v[80:83], v[160:163], v[212:215], v[80:83]
	v_mfma_f32_16x16x32_bf16 v[124:127], v[156:159], v[192:195], v[124:127]
	v_mfma_f32_16x16x32_bf16 v[120:123], v[164:167], v[192:195], v[120:123]
	v_mfma_f32_16x16x32_bf16 v[116:119], v[156:159], v[200:203], v[116:119]
	v_mfma_f32_16x16x32_bf16 v[112:115], v[164:167], v[200:203], v[112:115]
	v_mfma_f32_16x16x32_bf16 v[100:103], v[156:159], v[208:211], v[100:103]
	v_mfma_f32_16x16x32_bf16 v[96:99], v[164:167], v[208:211], v[96:99]
	v_mfma_f32_16x16x32_bf16 v[84:87], v[156:159], v[216:219], v[84:87]
	v_mfma_f32_16x16x32_bf16 v[80:83], v[164:167], v[216:219], v[80:83]
	v_mfma_f32_16x16x32_bf16 v[108:111], v[168:171], v[188:191], v[108:111]
	v_mfma_f32_16x16x32_bf16 v[104:107], v[180:183], v[188:191], v[104:107]
	v_mfma_f32_16x16x32_bf16 v[92:95], v[168:171], v[196:199], v[92:95]
	v_mfma_f32_16x16x32_bf16 v[88:91], v[180:183], v[196:199], v[88:91]
	v_mfma_f32_16x16x32_bf16 v[76:79], v[168:171], v[204:207], v[76:79]
	v_mfma_f32_16x16x32_bf16 v[72:75], v[180:183], v[204:207], v[72:75]
	v_mfma_f32_16x16x32_bf16 v[68:71], v[168:171], v[212:215], v[68:71]
	v_mfma_f32_16x16x32_bf16 v[64:67], v[180:183], v[212:215], v[64:67]
	v_mfma_f32_16x16x32_bf16 v[108:111], v[172:175], v[192:195], v[108:111]
	v_mfma_f32_16x16x32_bf16 v[104:107], v[184:187], v[192:195], v[104:107]
	v_mfma_f32_16x16x32_bf16 v[92:95], v[172:175], v[200:203], v[92:95]
	v_mfma_f32_16x16x32_bf16 v[88:91], v[184:187], v[200:203], v[88:91]
	v_mfma_f32_16x16x32_bf16 v[76:79], v[172:175], v[208:211], v[76:79]
	v_mfma_f32_16x16x32_bf16 v[72:75], v[184:187], v[208:211], v[72:75]
	v_mfma_f32_16x16x32_bf16 v[68:71], v[172:175], v[216:219], v[68:71]
	v_mfma_f32_16x16x32_bf16 v[64:67], v[184:187], v[216:219], v[64:67]
	s_barrier
; #define PG8_STAGE(bufoff, gbase, voff) do { _Pragma("unroll") for (int _i = 0; _i < 2; ++_i) \
;         __builtin_amdgcn_global_load_lds((const unsigned*)((const char*)(gbase) + (voff)[_i]), (LAS unsigned*)(lds + (bufoff) + ldsw + _i * 8192), 16, 0, 0); } while (0)
; #define PG8_LDA(dst, b, h) do { _Pragma("unroll") for (int m = 0; m < 4; ++m) _Pragma("unroll") for (int k = 0; k < 2; ++k) dst[m][k] = *(const LAS bf16x8*)(lds + PG8_SA(b, h) + aoff + m * 2048 + k * 1024); } while (0)
; #define PG8_MMA(ai, bj, At, Bt) do { __builtin_amdgcn_s_setprio(1); _Pragma("unroll") for (int m = 0; m < 4; ++m) _Pragma("unroll") for (int n = 0; n < 2; ++n) _Pragma("unroll") for (int k = 0; k < 2; ++k) \
;         acc[ai][bj][m][n] = __builtin_amdgcn_mfma_f32_16x16x32_bf16(Bt[n][k], At[m][k], acc[ai][bj][m][n], 0, 0, 0); __builtin_amdgcn_s_setprio(0); } while (0)
; #define PG8_WAIT_V(n) asm volatile("s_waitcnt vmcnt(" #n ")" ::: "memory")
; #define PG8_WAIT_L(n) asm volatile("s_waitcnt lgkmcnt(" #n ")" ::: "memory")
; #define PG8_BAR __builtin_amdgcn_s_barrier()
; #define PG8_SCHED __builtin_amdgcn_sched_barrier(0)
;     __device__ __forceinline__ const char* b(const pg8::Unit& u) const { return (const char*)ws + boff + (size_t)u.pn * 256 * K_ * 2 + (u.kq < 0 ? 0 : u.kq * (K_ / 4) * 2); }
; template <class Epi, class Sched, bool ALIGN_EPI>
; __device__ __forceinline__ void gemm_phase(LAS unsigned char* lds, const int wid, const int lda_, const int ldb_, const int K_, const Sched& S, const Epi& E) {
;     ...
;             PG8_LDA(At, 1, 1); PG8_STAGE(PG8_SB(1, 0), b3, voffB); PG8_STAGE(PG8_SB(1, 1), b3 + hstepB, voffB); PG8_STAGE(PG8_SA(1, 0), a3, voffA);
;             PG8_WAIT_V(8); PG8_WAIT_L(0); PG8_BAR; PG8_MMA(1, 0, At, B0); PG8_MMA(1, 1, At, B1); PG8_BAR; PG8_SCHED;
;         }
;         if constexpr (ALIGN_EPI) { if (wr == 0) PG8_BAR; }
;         E(acc, cur, S, wr, wc, fr, fq);
;     __device__ __forceinline__ void out(const pg8::Unit& u, char*& o, int& ldo, int& kind) const { const int g = u.pm >> 1, cs = u.pm & 1;
;         if (u.pn < 64) { const int b = u.pn >> 3, p0 = (u.pn & 7) * 256; o = (char*)ws + WS_PQT + (((size_t)(b * 2048 + g * 256)) * 4096 + (size_t)cs * 2048 + p0) * 2; ldo = 4096; }
;         else { const int b = u.pn - 64; o = (char*)ws + WS_PQTC + (((size_t)(b * 2048 + g * 256)) * 512 + (size_t)cs * 256) * 2; ldo = 512; }
	s_mov_b32 m0, s77
	v_lshl_add_u64 v[220:221], v[220:221], 0, s[24:25]
	ds_read_b128 v[188:191], v139 offset:49152
	ds_read_b128 v[192:195], v139 offset:50176
	ds_read_b128 v[196:199], v139 offset:51200
	ds_read_b128 v[200:203], v139 offset:52224
	ds_read_b128 v[204:207], v139 offset:53248
	ds_read_b128 v[208:211], v139 offset:54272
	ds_read_b128 v[212:215], v139 offset:55296
	ds_read_b128 v[216:219], v139 offset:56320
	global_load_lds_dwordx4 v[220:221], off
	v_lshl_add_u64 v[220:221], v[222:223], 0, s[24:25]
	s_mov_b32 m0, s43
	s_nop 0
	global_load_lds_dwordx4 v[220:221], off
	v_lshl_add_u64 v[220:221], v[224:225], 0, s[24:25]
	s_mov_b32 m0, s93
	s_nop 0
	global_load_lds_dwordx4 v[220:221], off
	v_lshl_add_u64 v[220:221], v[226:227], 0, s[24:25]
	s_mov_b32 m0, s42
	s_nop 0
	global_load_lds_dwordx4 v[220:221], off
	v_lshl_add_u64 v[220:221], v[228:229], 0, s[24:25]
	s_mov_b32 m0, s15
	s_nop 0
	global_load_lds_dwordx4 v[220:221], off
	v_lshl_add_u64 v[220:221], v[230:231], 0, s[24:25]
	s_mov_b32 m0, s26
	s_nop 0
	global_load_lds_dwordx4 v[220:221], off
	s_waitcnt vmcnt(8)
	s_waitcnt lgkmcnt(0)
	s_barrier
	s_waitcnt lgkmcnt(0)
	v_mfma_f32_16x16x32_bf16 v[60:63], v[152:155], v[188:191], v[60:63]
	v_mfma_f32_16x16x32_bf16 v[56:59], v[160:163], v[188:191], v[56:59]
	v_mfma_f32_16x16x32_bf16 v[52:55], v[152:155], v[196:199], v[52:55]
	v_mfma_f32_16x16x32_bf16 v[48:51], v[160:163], v[196:199], v[48:51]
	v_mfma_f32_16x16x32_bf16 v[36:39], v[152:155], v[204:207], v[36:39]
	v_mfma_f32_16x16x32_bf16 v[32:35], v[160:163], v[204:207], v[32:35]
	v_mfma_f32_16x16x32_bf16 v[20:23], v[152:155], v[212:215], v[20:23]
	v_mfma_f32_16x16x32_bf16 v[16:19], v[160:163], v[212:215], v[16:19]
	v_mfma_f32_16x16x32_bf16 v[60:63], v[156:159], v[192:195], v[60:63]
	v_mfma_f32_16x16x32_bf16 v[56:59], v[164:167], v[192:195], v[56:59]
	v_mfma_f32_16x16x32_bf16 v[52:55], v[156:159], v[200:203], v[52:55]
	v_mfma_f32_16x16x32_bf16 v[48:51], v[164:167], v[200:203], v[48:51]
	v_mfma_f32_16x16x32_bf16 v[36:39], v[156:159], v[208:211], v[36:39]
	v_mfma_f32_16x16x32_bf16 v[32:35], v[164:167], v[208:211], v[32:35]
	v_mfma_f32_16x16x32_bf16 v[20:23], v[156:159], v[216:219], v[20:23]
	v_mfma_f32_16x16x32_bf16 v[16:19], v[164:167], v[216:219], v[16:19]
	v_mfma_f32_16x16x32_bf16 v[44:47], v[168:171], v[188:191], v[44:47]
	v_mfma_f32_16x16x32_bf16 v[40:43], v[180:183], v[188:191], v[40:43]
	v_mfma_f32_16x16x32_bf16 v[28:31], v[168:171], v[196:199], v[28:31]
	v_mfma_f32_16x16x32_bf16 v[24:27], v[180:183], v[196:199], v[24:27]
	v_mfma_f32_16x16x32_bf16 v[12:15], v[168:171], v[204:207], v[12:15]
	v_mfma_f32_16x16x32_bf16 v[8:11], v[180:183], v[204:207], v[8:11]
	v_mfma_f32_16x16x32_bf16 v[4:7], v[168:171], v[212:215], v[4:7]
	v_mfma_f32_16x16x32_bf16 v[0:3], v[180:183], v[212:215], v[0:3]
	v_mfma_f32_16x16x32_bf16 v[44:47], v[172:175], v[192:195], v[44:47]
	v_mfma_f32_16x16x32_bf16 v[40:43], v[184:187], v[192:195], v[40:43]
	v_mfma_f32_16x16x32_bf16 v[28:31], v[172:175], v[200:203], v[28:31]
	v_mfma_f32_16x16x32_bf16 v[24:27], v[184:187], v[200:203], v[24:27]
	v_mfma_f32_16x16x32_bf16 v[12:15], v[172:175], v[208:211], v[12:15]
	v_mfma_f32_16x16x32_bf16 v[8:11], v[184:187], v[208:211], v[8:11]
	v_mfma_f32_16x16x32_bf16 v[4:7], v[172:175], v[216:219], v[4:7]
	v_mfma_f32_16x16x32_bf16 v[0:3], v[184:187], v[216:219], v[0:3]
	s_barrier
	s_andn2_b64 vcc, exec, s[46:47]
	s_mov_b64 s[48:49], -1
	s_mov_b64 s[46:47], 0
	s_mov_b64 s[50:51], 0x100
	s_cbranch_vccz .LBB0_697
	s_setprio 0
	s_ashr_i32 s43, s75, 1
	s_and_b32 s42, s75, 1
	s_cmp_gt_i32 s74, 63
	s_mov_b64 s[40:41], -1
	s_cbranch_scc0 .LBB0_700
	s_lshl_b32 s4, s74, 11
	s_lshl_b32 s5, s43, 8
	s_add_i32 s4, s4, s5
	s_add_i32 s4, s4, 0xfffe0000
	s_ashr_i32 s5, s4, 31
	s_lshl_b32 s31, s42, 9
	s_lshl_b64 s[4:5], s[4:5], 10
	v_readlane_b32 s17, v254, 2
	s_add_u32 s4, s17, s4
	v_readlane_b32 s17, v254, 3
	s_addc_u32 s5, s17, s5
	s_add_u32 s4, s4, s31
	s_addc_u32 s5, s5, 0
	s_mov_b64 s[40:41], 0

; #define PG8_STAGE(bufoff, gbase, voff) do { _Pragma("unroll") for (int _i = 0; _i < 2; ++_i) \
;         __builtin_amdgcn_global_load_lds((const unsigned*)((const char*)(gbase) + (voff)[_i]), (LAS unsigned*)(lds + (bufoff) + ldsw + _i * 8192), 16, 0, 0); } while (0)
; #define PG8_LDA(dst, b, h) do { _Pragma("unroll") for (int m = 0; m < 4; ++m) _Pragma("unroll") for (int k = 0; k < 2; ++k) dst[m][k] = *(const LAS bf16x8*)(lds + PG8_SA(b, h) + aoff + m * 2048 + k * 1024); } while (0)
; #define PG8_LDB(dst, b, h) do { _Pragma("unroll") for (int n = 0; n < 2; ++n) _Pragma("unroll") for (int k = 0; k < 2; ++k) dst[n][k] = *(const LAS bf16x8*)(lds + PG8_SB(b, h) + boff + n * 2048 + k * 1024); } while (0)
; #define PG8_MMA(ai, bj, At, Bt) do { __builtin_amdgcn_s_setprio(1); _Pragma("unroll") for (int m = 0; m < 4; ++m) _Pragma("unroll") for (int n = 0; n < 2; ++n) _Pragma("unroll") for (int k = 0; k < 2; ++k) \
;         acc[ai][bj][m][n] = __builtin_amdgcn_mfma_f32_16x16x32_bf16(Bt[n][k], At[m][k], acc[ai][bj][m][n], 0, 0, 0); __builtin_amdgcn_s_setprio(0); } while (0)
; #define PG8_WAIT_V(n) asm volatile("s_waitcnt vmcnt(" #n ")" ::: "memory")
; #define PG8_WAIT_L(n) asm volatile("s_waitcnt lgkmcnt(" #n ")" ::: "memory")
; #define PG8_BAR __builtin_amdgcn_s_barrier()
; #define PG8_SCHED __builtin_amdgcn_sched_barrier(0)
; template <class Epi, class Sched, bool ALIGN_EPI>
; __device__ __forceinline__ void gemm_phase(LAS unsigned char* lds, const int wid, const int lda_, const int ldb_, const int K_, const Sched& S, const Epi& E) {
;     ...
;         const bool has_next = S.next(ui + 1, nxt);
;         const int nt = S.nt(cur);
;         const char* nA = has_next ? S.a(nxt) : cA; const char* nB = has_next ? S.b(nxt) : cB;
; #pragma unroll 1
;         for (int t = 0; t < nt; t += 2) {
;             const bool last = (t == nt - 2);
;             const char* a1 = cA + (size_t)(t + 1) * kstep;
;             const char* a2 = last ? nA : cA + (size_t)(t + 2) * kstep; const char* b2 = last ? nB : cB + (size_t)(t + 2) * kstep;
;             const char* a3 = a2 + kstep; const char* b3 = b2 + kstep;
;             PG8_LDB(B0, 0, 0); PG8_LDB(B1, 0, 1); PG8_SCHED; PG8_LDA(At, 0, 0); PG8_STAGE(PG8_SA(1, 1), a1 + hstepA, voffA);
;             PG8_WAIT_V(8); PG8_WAIT_L(0); PG8_BAR; PG8_MMA(0, 0, At, B0); PG8_MMA(0, 1, At, B1); PG8_BAR; PG8_SCHED;
.LBB0_882:
	s_and_b64 s[4:5], s[4:5], exec
	s_cselect_b32 s4, s27, 0x380000
	s_add_u32 s44, s66, s4
	s_addc_u32 s45, s67, 0
	s_and_b64 s[4:5], s[50:51], exec
	s_cselect_b32 s4, s45, s47
	s_cselect_b32 s5, s44, s46
	s_add_u32 s42, s46, 0x80
	s_addc_u32 s43, s47, 0
	s_add_u32 s31, s48, 0x100
	v_lshl_add_u64 v[156:157], s[42:43], 0, v[152:153]
	v_lshl_add_u64 v[158:159], s[42:43], 0, v[154:155]
	s_addc_u32 s35, s49, 0
	s_mov_b32 s73, -2
	s_mov_b64 s[48:49], 0
	s_add_u32 s17, s46, s48
	s_addc_u32 s27, s47, s49
	s_add_u32 s17, s17, 0x100
	s_addc_u32 s27, s27, 0
	s_add_u32 s42, s31, s48
	s_addc_u32 s43, s35, s49
	s_add_i32 s74, 0, 0x10000
	s_cmpk_eq_i32 s48, 0x300
	s_cselect_b32 s51, s4, s27
	s_cselect_b32 s50, s5, s17
	v_add_u32_e32 v141, s74, v135
	s_cselect_b32 s43, s39, s43
	s_cselect_b32 s42, s38, s42
	s_add_i32 s17, 0, 0x14000
	ds_read_b128 v[160:163], v141
	ds_read_b128 v[164:167], v141 offset:1024
	ds_read_b128 v[168:171], v141 offset:2048
	ds_read_b128 v[172:175], v141 offset:3072
	v_add_u32_e32 v141, s17, v135
	ds_read_b128 v[180:183], v141
	ds_read_b128 v[184:187], v141 offset:1024
	ds_read_b128 v[188:191], v141 offset:2048
	ds_read_b128 v[192:195], v141 offset:3072
	v_lshl_add_u64 v[228:229], v[158:159], 0, s[48:49]
	s_add_i32 m0, s16, 0xc000
	ds_read_b128 v[196:199], v139
	ds_read_b128 v[200:203], v139 offset:1024
	ds_read_b128 v[204:207], v139 offset:2048
	ds_read_b128 v[208:211], v139 offset:3072
	ds_read_b128 v[212:215], v139 offset:4096
	ds_read_b128 v[216:219], v139 offset:5120
	ds_read_b128 v[220:223], v139 offset:6144
	ds_read_b128 v[224:227], v139 offset:7168
	global_load_lds_dwordx4 v[228:229], off
	v_lshl_add_u64 v[228:229], v[156:157], 0, s[48:49]
	s_add_i32 m0, s16, 0xe000
	s_nop 0
	global_load_lds_dwordx4 v[228:229], off
	s_waitcnt vmcnt(8)
	s_waitcnt lgkmcnt(0)
	s_barrier
	s_setprio 1
	s_waitcnt lgkmcnt(0)
	v_mfma_f32_16x16x32_bf16 v[124:127], v[160:163], v[196:199], 0
	v_mfma_f32_16x16x32_bf16 v[120:123], v[168:171], v[196:199], 0
	v_mfma_f32_16x16x32_bf16 v[116:119], v[160:163], v[204:207], 0
	v_mfma_f32_16x16x32_bf16 v[112:115], v[168:171], v[204:207], 0
	v_mfma_f32_16x16x32_bf16 v[100:103], v[160:163], v[212:215], 0
	v_mfma_f32_16x16x32_bf16 v[96:99], v[168:171], v[212:215], 0
	v_mfma_f32_16x16x32_bf16 v[84:87], v[160:163], v[220:223], 0
	v_mfma_f32_16x16x32_bf16 v[80:83], v[168:171], v[220:223], 0
	v_mfma_f32_16x16x32_bf16 v[124:127], v[164:167], v[200:203], v[124:127]
	v_mfma_f32_16x16x32_bf16 v[120:123], v[172:175], v[200:203], v[120:123]
	v_mfma_f32_16x16x32_bf16 v[116:119], v[164:167], v[208:211], v[116:119]
	v_mfma_f32_16x16x32_bf16 v[112:115], v[172:175], v[208:211], v[112:115]
	v_mfma_f32_16x16x32_bf16 v[100:103], v[164:167], v[216:219], v[100:103]
	v_mfma_f32_16x16x32_bf16 v[96:99], v[172:175], v[216:219], v[96:99]
	v_mfma_f32_16x16x32_bf16 v[84:87], v[164:167], v[224:227], v[84:87]
	v_mfma_f32_16x16x32_bf16 v[80:83], v[172:175], v[224:227], v[80:83]
	v_mfma_f32_16x16x32_bf16 v[108:111], v[180:183], v[196:199], 0
	v_mfma_f32_16x16x32_bf16 v[104:107], v[188:191], v[196:199], 0
	v_mfma_f32_16x16x32_bf16 v[92:95], v[180:183], v[204:207], 0
	v_mfma_f32_16x16x32_bf16 v[88:91], v[188:191], v[204:207], 0
	v_mfma_f32_16x16x32_bf16 v[76:79], v[180:183], v[212:215], 0
	v_mfma_f32_16x16x32_bf16 v[72:75], v[188:191], v[212:215], 0
	v_mfma_f32_16x16x32_bf16 v[68:71], v[180:183], v[220:223], 0
	v_mfma_f32_16x16x32_bf16 v[64:67], v[188:191], v[220:223], 0
	v_mfma_f32_16x16x32_bf16 v[108:111], v[184:187], v[200:203], v[108:111]
	v_mfma_f32_16x16x32_bf16 v[104:107], v[192:195], v[200:203], v[104:107]
	v_mfma_f32_16x16x32_bf16 v[92:95], v[184:187], v[208:211], v[92:95]
	v_mfma_f32_16x16x32_bf16 v[88:91], v[192:195], v[208:211], v[88:91]
	v_mfma_f32_16x16x32_bf16 v[76:79], v[184:187], v[216:219], v[76:79]
	v_mfma_f32_16x16x32_bf16 v[72:75], v[192:195], v[216:219], v[72:75]
	v_mfma_f32_16x16x32_bf16 v[68:71], v[184:187], v[224:227], v[68:71]
	v_mfma_f32_16x16x32_bf16 v[64:67], v[192:195], v[224:227], v[64:67]
	s_barrier
; #define PG8_STAGE(bufoff, gbase, voff) do { _Pragma("unroll") for (int _i = 0; _i < 2; ++_i) \
;         __builtin_amdgcn_global_load_lds((const unsigned*)((const char*)(gbase) + (voff)[_i]), (LAS unsigned*)(lds + (bufoff) + ldsw + _i * 8192), 16, 0, 0); } while (0)
; #define PG8_LDA(dst, b, h) do { _Pragma("unroll") for (int m = 0; m < 4; ++m) _Pragma("unroll") for (int k = 0; k < 2; ++k) dst[m][k] = *(const LAS bf16x8*)(lds + PG8_SA(b, h) + aoff + m * 2048 + k * 1024); } while (0)
; #define PG8_MMA(ai, bj, At, Bt) do { __builtin_amdgcn_s_setprio(1); _Pragma("unroll") for (int m = 0; m < 4; ++m) _Pragma("unroll") for (int n = 0; n < 2; ++n) _Pragma("unroll") for (int k = 0; k < 2; ++k) \
;         acc[ai][bj][m][n] = __builtin_amdgcn_mfma_f32_16x16x32_bf16(Bt[n][k], At[m][k], acc[ai][bj][m][n], 0, 0, 0); __builtin_amdgcn_s_setprio(0); } while (0)
; #define PG8_WAIT_V(n) asm volatile("s_waitcnt vmcnt(" #n ")" ::: "memory")
; #define PG8_WAIT_L(n) asm volatile("s_waitcnt lgkmcnt(" #n ")" ::: "memory")
; #define PG8_BAR __builtin_amdgcn_s_barrier()
; #define PG8_SCHED __builtin_amdgcn_sched_barrier(0)
; template <class Epi, class Sched, bool ALIGN_EPI>
; __device__ __forceinline__ void gemm_phase(LAS unsigned char* lds, const int wid, const int lda_, const int ldb_, const int K_, const Sched& S, const Epi& E) {
;     ...
;             PG8_LDA(At, 0, 1); PG8_STAGE(PG8_SB(0, 0), b2, voffB); PG8_STAGE(PG8_SB(0, 1), b2 + hstepB, voffB); PG8_STAGE(PG8_SA(0, 0), a2, voffA);
;             PG8_WAIT_V(8); PG8_WAIT_L(0); PG8_BAR; PG8_MMA(1, 0, At, B0); PG8_MMA(1, 1, At, B1); PG8_BAR; PG8_SCHED;
	s_add_i32 s27, s74, s3
	v_lshl_add_u64 v[228:229], s[42:43], 0, v[176:177]
	s_mov_b32 m0, s27
	ds_read_b128 v[196:199], v139 offset:16384
	ds_read_b128 v[200:203], v139 offset:17408
	ds_read_b128 v[204:207], v139 offset:18432
	ds_read_b128 v[208:211], v139 offset:19456
	ds_read_b128 v[212:215], v139 offset:20480
	ds_read_b128 v[216:219], v139 offset:21504
	ds_read_b128 v[220:223], v139 offset:22528
	ds_read_b128 v[224:227], v139 offset:23552
	global_load_lds_dwordx4 v[228:229], off
	s_add_i32 m0, s27, 0x2000
	v_lshl_add_u64 v[230:231], s[42:43], 0, v[132:133]
	s_add_u32 s42, s42, s10
	s_addc_u32 s43, s43, s11
	s_add_i32 s17, s17, s3
	global_load_lds_dwordx4 v[230:231], off
	v_lshl_add_u64 v[232:233], s[42:43], 0, v[176:177]
	s_mov_b32 m0, s17
	v_lshl_add_u64 v[234:235], s[42:43], 0, v[132:133]
	global_load_lds_dwordx4 v[232:233], off
	s_add_i32 m0, s17, 0x2000
	v_lshl_add_u64 v[236:237], s[50:51], 0, v[128:129]
	global_load_lds_dwordx4 v[234:235], off
	s_mov_b32 m0, s16
	v_lshl_add_u64 v[246:247], s[50:51], 0, v[130:131]
	global_load_lds_dwordx4 v[236:237], off
	s_mov_b32 m0, s6
	s_nop 0
	global_load_lds_dwordx4 v[246:247], off
	s_waitcnt vmcnt(8)
	s_waitcnt lgkmcnt(0)
	s_barrier
	s_waitcnt lgkmcnt(0)
	v_mfma_f32_16x16x32_bf16 v[60:63], v[160:163], v[196:199], 0
	v_mfma_f32_16x16x32_bf16 v[56:59], v[168:171], v[196:199], 0
	v_mfma_f32_16x16x32_bf16 v[52:55], v[160:163], v[204:207], 0
	v_mfma_f32_16x16x32_bf16 v[48:51], v[168:171], v[204:207], 0
	v_mfma_f32_16x16x32_bf16 v[36:39], v[160:163], v[212:215], 0
	v_mfma_f32_16x16x32_bf16 v[32:35], v[168:171], v[212:215], 0
	v_mfma_f32_16x16x32_bf16 v[20:23], v[160:163], v[220:223], 0
	v_mfma_f32_16x16x32_bf16 v[16:19], v[168:171], v[220:223], 0
	v_mfma_f32_16x16x32_bf16 v[60:63], v[164:167], v[200:203], v[60:63]
	v_mfma_f32_16x16x32_bf16 v[56:59], v[172:175], v[200:203], v[56:59]
	v_mfma_f32_16x16x32_bf16 v[52:55], v[164:167], v[208:211], v[52:55]
	v_mfma_f32_16x16x32_bf16 v[48:51], v[172:175], v[208:211], v[48:51]
	v_mfma_f32_16x16x32_bf16 v[36:39], v[164:167], v[216:219], v[36:39]
	v_mfma_f32_16x16x32_bf16 v[32:35], v[172:175], v[216:219], v[32:35]
	v_mfma_f32_16x16x32_bf16 v[20:23], v[164:167], v[224:227], v[20:23]
	v_mfma_f32_16x16x32_bf16 v[16:19], v[172:175], v[224:227], v[16:19]
	v_mfma_f32_16x16x32_bf16 v[44:47], v[180:183], v[196:199], 0
	v_mfma_f32_16x16x32_bf16 v[40:43], v[188:191], v[196:199], 0
	v_mfma_f32_16x16x32_bf16 v[28:31], v[180:183], v[204:207], 0
	v_mfma_f32_16x16x32_bf16 v[24:27], v[188:191], v[204:207], 0
	v_mfma_f32_16x16x32_bf16 v[12:15], v[180:183], v[212:215], 0
	v_mfma_f32_16x16x32_bf16 v[8:11], v[188:191], v[212:215], 0
	v_mfma_f32_16x16x32_bf16 v[4:7], v[180:183], v[220:223], 0
	v_mfma_f32_16x16x32_bf16 v[0:3], v[188:191], v[220:223], 0
	v_mfma_f32_16x16x32_bf16 v[44:47], v[184:187], v[200:203], v[44:47]
	v_mfma_f32_16x16x32_bf16 v[40:43], v[192:195], v[200:203], v[40:43]
	v_mfma_f32_16x16x32_bf16 v[28:31], v[184:187], v[208:211], v[28:31]
	v_mfma_f32_16x16x32_bf16 v[24:27], v[192:195], v[208:211], v[24:27]
	v_mfma_f32_16x16x32_bf16 v[12:15], v[184:187], v[216:219], v[12:15]
	v_mfma_f32_16x16x32_bf16 v[8:11], v[192:195], v[216:219], v[8:11]
	v_mfma_f32_16x16x32_bf16 v[4:7], v[184:187], v[224:227], v[4:7]
	v_mfma_f32_16x16x32_bf16 v[0:3], v[192:195], v[224:227], v[0:3]
	s_barrier
	s_branch .Lgemm_join_883

; #define PG8_STAGE(bufoff, gbase, voff) do { _Pragma("unroll") for (int _i = 0; _i < 2; ++_i) \
;         __builtin_amdgcn_global_load_lds((const unsigned*)((const char*)(gbase) + (voff)[_i]), (LAS unsigned*)(lds + (bufoff) + ldsw + _i * 8192), 16, 0, 0); } while (0)
; #define PG8_LDA(dst, b, h) do { _Pragma("unroll") for (int m = 0; m < 4; ++m) _Pragma("unroll") for (int k = 0; k < 2; ++k) dst[m][k] = *(const LAS bf16x8*)(lds + PG8_SA(b, h) + aoff + m * 2048 + k * 1024); } while (0)
; #define PG8_LDB(dst, b, h) do { _Pragma("unroll") for (int n = 0; n < 2; ++n) _Pragma("unroll") for (int k = 0; k < 2; ++k) dst[n][k] = *(const LAS bf16x8*)(lds + PG8_SB(b, h) + boff + n * 2048 + k * 1024); } while (0)
; #define PG8_MMA(ai, bj, At, Bt) do { __builtin_amdgcn_s_setprio(1); _Pragma("unroll") for (int m = 0; m < 4; ++m) _Pragma("unroll") for (int n = 0; n < 2; ++n) _Pragma("unroll") for (int k = 0; k < 2; ++k) \
;         acc[ai][bj][m][n] = __builtin_amdgcn_mfma_f32_16x16x32_bf16(Bt[n][k], At[m][k], acc[ai][bj][m][n], 0, 0, 0); __builtin_amdgcn_s_setprio(0); } while (0)
; #define PG8_WAIT_V(n) asm volatile("s_waitcnt vmcnt(" #n ")" ::: "memory")
; #define PG8_WAIT_L(n) asm volatile("s_waitcnt lgkmcnt(" #n ")" ::: "memory")
; #define PG8_BAR __builtin_amdgcn_s_barrier()
; #define PG8_SCHED __builtin_amdgcn_sched_barrier(0)
; template <class Epi, class Sched, bool ALIGN_EPI>
; __device__ __forceinline__ void gemm_phase(LAS unsigned char* lds, const int wid, const int lda_, const int ldb_, const int K_, const Sched& S, const Epi& E) {
;     ...
;             PG8_LDB(B0, 1, 0); PG8_LDB(B1, 1, 1); PG8_SCHED; PG8_LDA(At, 1, 0); PG8_STAGE(PG8_SA(0, 1), a2 + hstepA, voffA);
;             PG8_WAIT_V(8); PG8_WAIT_L(0); PG8_BAR; PG8_MMA(0, 0, At, B0); PG8_MMA(0, 1, At, B1); PG8_BAR; PG8_SCHED;
;             PG8_LDA(At, 1, 1); PG8_STAGE(PG8_SB(1, 0), b3, voffB); PG8_STAGE(PG8_SB(1, 1), b3 + hstepB, voffB); PG8_STAGE(PG8_SA(1, 0), a3, voffA);
;             PG8_WAIT_V(8); PG8_WAIT_L(0); PG8_BAR; PG8_MMA(1, 0, At, B0); PG8_MMA(1, 1, At, B1); PG8_BAR; PG8_SCHED;
.Lgemm_join_883:
	s_add_i32 s17, 0, 0x18000
	v_add_u32_e32 v141, s17, v135
	s_add_i32 s27, 0, 0x1c000
	ds_read_b128 v[160:163], v141
	ds_read_b128 v[164:167], v141 offset:1024
	ds_read_b128 v[168:171], v141 offset:2048
	ds_read_b128 v[172:175], v141 offset:3072
	v_add_u32_e32 v141, s27, v135
	ds_read_b128 v[180:183], v141
	ds_read_b128 v[184:187], v141 offset:1024
	ds_read_b128 v[188:191], v141 offset:2048
	ds_read_b128 v[192:195], v141 offset:3072
	s_add_u32 s42, s50, s0
	s_addc_u32 s43, s51, s1
	s_mov_b32 m0, s7
	v_lshl_add_u64 v[248:249], s[42:43], 0, v[128:129]
	ds_read_b128 v[196:199], v139 offset:32768
	ds_read_b128 v[200:203], v139 offset:33792
	ds_read_b128 v[204:207], v139 offset:34816
	ds_read_b128 v[208:211], v139 offset:35840
	ds_read_b128 v[212:215], v139 offset:36864
	ds_read_b128 v[216:219], v139 offset:37888
	ds_read_b128 v[220:223], v139 offset:38912
	ds_read_b128 v[224:227], v139 offset:39936
	global_load_lds_dwordx4 v[248:249], off
	v_lshl_add_u64 v[248:249], s[42:43], 0, v[130:131]
	s_mov_b32 m0, s14
	s_nop 0
	global_load_lds_dwordx4 v[248:249], off
	s_waitcnt vmcnt(8)
	s_waitcnt lgkmcnt(0)
	s_barrier
	s_waitcnt lgkmcnt(0)
	v_mfma_f32_16x16x32_bf16 v[124:127], v[160:163], v[196:199], v[124:127]
	v_mfma_f32_16x16x32_bf16 v[120:123], v[168:171], v[196:199], v[120:123]
	v_mfma_f32_16x16x32_bf16 v[116:119], v[160:163], v[204:207], v[116:119]
	v_mfma_f32_16x16x32_bf16 v[112:115], v[168:171], v[204:207], v[112:115]
	v_mfma_f32_16x16x32_bf16 v[100:103], v[160:163], v[212:215], v[100:103]
	v_mfma_f32_16x16x32_bf16 v[96:99], v[168:171], v[212:215], v[96:99]
	v_mfma_f32_16x16x32_bf16 v[84:87], v[160:163], v[220:223], v[84:87]
	v_mfma_f32_16x16x32_bf16 v[80:83], v[168:171], v[220:223], v[80:83]
	v_mfma_f32_16x16x32_bf16 v[124:127], v[164:167], v[200:203], v[124:127]
	v_mfma_f32_16x16x32_bf16 v[120:123], v[172:175], v[200:203], v[120:123]
	v_mfma_f32_16x16x32_bf16 v[116:119], v[164:167], v[208:211], v[116:119]
	v_mfma_f32_16x16x32_bf16 v[112:115], v[172:175], v[208:211], v[112:115]
	v_mfma_f32_16x16x32_bf16 v[100:103], v[164:167], v[216:219], v[100:103]
	v_mfma_f32_16x16x32_bf16 v[96:99], v[172:175], v[216:219], v[96:99]
	v_mfma_f32_16x16x32_bf16 v[84:87], v[164:167], v[224:227], v[84:87]
	v_mfma_f32_16x16x32_bf16 v[80:83], v[172:175], v[224:227], v[80:83]
	v_mfma_f32_16x16x32_bf16 v[108:111], v[180:183], v[196:199], v[108:111]
	v_mfma_f32_16x16x32_bf16 v[104:107], v[188:191], v[196:199], v[104:107]
	v_mfma_f32_16x16x32_bf16 v[92:95], v[180:183], v[204:207], v[92:95]
	v_mfma_f32_16x16x32_bf16 v[88:91], v[188:191], v[204:207], v[88:91]
	v_mfma_f32_16x16x32_bf16 v[76:79], v[180:183], v[212:215], v[76:79]
	v_mfma_f32_16x16x32_bf16 v[72:75], v[188:191], v[212:215], v[72:75]
	v_mfma_f32_16x16x32_bf16 v[68:71], v[180:183], v[220:223], v[68:71]
	v_mfma_f32_16x16x32_bf16 v[64:67], v[188:191], v[220:223], v[64:67]
	v_mfma_f32_16x16x32_bf16 v[108:111], v[184:187], v[200:203], v[108:111]
	v_mfma_f32_16x16x32_bf16 v[104:107], v[192:195], v[200:203], v[104:107]
	v_mfma_f32_16x16x32_bf16 v[92:95], v[184:187], v[208:211], v[92:95]
	v_mfma_f32_16x16x32_bf16 v[88:91], v[192:195], v[208:211], v[88:91]
	v_mfma_f32_16x16x32_bf16 v[76:79], v[184:187], v[216:219], v[76:79]
	v_mfma_f32_16x16x32_bf16 v[72:75], v[192:195], v[216:219], v[72:75]
	v_mfma_f32_16x16x32_bf16 v[68:71], v[184:187], v[224:227], v[68:71]
	v_mfma_f32_16x16x32_bf16 v[64:67], v[192:195], v[224:227], v[64:67]
	s_barrier
	s_add_i32 s17, s17, s3
	v_lshl_add_u64 v[228:229], v[228:229], 0, s[24:25]
	s_mov_b32 m0, s17
	ds_read_b128 v[196:199], v139 offset:49152
	ds_read_b128 v[200:203], v139 offset:50176
	ds_read_b128 v[204:207], v139 offset:51200
	ds_read_b128 v[208:211], v139 offset:52224
	ds_read_b128 v[212:215], v139 offset:53248
	ds_read_b128 v[216:219], v139 offset:54272
	ds_read_b128 v[220:223], v139 offset:55296
	ds_read_b128 v[224:227], v139 offset:56320
	global_load_lds_dwordx4 v[228:229], off
	v_lshl_add_u64 v[228:229], v[230:231], 0, s[24:25]
	s_add_i32 m0, s17, 0x2000
	s_add_i32 s17, s27, s3
	global_load_lds_dwordx4 v[228:229], off
	v_lshl_add_u64 v[228:229], v[232:233], 0, s[24:25]
	s_mov_b32 m0, s17
	s_nop 0
	global_load_lds_dwordx4 v[228:229], off
	v_lshl_add_u64 v[228:229], v[234:235], 0, s[24:25]
	s_add_i32 m0, s17, 0x2000
	s_nop 0
	global_load_lds_dwordx4 v[228:229], off
	v_lshl_add_u64 v[228:229], v[236:237], 0, s[24:25]
	s_mov_b32 m0, s15
	s_nop 0
	global_load_lds_dwordx4 v[228:229], off
	v_lshl_add_u64 v[228:229], v[246:247], 0, s[24:25]
	s_mov_b32 m0, s26
	s_nop 0
	global_load_lds_dwordx4 v[228:229], off
	s_waitcnt vmcnt(8)
	s_waitcnt lgkmcnt(0)
	s_barrier
; __device__ __forceinline__ unsigned cvt_pk_bf16(float lo, float hi) { const f32x2 v = {lo, hi}; return __builtin_bit_cast(unsigned, __builtin_convertvector(v, bf16x2_t)); }
; #define PG8_WAIT_V(n) asm volatile("s_waitcnt vmcnt(" #n ")" ::: "memory")
; #define PG8_WAIT_L(n) asm volatile("s_waitcnt lgkmcnt(" #n ")" ::: "memory")
; #define PG8_BAR __builtin_amdgcn_s_barrier()
; #define PG8_SCHED __builtin_amdgcn_sched_barrier(0)
;     template <class Sched> __device__ __forceinline__ void operator()(const f32x4 (&acc)[2][2][4][2], const Unit& u, const Sched& S, int wr, int wc, int fr, int fq) const {
;         const int rl0 = wr * 64 + fr, cl0 = wc * 32 + 8 * fq;
;         char* uo; int ldo, kind; S.out(u, uo, ldo, kind);
;         asm volatile("" : "+s"(ldo));
;         if (kind == 0) {
;             bf16_t* base = (bf16_t*)uo;
; #pragma unroll
;             for (int ai = 0; ai < 2; ++ai)
; #pragma unroll
;                 for (int m = 0; m < 4; ++m) { bf16_t* rowp = base + (size_t)(rl0 + ai * HALF + m * 16) * ldo + cl0;
; #pragma unroll
;                     for (int bj = 0; bj < 2; ++bj) { const f32x4 v0 = acc[ai][bj][m][0], v1 = acc[ai][bj][m][1];
;                         u32x4 w; w.x = cvt_pk_bf16(v0[0], v0[1]); w.y = cvt_pk_bf16(v0[2], v0[3]); w.z = cvt_pk_bf16(v1[0], v1[1]); w.w = cvt_pk_bf16(v1[2], v1[3]);
;                         *(u32x4*)(rowp + bj * HALF) = w; } }
; template <class Epi, class Sched, bool ALIGN_EPI>
; __device__ __forceinline__ void gemm_phase(LAS unsigned char* lds, const int wid, const int lda_, const int ldb_, const int K_, const Sched& S, const Epi& E) {
;     ...
;             PG8_WAIT_V(8); PG8_WAIT_L(0); PG8_BAR; PG8_MMA(1, 0, At, B0); PG8_MMA(1, 1, At, B1); PG8_BAR; PG8_SCHED;
;         }
;         if constexpr (ALIGN_EPI) { if (wr == 0) PG8_BAR; }
;         E(acc, cur, S, wr, wc, fr, fq);
;         if (!has_next) break;
; #pragma unroll
;         for (int a = 0; a < 2; ++a)
; #pragma unroll
;             for (int b = 0; b < 2; ++b)
; #pragma unroll
;                 for (int m = 0; m < 4; ++m)
; #pragma unroll
;                     for (int n = 0; n < 2; ++n) acc[a][b][m][n] = (f32x4){0.f, 0.f, 0.f, 0.f};
;         cur = nxt; cA = nA; cB = nB; ++ui;
;         if constexpr (ALIGN_EPI) { if (wr == 1) PG8_BAR; }
;     }
;     PG8_WAIT_V(0);
;     if constexpr (!ALIGN_EPI) { if (wr == 0) PG8_BAR; }
;     PG8_BAR;
	s_waitcnt lgkmcnt(0)
	v_mfma_f32_16x16x32_bf16 v[60:63], v[160:163], v[196:199], v[60:63]
	v_mfma_f32_16x16x32_bf16 v[56:59], v[168:171], v[196:199], v[56:59]
	v_mfma_f32_16x16x32_bf16 v[52:55], v[160:163], v[204:207], v[52:55]
	v_mfma_f32_16x16x32_bf16 v[48:51], v[168:171], v[204:207], v[48:51]
	v_mfma_f32_16x16x32_bf16 v[36:39], v[160:163], v[212:215], v[36:39]
	v_mfma_f32_16x16x32_bf16 v[32:35], v[168:171], v[212:215], v[32:35]
	v_mfma_f32_16x16x32_bf16 v[20:23], v[160:163], v[220:223], v[20:23]
	v_mfma_f32_16x16x32_bf16 v[16:19], v[168:171], v[220:223], v[16:19]
	v_mfma_f32_16x16x32_bf16 v[60:63], v[164:167], v[200:203], v[60:63]
	v_mfma_f32_16x16x32_bf16 v[56:59], v[172:175], v[200:203], v[56:59]
	v_mfma_f32_16x16x32_bf16 v[52:55], v[164:167], v[208:211], v[52:55]
	v_mfma_f32_16x16x32_bf16 v[48:51], v[172:175], v[208:211], v[48:51]
	v_mfma_f32_16x16x32_bf16 v[36:39], v[164:167], v[216:219], v[36:39]
	v_mfma_f32_16x16x32_bf16 v[32:35], v[172:175], v[216:219], v[32:35]
	v_mfma_f32_16x16x32_bf16 v[20:23], v[164:167], v[224:227], v[20:23]
	v_mfma_f32_16x16x32_bf16 v[16:19], v[172:175], v[224:227], v[16:19]
	v_mfma_f32_16x16x32_bf16 v[44:47], v[180:183], v[196:199], v[44:47]
	v_mfma_f32_16x16x32_bf16 v[40:43], v[188:191], v[196:199], v[40:43]
	v_mfma_f32_16x16x32_bf16 v[28:31], v[180:183], v[204:207], v[28:31]
	v_mfma_f32_16x16x32_bf16 v[24:27], v[188:191], v[204:207], v[24:27]
	v_mfma_f32_16x16x32_bf16 v[12:15], v[180:183], v[212:215], v[12:15]
	v_mfma_f32_16x16x32_bf16 v[8:11], v[188:191], v[212:215], v[8:11]
	v_mfma_f32_16x16x32_bf16 v[4:7], v[180:183], v[220:223], v[4:7]
	v_mfma_f32_16x16x32_bf16 v[0:3], v[188:191], v[220:223], v[0:3]
	v_mfma_f32_16x16x32_bf16 v[44:47], v[184:187], v[200:203], v[44:47]
	v_mfma_f32_16x16x32_bf16 v[40:43], v[192:195], v[200:203], v[40:43]
	v_mfma_f32_16x16x32_bf16 v[28:31], v[184:187], v[208:211], v[28:31]
	v_mfma_f32_16x16x32_bf16 v[24:27], v[192:195], v[208:211], v[24:27]
	v_mfma_f32_16x16x32_bf16 v[12:15], v[184:187], v[216:219], v[12:15]
	v_mfma_f32_16x16x32_bf16 v[8:11], v[192:195], v[216:219], v[8:11]
	v_mfma_f32_16x16x32_bf16 v[4:7], v[184:187], v[224:227], v[4:7]
	v_mfma_f32_16x16x32_bf16 v[0:3], v[192:195], v[224:227], v[0:3]
	s_barrier
	s_add_i32 s73, s73, 2
	s_add_u32 s48, s48, 0x100
	s_addc_u32 s49, s49, 0
	s_cmp_gt_u32 s73, 5
	s_cbranch_scc0 .LBB0_883
	s_setprio 0
	s_lshl_b32 s4, s41, 8
	s_and_b32 s5, s4, 0xfffff800
	s_and_b32 s17, s41, 7
	s_or_b32 s17, s5, s17
	s_ashr_i32 s5, s17, 31
	s_cmp_lt_i32 s41, 64
	s_cselect_b32 s4, s17, s4
	s_movk_i32 s17, 0x800
	s_cselect_b32 s5, s5, 0
	s_cselect_b32 s17, 0x4000, s17
	s_ashr_i32 s41, s40, 31
	s_lshl_b64 s[40:41], s[40:41], 9
	s_lshl_b64 s[4:5], s[4:5], 12
	v_readlane_b32 s27, v254, 19
	s_add_u32 s4, s27, s4
	v_readlane_b32 s27, v254, 20
	s_addc_u32 s5, s27, s5
	s_add_u32 s4, s4, s40
	s_addc_u32 s5, s5, s41
	v_lshl_add_u64 v[156:157], v[136:137], 1, s[4:5]
	v_mad_i64_i32 v[158:159], s[4:5], s17, v134, 0
	v_lshl_add_u64 v[158:159], v[158:159], 1, v[156:157]
	v_cvt_pk_bf16_f32 v108, v108, v109
	v_cvt_pk_bf16_f32 v109, v110, v111
	v_cvt_pk_bf16_f32 v110, v104, v105
	v_cvt_pk_bf16_f32 v111, v106, v107
	v_mad_i64_i32 v[104:105], s[4:5], s17, v138, 0
	v_cvt_pk_bf16_f32 v124, v124, v125
	v_cvt_pk_bf16_f32 v125, v126, v127
	v_cvt_pk_bf16_f32 v126, v120, v121
	v_cvt_pk_bf16_f32 v127, v122, v123
	global_store_dwordx4 v[158:159], v[108:111], off offset:256
	v_cvt_pk_bf16_f32 v92, v92, v93
	v_cvt_pk_bf16_f32 v93, v94, v95
	v_lshl_add_u64 v[108:109], v[104:105], 1, v[156:157]
	v_cvt_pk_bf16_f32 v94, v88, v89
	v_cvt_pk_bf16_f32 v95, v90, v91
	v_mad_i64_i32 v[88:89], s[4:5], s17, v140, 0
	global_store_dwordx4 v[158:159], v[124:127], off
	v_cvt_pk_bf16_f32 v104, v116, v117
	v_cvt_pk_bf16_f32 v105, v118, v119
	v_cvt_pk_bf16_f32 v106, v112, v113
	v_cvt_pk_bf16_f32 v107, v114, v115
	global_store_dwordx4 v[108:109], v[92:95], off offset:256
	v_cvt_pk_bf16_f32 v76, v76, v77
	v_cvt_pk_bf16_f32 v77, v78, v79
	v_lshl_add_u64 v[92:93], v[88:89], 1, v[156:157]
	v_cvt_pk_bf16_f32 v78, v72, v73
	v_cvt_pk_bf16_f32 v79, v74, v75
	v_mad_i64_i32 v[72:73], s[4:5], s17, v142, 0
	v_cvt_pk_bf16_f32 v68, v68, v69
	v_cvt_pk_bf16_f32 v69, v70, v71
	v_cvt_pk_bf16_f32 v70, v64, v65
	v_mad_i64_i32 v[64:65], s[4:5], s17, v144, 0
	global_store_dwordx4 v[108:109], v[104:107], off
	v_cvt_pk_bf16_f32 v88, v100, v101
	v_cvt_pk_bf16_f32 v89, v102, v103
	v_cvt_pk_bf16_f32 v90, v96, v97
	v_cvt_pk_bf16_f32 v91, v98, v99
	global_store_dwordx4 v[92:93], v[76:79], off offset:256
	v_cvt_pk_bf16_f32 v74, v80, v81
	v_cvt_pk_bf16_f32 v75, v82, v83
	v_lshl_add_u64 v[76:77], v[72:73], 1, v[156:157]
	v_cvt_pk_bf16_f32 v72, v84, v85
	v_cvt_pk_bf16_f32 v73, v86, v87
	v_cvt_pk_bf16_f32 v71, v66, v67
	v_lshl_add_u64 v[64:65], v[64:65], 1, v[156:157]
	v_cvt_pk_bf16_f32 v44, v44, v45
	v_cvt_pk_bf16_f32 v45, v46, v47
	v_cvt_pk_bf16_f32 v46, v40, v41
	v_cvt_pk_bf16_f32 v47, v42, v43
	v_mad_i64_i32 v[40:41], s[4:5], s17, v146, 0
	global_store_dwordx4 v[92:93], v[88:91], off
	global_store_dwordx4 v[76:77], v[72:75], off
	global_store_dwordx4 v[76:77], v[68:71], off offset:256
	v_cvt_pk_bf16_f32 v60, v60, v61
	v_cvt_pk_bf16_f32 v61, v62, v63
	v_cvt_pk_bf16_f32 v62, v56, v57
	v_cvt_pk_bf16_f32 v63, v58, v59
	global_store_dwordx4 v[64:65], v[44:47], off offset:256
	v_cvt_pk_bf16_f32 v28, v28, v29
	v_cvt_pk_bf16_f32 v29, v30, v31
	v_lshl_add_u64 v[44:45], v[40:41], 1, v[156:157]
	v_cvt_pk_bf16_f32 v30, v24, v25
	v_cvt_pk_bf16_f32 v31, v26, v27
	v_mad_i64_i32 v[24:25], s[4:5], s17, v148, 0
	global_store_dwordx4 v[64:65], v[60:63], off
	v_cvt_pk_bf16_f32 v40, v52, v53
	v_cvt_pk_bf16_f32 v41, v54, v55
	v_cvt_pk_bf16_f32 v42, v48, v49
	v_cvt_pk_bf16_f32 v43, v50, v51
	global_store_dwordx4 v[44:45], v[28:31], off offset:256
	v_cvt_pk_bf16_f32 v12, v12, v13
	v_cvt_pk_bf16_f32 v13, v14, v15
	v_lshl_add_u64 v[28:29], v[24:25], 1, v[156:157]
	v_cvt_pk_bf16_f32 v14, v8, v9
	v_cvt_pk_bf16_f32 v15, v10, v11
	v_mad_i64_i32 v[8:9], s[4:5], s17, v150, 0
	global_store_dwordx4 v[44:45], v[40:43], off
	v_cvt_pk_bf16_f32 v24, v36, v37
	v_cvt_pk_bf16_f32 v25, v38, v39
	v_cvt_pk_bf16_f32 v26, v32, v33
	v_cvt_pk_bf16_f32 v27, v34, v35
	global_store_dwordx4 v[28:29], v[12:15], off offset:256
	v_cvt_pk_bf16_f32 v10, v16, v17
	v_cvt_pk_bf16_f32 v11, v18, v19
	v_lshl_add_u64 v[12:13], v[8:9], 1, v[156:157]
	v_cvt_pk_bf16_f32 v8, v20, v21
	v_cvt_pk_bf16_f32 v9, v22, v23
	v_cvt_pk_bf16_f32 v4, v4, v5
	v_cvt_pk_bf16_f32 v5, v6, v7
	v_cvt_pk_bf16_f32 v6, v0, v1
	v_cvt_pk_bf16_f32 v7, v2, v3
	s_and_b64 vcc, exec, s[36:37]
	s_mov_b32 s40, s30
	s_mov_b32 s41, s34
	s_mov_b64 s[48:49], s[38:39]
	s_mov_b64 s[46:47], s[44:45]
	global_store_dwordx4 v[28:29], v[24:27], off
	global_store_dwordx4 v[12:13], v[8:11], off
	global_store_dwordx4 v[12:13], v[4:7], off offset:256
	s_cbranch_vccz .LBB0_868
	v_readlane_b32 s0, v253, 1
	s_waitcnt vmcnt(0)
	v_readlane_b32 s1, v253, 2
	v_readlane_b32 s72, v255, 28
	s_andn2_b64 vcc, exec, s[0:1]
	v_readlane_b32 s73, v255, 29
	s_cbranch_vccnz .LBB0_887
	s_barrier

; #define PG8_STAGE(bufoff, gbase, voff) do { _Pragma("unroll") for (int _i = 0; _i < 2; ++_i) \
;         __builtin_amdgcn_global_load_lds((const unsigned*)((const char*)(gbase) + (voff)[_i]), (LAS unsigned*)(lds + (bufoff) + ldsw + _i * 8192), 16, 0, 0); } while (0)
; #define PG8_LDA(dst, b, h) do { _Pragma("unroll") for (int m = 0; m < 4; ++m) _Pragma("unroll") for (int k = 0; k < 2; ++k) dst[m][k] = *(const LAS bf16x8*)(lds + PG8_SA(b, h) + aoff + m * 2048 + k * 1024); } while (0)
; #define PG8_LDB(dst, b, h) do { _Pragma("unroll") for (int n = 0; n < 2; ++n) _Pragma("unroll") for (int k = 0; k < 2; ++k) dst[n][k] = *(const LAS bf16x8*)(lds + PG8_SB(b, h) + boff + n * 2048 + k * 1024); } while (0)
; #define PG8_MMA(ai, bj, At, Bt) do { __builtin_amdgcn_s_setprio(1); _Pragma("unroll") for (int m = 0; m < 4; ++m) _Pragma("unroll") for (int n = 0; n < 2; ++n) _Pragma("unroll") for (int k = 0; k < 2; ++k) \
;         acc[ai][bj][m][n] = __builtin_amdgcn_mfma_f32_16x16x32_bf16(Bt[n][k], At[m][k], acc[ai][bj][m][n], 0, 0, 0); __builtin_amdgcn_s_setprio(0); } while (0)
; #define PG8_WAIT_V(n) asm volatile("s_waitcnt vmcnt(" #n ")" ::: "memory")
; #define PG8_WAIT_L(n) asm volatile("s_waitcnt lgkmcnt(" #n ")" ::: "memory")
; #define PG8_BAR __builtin_amdgcn_s_barrier()
; #define PG8_SCHED __builtin_amdgcn_sched_barrier(0)
; template <class Epi, class Sched, bool ALIGN_EPI>
; __device__ __forceinline__ void gemm_phase(LAS unsigned char* lds, const int wid, const int lda_, const int ldb_, const int K_, const Sched& S, const Epi& E) {
;     ...
;         const bool has_next = S.next(ui + 1, nxt);
;         const int nt = S.nt(cur);
;         const char* nA = has_next ? S.a(nxt) : cA; const char* nB = has_next ? S.b(nxt) : cB;
; #pragma unroll 1
;         for (int t = 0; t < nt; t += 2) {
;             const bool last = (t == nt - 2);
;             const char* a1 = cA + (size_t)(t + 1) * kstep;
;             const char* a2 = last ? nA : cA + (size_t)(t + 2) * kstep; const char* b2 = last ? nB : cB + (size_t)(t + 2) * kstep;
;             const char* a3 = a2 + kstep; const char* b3 = b2 + kstep;
;             PG8_LDB(B0, 0, 0); PG8_LDB(B1, 0, 1); PG8_SCHED; PG8_LDA(At, 0, 0); PG8_STAGE(PG8_SA(1, 1), a1 + hstepA, voffA);
;             PG8_WAIT_V(8); PG8_WAIT_L(0); PG8_BAR; PG8_MMA(0, 0, At, B0); PG8_MMA(0, 1, At, B1); PG8_BAR; PG8_SCHED;
.LBB0_961:
	s_xor_b64 s[36:37], s[4:5], -1
	s_cmp_gt_i32 s48, -1
	s_cselect_b64 s[50:51], -1, 0
	s_cmp_lt_i32 s48, 0
	s_cselect_b32 s45, 32, 8
	s_max_i32 s17, s75, 0
	s_ashr_i32 s35, s34, 31
	s_lshl_b32 s17, s17, 10
	s_lshl_b64 s[38:39], s[34:35], 20
	v_readlane_b32 s27, v254, 19
	s_add_u32 s27, s27, s38
	v_readlane_b32 s31, v254, 20
	s_addc_u32 s31, s31, s39
	s_add_u32 s38, s27, s17
	s_addc_u32 s39, s31, 0
	s_and_b64 s[40:41], s[4:5], exec
	s_cselect_b32 s35, s39, s95
	s_cselect_b32 s47, s38, s94
	s_ashr_i32 s31, s30, 31
	s_lshl_b64 s[40:41], s[30:31], 20
	s_add_u32 s27, s6, s40
	s_addc_u32 s31, s7, s41
	s_add_u32 s40, s27, s17
	s_addc_u32 s41, s31, 0
	s_and_b64 s[4:5], s[4:5], exec
	s_cselect_b32 s4, s41, s97
	s_cselect_b32 s5, s40, s96
	s_add_i32 s31, s45, -2
	s_add_u32 s94, s94, 0x80
	s_addc_u32 s95, s95, 0
	s_add_u32 s49, s96, 0x100
	s_mov_b32 s77, 0
	s_addc_u32 s76, s97, 0
	s_add_i32 s78, s77, 2
	s_add_u32 s17, s94, 0x80
	s_addc_u32 s27, s95, 0
	s_add_i32 s79, 0, 0x10000
	s_cmp_eq_u32 s31, s77
	s_cselect_b32 s97, s35, s27
	s_cselect_b32 s96, s47, s17
	v_add_u32_e32 v141, s79, v135
	s_cselect_b32 s43, s4, s76
	s_cselect_b32 s42, s5, s49
	s_add_i32 s17, 0, 0x14000
	ds_read_b128 v[156:159], v141
	ds_read_b128 v[160:163], v141 offset:1024
	ds_read_b128 v[164:167], v141 offset:2048
	ds_read_b128 v[168:171], v141 offset:3072
	v_add_u32_e32 v141, s17, v135
	ds_read_b128 v[172:175], v141
	ds_read_b128 v[180:183], v141 offset:1024
	ds_read_b128 v[184:187], v141 offset:2048
	ds_read_b128 v[188:191], v141 offset:3072
	v_lshl_add_u64 v[224:225], s[94:95], 0, v[152:153]
	s_add_i32 m0, s16, 0xc000
	ds_read_b128 v[192:195], v139
	ds_read_b128 v[196:199], v139 offset:1024
	ds_read_b128 v[200:203], v139 offset:2048
	ds_read_b128 v[204:207], v139 offset:3072
	ds_read_b128 v[208:211], v139 offset:4096
	ds_read_b128 v[212:215], v139 offset:5120
	ds_read_b128 v[216:219], v139 offset:6144
	ds_read_b128 v[220:223], v139 offset:7168
	global_load_lds_dwordx4 v[224:225], off
	v_lshl_add_u64 v[224:225], s[94:95], 0, v[154:155]
	s_add_i32 m0, s16, 0xe000
	s_nop 0
	global_load_lds_dwordx4 v[224:225], off
	s_waitcnt vmcnt(8)
	s_waitcnt lgkmcnt(0)
	s_barrier
	s_setprio 1
	s_waitcnt lgkmcnt(0)
	v_mfma_f32_16x16x32_bf16 v[124:127], v[156:159], v[192:195], 0
	v_mfma_f32_16x16x32_bf16 v[120:123], v[164:167], v[192:195], 0
	v_mfma_f32_16x16x32_bf16 v[116:119], v[156:159], v[200:203], 0
	v_mfma_f32_16x16x32_bf16 v[112:115], v[164:167], v[200:203], 0
	v_mfma_f32_16x16x32_bf16 v[100:103], v[156:159], v[208:211], 0
	v_mfma_f32_16x16x32_bf16 v[96:99], v[164:167], v[208:211], 0
	v_mfma_f32_16x16x32_bf16 v[84:87], v[156:159], v[216:219], 0
	v_mfma_f32_16x16x32_bf16 v[80:83], v[164:167], v[216:219], 0
	v_mfma_f32_16x16x32_bf16 v[124:127], v[160:163], v[196:199], v[124:127]
	v_mfma_f32_16x16x32_bf16 v[120:123], v[168:171], v[196:199], v[120:123]
	v_mfma_f32_16x16x32_bf16 v[116:119], v[160:163], v[204:207], v[116:119]
	v_mfma_f32_16x16x32_bf16 v[112:115], v[168:171], v[204:207], v[112:115]
	v_mfma_f32_16x16x32_bf16 v[100:103], v[160:163], v[212:215], v[100:103]
	v_mfma_f32_16x16x32_bf16 v[96:99], v[168:171], v[212:215], v[96:99]
	v_mfma_f32_16x16x32_bf16 v[84:87], v[160:163], v[220:223], v[84:87]
	v_mfma_f32_16x16x32_bf16 v[80:83], v[168:171], v[220:223], v[80:83]
	v_mfma_f32_16x16x32_bf16 v[108:111], v[172:175], v[192:195], 0
	v_mfma_f32_16x16x32_bf16 v[104:107], v[184:187], v[192:195], 0
	v_mfma_f32_16x16x32_bf16 v[92:95], v[172:175], v[200:203], 0
	v_mfma_f32_16x16x32_bf16 v[88:91], v[184:187], v[200:203], 0
	v_mfma_f32_16x16x32_bf16 v[76:79], v[172:175], v[208:211], 0
	v_mfma_f32_16x16x32_bf16 v[72:75], v[184:187], v[208:211], 0
	v_mfma_f32_16x16x32_bf16 v[68:71], v[172:175], v[216:219], 0
	v_mfma_f32_16x16x32_bf16 v[64:67], v[184:187], v[216:219], 0
	v_mfma_f32_16x16x32_bf16 v[108:111], v[180:183], v[196:199], v[108:111]
	v_mfma_f32_16x16x32_bf16 v[104:107], v[188:191], v[196:199], v[104:107]
	v_mfma_f32_16x16x32_bf16 v[92:95], v[180:183], v[204:207], v[92:95]
	v_mfma_f32_16x16x32_bf16 v[88:91], v[188:191], v[204:207], v[88:91]
	v_mfma_f32_16x16x32_bf16 v[76:79], v[180:183], v[212:215], v[76:79]
	v_mfma_f32_16x16x32_bf16 v[72:75], v[188:191], v[212:215], v[72:75]
	v_mfma_f32_16x16x32_bf16 v[68:71], v[180:183], v[220:223], v[68:71]
	v_mfma_f32_16x16x32_bf16 v[64:67], v[188:191], v[220:223], v[64:67]
	s_barrier
; #define PG8_STAGE(bufoff, gbase, voff) do { _Pragma("unroll") for (int _i = 0; _i < 2; ++_i) \
;         __builtin_amdgcn_global_load_lds((const unsigned*)((const char*)(gbase) + (voff)[_i]), (LAS unsigned*)(lds + (bufoff) + ldsw + _i * 8192), 16, 0, 0); } while (0)
; #define PG8_LDA(dst, b, h) do { _Pragma("unroll") for (int m = 0; m < 4; ++m) _Pragma("unroll") for (int k = 0; k < 2; ++k) dst[m][k] = *(const LAS bf16x8*)(lds + PG8_SA(b, h) + aoff + m * 2048 + k * 1024); } while (0)
; #define PG8_MMA(ai, bj, At, Bt) do { __builtin_amdgcn_s_setprio(1); _Pragma("unroll") for (int m = 0; m < 4; ++m) _Pragma("unroll") for (int n = 0; n < 2; ++n) _Pragma("unroll") for (int k = 0; k < 2; ++k) \
;         acc[ai][bj][m][n] = __builtin_amdgcn_mfma_f32_16x16x32_bf16(Bt[n][k], At[m][k], acc[ai][bj][m][n], 0, 0, 0); __builtin_amdgcn_s_setprio(0); } while (0)
; #define PG8_WAIT_V(n) asm volatile("s_waitcnt vmcnt(" #n ")" ::: "memory")
; #define PG8_WAIT_L(n) asm volatile("s_waitcnt lgkmcnt(" #n ")" ::: "memory")
; #define PG8_BAR __builtin_amdgcn_s_barrier()
; #define PG8_SCHED __builtin_amdgcn_sched_barrier(0)
; template <class Epi, class Sched, bool ALIGN_EPI>
; __device__ __forceinline__ void gemm_phase(LAS unsigned char* lds, const int wid, const int lda_, const int ldb_, const int K_, const Sched& S, const Epi& E) {
;     ...
;             PG8_LDA(At, 0, 1); PG8_STAGE(PG8_SB(0, 0), b2, voffB); PG8_STAGE(PG8_SB(0, 1), b2 + hstepB, voffB); PG8_STAGE(PG8_SA(0, 0), a2, voffA);
;             PG8_WAIT_V(8); PG8_WAIT_L(0); PG8_BAR; PG8_MMA(1, 0, At, B0); PG8_MMA(1, 1, At, B1); PG8_BAR; PG8_SCHED;
	s_add_i32 s27, s79, s3
	v_lshl_add_u64 v[224:225], s[42:43], 0, v[176:177]
	s_mov_b32 m0, s27
	ds_read_b128 v[192:195], v139 offset:16384
	ds_read_b128 v[196:199], v139 offset:17408
	ds_read_b128 v[200:203], v139 offset:18432
	ds_read_b128 v[204:207], v139 offset:19456
	ds_read_b128 v[208:211], v139 offset:20480
	ds_read_b128 v[212:215], v139 offset:21504
	ds_read_b128 v[216:219], v139 offset:22528
	ds_read_b128 v[220:223], v139 offset:23552
	global_load_lds_dwordx4 v[224:225], off
	s_add_i32 m0, s27, 0x2000
	v_lshl_add_u64 v[226:227], s[42:43], 0, v[128:129]
	s_add_u32 s42, s42, s10
	s_addc_u32 s43, s43, s11
	s_add_i32 s17, s17, s3
	global_load_lds_dwordx4 v[226:227], off
	v_lshl_add_u64 v[228:229], s[42:43], 0, v[176:177]
	s_mov_b32 m0, s17
	v_lshl_add_u64 v[230:231], s[42:43], 0, v[128:129]
	global_load_lds_dwordx4 v[228:229], off
	s_add_i32 m0, s17, 0x2000
	v_lshl_add_u64 v[232:233], s[96:97], 0, v[132:133]
	global_load_lds_dwordx4 v[230:231], off
	s_mov_b32 m0, s16
	v_lshl_add_u64 v[234:235], s[96:97], 0, v[130:131]
	global_load_lds_dwordx4 v[232:233], off
	s_mov_b32 m0, s14
	s_nop 0
	global_load_lds_dwordx4 v[234:235], off
	s_waitcnt vmcnt(8)
	s_waitcnt lgkmcnt(0)
	s_barrier
	s_waitcnt lgkmcnt(0)
	v_mfma_f32_16x16x32_bf16 v[60:63], v[156:159], v[192:195], 0
	v_mfma_f32_16x16x32_bf16 v[56:59], v[164:167], v[192:195], 0
	v_mfma_f32_16x16x32_bf16 v[52:55], v[156:159], v[200:203], 0
	v_mfma_f32_16x16x32_bf16 v[48:51], v[164:167], v[200:203], 0
	v_mfma_f32_16x16x32_bf16 v[36:39], v[156:159], v[208:211], 0
	v_mfma_f32_16x16x32_bf16 v[32:35], v[164:167], v[208:211], 0
	v_mfma_f32_16x16x32_bf16 v[20:23], v[156:159], v[216:219], 0
	v_mfma_f32_16x16x32_bf16 v[16:19], v[164:167], v[216:219], 0
	v_mfma_f32_16x16x32_bf16 v[60:63], v[160:163], v[196:199], v[60:63]
	v_mfma_f32_16x16x32_bf16 v[56:59], v[168:171], v[196:199], v[56:59]
	v_mfma_f32_16x16x32_bf16 v[52:55], v[160:163], v[204:207], v[52:55]
	v_mfma_f32_16x16x32_bf16 v[48:51], v[168:171], v[204:207], v[48:51]
	v_mfma_f32_16x16x32_bf16 v[36:39], v[160:163], v[212:215], v[36:39]
	v_mfma_f32_16x16x32_bf16 v[32:35], v[168:171], v[212:215], v[32:35]
	v_mfma_f32_16x16x32_bf16 v[20:23], v[160:163], v[220:223], v[20:23]
	v_mfma_f32_16x16x32_bf16 v[16:19], v[168:171], v[220:223], v[16:19]
	v_mfma_f32_16x16x32_bf16 v[44:47], v[172:175], v[192:195], 0
	v_mfma_f32_16x16x32_bf16 v[40:43], v[184:187], v[192:195], 0
	v_mfma_f32_16x16x32_bf16 v[28:31], v[172:175], v[200:203], 0
	v_mfma_f32_16x16x32_bf16 v[24:27], v[184:187], v[200:203], 0
	v_mfma_f32_16x16x32_bf16 v[12:15], v[172:175], v[208:211], 0
	v_mfma_f32_16x16x32_bf16 v[8:11], v[184:187], v[208:211], 0
	v_mfma_f32_16x16x32_bf16 v[4:7], v[172:175], v[216:219], 0
	v_mfma_f32_16x16x32_bf16 v[0:3], v[184:187], v[216:219], 0
	v_mfma_f32_16x16x32_bf16 v[44:47], v[180:183], v[196:199], v[44:47]
	v_mfma_f32_16x16x32_bf16 v[40:43], v[188:191], v[196:199], v[40:43]
	v_mfma_f32_16x16x32_bf16 v[28:31], v[180:183], v[204:207], v[28:31]
	v_mfma_f32_16x16x32_bf16 v[24:27], v[188:191], v[204:207], v[24:27]
	v_mfma_f32_16x16x32_bf16 v[12:15], v[180:183], v[212:215], v[12:15]
	v_mfma_f32_16x16x32_bf16 v[8:11], v[188:191], v[212:215], v[8:11]
	v_mfma_f32_16x16x32_bf16 v[4:7], v[180:183], v[220:223], v[4:7]
	v_mfma_f32_16x16x32_bf16 v[0:3], v[188:191], v[220:223], v[0:3]
	s_barrier
	s_branch .Lgemm_join_962

; #define PG8_STAGE(bufoff, gbase, voff) do { _Pragma("unroll") for (int _i = 0; _i < 2; ++_i) \
;         __builtin_amdgcn_global_load_lds((const unsigned*)((const char*)(gbase) + (voff)[_i]), (LAS unsigned*)(lds + (bufoff) + ldsw + _i * 8192), 16, 0, 0); } while (0)
; #define PG8_LDA(dst, b, h) do { _Pragma("unroll") for (int m = 0; m < 4; ++m) _Pragma("unroll") for (int k = 0; k < 2; ++k) dst[m][k] = *(const LAS bf16x8*)(lds + PG8_SA(b, h) + aoff + m * 2048 + k * 1024); } while (0)
; #define PG8_LDB(dst, b, h) do { _Pragma("unroll") for (int n = 0; n < 2; ++n) _Pragma("unroll") for (int k = 0; k < 2; ++k) dst[n][k] = *(const LAS bf16x8*)(lds + PG8_SB(b, h) + boff + n * 2048 + k * 1024); } while (0)
; #define PG8_MMA(ai, bj, At, Bt) do { __builtin_amdgcn_s_setprio(1); _Pragma("unroll") for (int m = 0; m < 4; ++m) _Pragma("unroll") for (int n = 0; n < 2; ++n) _Pragma("unroll") for (int k = 0; k < 2; ++k) \
;         acc[ai][bj][m][n] = __builtin_amdgcn_mfma_f32_16x16x32_bf16(Bt[n][k], At[m][k], acc[ai][bj][m][n], 0, 0, 0); __builtin_amdgcn_s_setprio(0); } while (0)
; #define PG8_WAIT_V(n) asm volatile("s_waitcnt vmcnt(" #n ")" ::: "memory")
; #define PG8_WAIT_L(n) asm volatile("s_waitcnt lgkmcnt(" #n ")" ::: "memory")
; #define PG8_BAR __builtin_amdgcn_s_barrier()
; #define PG8_SCHED __builtin_amdgcn_sched_barrier(0)
; template <class Epi, class Sched, bool ALIGN_EPI>
; __device__ __forceinline__ void gemm_phase(LAS unsigned char* lds, const int wid, const int lda_, const int ldb_, const int K_, const Sched& S, const Epi& E) {
;     ...
;             PG8_LDB(B0, 1, 0); PG8_LDB(B1, 1, 1); PG8_SCHED; PG8_LDA(At, 1, 0); PG8_STAGE(PG8_SA(0, 1), a2 + hstepA, voffA);
;             PG8_WAIT_V(8); PG8_WAIT_L(0); PG8_BAR; PG8_MMA(0, 0, At, B0); PG8_MMA(0, 1, At, B1); PG8_BAR; PG8_SCHED;
.Lgemm_join_962:
	s_add_i32 s17, 0, 0x18000
	v_add_u32_e32 v141, s17, v135
	s_add_i32 s27, 0, 0x1c000
	ds_read_b128 v[156:159], v141
	ds_read_b128 v[160:163], v141 offset:1024
	ds_read_b128 v[164:167], v141 offset:2048
	ds_read_b128 v[168:171], v141 offset:3072
	v_add_u32_e32 v141, s27, v135
	ds_read_b128 v[172:175], v141
	ds_read_b128 v[180:183], v141 offset:1024
	ds_read_b128 v[184:187], v141 offset:2048
	ds_read_b128 v[188:191], v141 offset:3072
	s_add_u32 s42, s96, s0
	s_addc_u32 s43, s97, s1
	s_mov_b32 m0, s15
	v_lshl_add_u64 v[236:237], s[42:43], 0, v[132:133]
	ds_read_b128 v[192:195], v139 offset:32768
	ds_read_b128 v[196:199], v139 offset:33792
	ds_read_b128 v[200:203], v139 offset:34816
	ds_read_b128 v[204:207], v139 offset:35840
	ds_read_b128 v[208:211], v139 offset:36864
	ds_read_b128 v[212:215], v139 offset:37888
	ds_read_b128 v[216:219], v139 offset:38912
	ds_read_b128 v[220:223], v139 offset:39936
	global_load_lds_dwordx4 v[236:237], off
	v_lshl_add_u64 v[236:237], s[42:43], 0, v[130:131]
	s_mov_b32 m0, s26
	s_nop 0
	global_load_lds_dwordx4 v[236:237], off
	s_waitcnt vmcnt(8)
	s_waitcnt lgkmcnt(0)
	s_barrier
	s_waitcnt lgkmcnt(0)
	v_mfma_f32_16x16x32_bf16 v[124:127], v[156:159], v[192:195], v[124:127]
	v_mfma_f32_16x16x32_bf16 v[120:123], v[164:167], v[192:195], v[120:123]
	v_mfma_f32_16x16x32_bf16 v[116:119], v[156:159], v[200:203], v[116:119]
	v_mfma_f32_16x16x32_bf16 v[112:115], v[164:167], v[200:203], v[112:115]
	v_mfma_f32_16x16x32_bf16 v[100:103], v[156:159], v[208:211], v[100:103]
	v_mfma_f32_16x16x32_bf16 v[96:99], v[164:167], v[208:211], v[96:99]
	v_mfma_f32_16x16x32_bf16 v[84:87], v[156:159], v[216:219], v[84:87]
	v_mfma_f32_16x16x32_bf16 v[80:83], v[164:167], v[216:219], v[80:83]
	v_mfma_f32_16x16x32_bf16 v[124:127], v[160:163], v[196:199], v[124:127]
	v_mfma_f32_16x16x32_bf16 v[120:123], v[168:171], v[196:199], v[120:123]
	v_mfma_f32_16x16x32_bf16 v[116:119], v[160:163], v[204:207], v[116:119]
	v_mfma_f32_16x16x32_bf16 v[112:115], v[168:171], v[204:207], v[112:115]
	v_mfma_f32_16x16x32_bf16 v[100:103], v[160:163], v[212:215], v[100:103]
	v_mfma_f32_16x16x32_bf16 v[96:99], v[168:171], v[212:215], v[96:99]
	v_mfma_f32_16x16x32_bf16 v[84:87], v[160:163], v[220:223], v[84:87]
	v_mfma_f32_16x16x32_bf16 v[80:83], v[168:171], v[220:223], v[80:83]
	v_mfma_f32_16x16x32_bf16 v[108:111], v[172:175], v[192:195], v[108:111]
	v_mfma_f32_16x16x32_bf16 v[104:107], v[184:187], v[192:195], v[104:107]
	v_mfma_f32_16x16x32_bf16 v[92:95], v[172:175], v[200:203], v[92:95]
	v_mfma_f32_16x16x32_bf16 v[88:91], v[184:187], v[200:203], v[88:91]
	v_mfma_f32_16x16x32_bf16 v[76:79], v[172:175], v[208:211], v[76:79]
	v_mfma_f32_16x16x32_bf16 v[72:75], v[184:187], v[208:211], v[72:75]
	v_mfma_f32_16x16x32_bf16 v[68:71], v[172:175], v[216:219], v[68:71]
	v_mfma_f32_16x16x32_bf16 v[64:67], v[184:187], v[216:219], v[64:67]
	v_mfma_f32_16x16x32_bf16 v[108:111], v[180:183], v[196:199], v[108:111]
	v_mfma_f32_16x16x32_bf16 v[104:107], v[188:191], v[196:199], v[104:107]
	v_mfma_f32_16x16x32_bf16 v[92:95], v[180:183], v[204:207], v[92:95]
	v_mfma_f32_16x16x32_bf16 v[88:91], v[188:191], v[204:207], v[88:91]
	v_mfma_f32_16x16x32_bf16 v[76:79], v[180:183], v[212:215], v[76:79]
	v_mfma_f32_16x16x32_bf16 v[72:75], v[188:191], v[212:215], v[72:75]
	v_mfma_f32_16x16x32_bf16 v[68:71], v[180:183], v[220:223], v[68:71]
	v_mfma_f32_16x16x32_bf16 v[64:67], v[188:191], v[220:223], v[64:67]
	s_barrier
; #define PG8_STAGE(bufoff, gbase, voff) do { _Pragma("unroll") for (int _i = 0; _i < 2; ++_i) \
;         __builtin_amdgcn_global_load_lds((const unsigned*)((const char*)(gbase) + (voff)[_i]), (LAS unsigned*)(lds + (bufoff) + ldsw + _i * 8192), 16, 0, 0); } while (0)
; #define PG8_LDA(dst, b, h) do { _Pragma("unroll") for (int m = 0; m < 4; ++m) _Pragma("unroll") for (int k = 0; k < 2; ++k) dst[m][k] = *(const LAS bf16x8*)(lds + PG8_SA(b, h) + aoff + m * 2048 + k * 1024); } while (0)
; #define PG8_MMA(ai, bj, At, Bt) do { __builtin_amdgcn_s_setprio(1); _Pragma("unroll") for (int m = 0; m < 4; ++m) _Pragma("unroll") for (int n = 0; n < 2; ++n) _Pragma("unroll") for (int k = 0; k < 2; ++k) \
;         acc[ai][bj][m][n] = __builtin_amdgcn_mfma_f32_16x16x32_bf16(Bt[n][k], At[m][k], acc[ai][bj][m][n], 0, 0, 0); __builtin_amdgcn_s_setprio(0); } while (0)
; #define PG8_WAIT_V(n) asm volatile("s_waitcnt vmcnt(" #n ")" ::: "memory")
; #define PG8_WAIT_L(n) asm volatile("s_waitcnt lgkmcnt(" #n ")" ::: "memory")
; #define PG8_BAR __builtin_amdgcn_s_barrier()
; #define PG8_SCHED __builtin_amdgcn_sched_barrier(0)
; template <class Epi, class Sched, bool ALIGN_EPI>
; __device__ __forceinline__ void gemm_phase(LAS unsigned char* lds, const int wid, const int lda_, const int ldb_, const int K_, const Sched& S, const Epi& E) {
;     ...
;             PG8_LDA(At, 1, 1); PG8_STAGE(PG8_SB(1, 0), b3, voffB); PG8_STAGE(PG8_SB(1, 1), b3 + hstepB, voffB); PG8_STAGE(PG8_SA(1, 0), a3, voffA);
;             PG8_WAIT_V(8); PG8_WAIT_L(0); PG8_BAR; PG8_MMA(1, 0, At, B0); PG8_MMA(1, 1, At, B1); PG8_BAR; PG8_SCHED;
;         }
;         if constexpr (ALIGN_EPI) { if (wr == 0) PG8_BAR; }
;         E(acc, cur, S, wr, wc, fr, fq);
;     __device__ __forceinline__ void out(const pg8::Unit& u, char*& o, int& ldo, int& kind) const { ldo = D;
;         if (u.kq < 0) { o = (char*)ws + YOFF + ((size_t)u.pm * 256 * D + (size_t)u.pn * 256) * 2; kind = 0; }
;         else { o = (char*)ws + WS_PART + (((size_t)u.kq * MCTX + (size_t)(u.pm - 64) * 256) * D + (size_t)u.pn * 256) * 2; kind = 0; } }
	s_add_i32 s17, s17, s3
	v_lshl_add_u64 v[224:225], v[224:225], 0, s[24:25]
	s_mov_b32 m0, s17
	ds_read_b128 v[192:195], v139 offset:49152
	ds_read_b128 v[196:199], v139 offset:50176
	ds_read_b128 v[200:203], v139 offset:51200
	ds_read_b128 v[204:207], v139 offset:52224
	ds_read_b128 v[208:211], v139 offset:53248
	ds_read_b128 v[212:215], v139 offset:54272
	ds_read_b128 v[216:219], v139 offset:55296
	ds_read_b128 v[220:223], v139 offset:56320
	global_load_lds_dwordx4 v[224:225], off
	v_lshl_add_u64 v[224:225], v[226:227], 0, s[24:25]
	s_add_i32 m0, s17, 0x2000
	s_add_i32 s17, s27, s3
	global_load_lds_dwordx4 v[224:225], off
	v_lshl_add_u64 v[224:225], v[228:229], 0, s[24:25]
	s_mov_b32 m0, s17
	s_nop 0
	global_load_lds_dwordx4 v[224:225], off
	v_lshl_add_u64 v[224:225], v[230:231], 0, s[24:25]
	s_add_i32 m0, s17, 0x2000
	s_nop 0
	global_load_lds_dwordx4 v[224:225], off
	v_lshl_add_u64 v[224:225], v[232:233], 0, s[24:25]
	s_mov_b32 m0, s72
	s_nop 0
	global_load_lds_dwordx4 v[224:225], off
	v_lshl_add_u64 v[224:225], v[234:235], 0, s[24:25]
	s_mov_b32 m0, s73
	s_nop 0
	global_load_lds_dwordx4 v[224:225], off
	s_waitcnt vmcnt(8)
	s_waitcnt lgkmcnt(0)
	s_barrier
	s_waitcnt lgkmcnt(0)
	v_mfma_f32_16x16x32_bf16 v[60:63], v[156:159], v[192:195], v[60:63]
	v_mfma_f32_16x16x32_bf16 v[56:59], v[164:167], v[192:195], v[56:59]
	v_mfma_f32_16x16x32_bf16 v[52:55], v[156:159], v[200:203], v[52:55]
	v_mfma_f32_16x16x32_bf16 v[48:51], v[164:167], v[200:203], v[48:51]
	v_mfma_f32_16x16x32_bf16 v[36:39], v[156:159], v[208:211], v[36:39]
	v_mfma_f32_16x16x32_bf16 v[32:35], v[164:167], v[208:211], v[32:35]
	v_mfma_f32_16x16x32_bf16 v[20:23], v[156:159], v[216:219], v[20:23]
	v_mfma_f32_16x16x32_bf16 v[16:19], v[164:167], v[216:219], v[16:19]
	v_mfma_f32_16x16x32_bf16 v[60:63], v[160:163], v[196:199], v[60:63]
	v_mfma_f32_16x16x32_bf16 v[56:59], v[168:171], v[196:199], v[56:59]
	v_mfma_f32_16x16x32_bf16 v[52:55], v[160:163], v[204:207], v[52:55]
	v_mfma_f32_16x16x32_bf16 v[48:51], v[168:171], v[204:207], v[48:51]
	v_mfma_f32_16x16x32_bf16 v[36:39], v[160:163], v[212:215], v[36:39]
	v_mfma_f32_16x16x32_bf16 v[32:35], v[168:171], v[212:215], v[32:35]
	v_mfma_f32_16x16x32_bf16 v[20:23], v[160:163], v[220:223], v[20:23]
	v_mfma_f32_16x16x32_bf16 v[16:19], v[168:171], v[220:223], v[16:19]
	v_mfma_f32_16x16x32_bf16 v[44:47], v[172:175], v[192:195], v[44:47]
	v_mfma_f32_16x16x32_bf16 v[40:43], v[184:187], v[192:195], v[40:43]
	v_mfma_f32_16x16x32_bf16 v[28:31], v[172:175], v[200:203], v[28:31]
	v_mfma_f32_16x16x32_bf16 v[24:27], v[184:187], v[200:203], v[24:27]
	v_mfma_f32_16x16x32_bf16 v[12:15], v[172:175], v[208:211], v[12:15]
	v_mfma_f32_16x16x32_bf16 v[8:11], v[184:187], v[208:211], v[8:11]
	v_mfma_f32_16x16x32_bf16 v[4:7], v[172:175], v[216:219], v[4:7]
	v_mfma_f32_16x16x32_bf16 v[0:3], v[184:187], v[216:219], v[0:3]
	v_mfma_f32_16x16x32_bf16 v[44:47], v[180:183], v[196:199], v[44:47]
	v_mfma_f32_16x16x32_bf16 v[40:43], v[188:191], v[196:199], v[40:43]
	v_mfma_f32_16x16x32_bf16 v[28:31], v[180:183], v[204:207], v[28:31]
	v_mfma_f32_16x16x32_bf16 v[24:27], v[188:191], v[204:207], v[24:27]
	v_mfma_f32_16x16x32_bf16 v[12:15], v[180:183], v[212:215], v[12:15]
	v_mfma_f32_16x16x32_bf16 v[8:11], v[188:191], v[212:215], v[8:11]
	v_mfma_f32_16x16x32_bf16 v[4:7], v[180:183], v[220:223], v[4:7]
	v_mfma_f32_16x16x32_bf16 v[0:3], v[188:191], v[220:223], v[0:3]
	s_barrier
	s_add_u32 s94, s94, 0x100
	s_addc_u32 s95, s95, 0
	s_add_u32 s49, s49, 0x100
	s_addc_u32 s76, s76, 0
	s_cmp_ge_u32 s78, s45
	s_mov_b32 s77, s78
	s_cbranch_scc0 .LBB0_962
	s_setprio 0
	s_mov_b64 s[94:95], -1
	s_and_b64 vcc, exec, s[50:51]
	s_cbranch_vccz .LBB0_965
	s_mov_b32 s49, s92
	s_ashr_i32 s47, s46, 31
	s_ashr_i32 s45, s44, 31
	s_lshl_b64 s[4:5], s[46:47], 20
	s_lshl_b64 s[42:43], s[44:45], 9
	s_lshl_b64 s[48:49], s[48:49], 23
	v_readlane_b32 s50, v251, 28
	v_readlane_b32 s51, v251, 29
	s_add_u32 s17, s50, s42
	s_addc_u32 s27, s51, s43
	s_add_u32 s17, s17, s48
	s_addc_u32 s27, s27, s49
	s_add_u32 s4, s17, s4
	s_addc_u32 s5, s27, s5
	s_add_u32 s4, s4, 0xfc000000
	s_addc_u32 s5, s5, -1
	s_mov_b64 s[94:95], 0

; #define PG8_STAGE(bufoff, gbase, voff) do { _Pragma("unroll") for (int _i = 0; _i < 2; ++_i) \
;         __builtin_amdgcn_global_load_lds((const unsigned*)((const char*)(gbase) + (voff)[_i]), (LAS unsigned*)(lds + (bufoff) + ldsw + _i * 8192), 16, 0, 0); } while (0)
; #define PG8_LDA(dst, b, h) do { _Pragma("unroll") for (int m = 0; m < 4; ++m) _Pragma("unroll") for (int k = 0; k < 2; ++k) dst[m][k] = *(const LAS bf16x8*)(lds + PG8_SA(b, h) + aoff + m * 2048 + k * 1024); } while (0)
; #define PG8_LDB(dst, b, h) do { _Pragma("unroll") for (int n = 0; n < 2; ++n) _Pragma("unroll") for (int k = 0; k < 2; ++k) dst[n][k] = *(const LAS bf16x8*)(lds + PG8_SB(b, h) + boff + n * 2048 + k * 1024); } while (0)
; #define PG8_MMA(ai, bj, At, Bt) do { __builtin_amdgcn_s_setprio(1); _Pragma("unroll") for (int m = 0; m < 4; ++m) _Pragma("unroll") for (int n = 0; n < 2; ++n) _Pragma("unroll") for (int k = 0; k < 2; ++k) \
;         acc[ai][bj][m][n] = __builtin_amdgcn_mfma_f32_16x16x32_bf16(Bt[n][k], At[m][k], acc[ai][bj][m][n], 0, 0, 0); __builtin_amdgcn_s_setprio(0); } while (0)
; template <int NN> __device__ __forceinline__ bool tile2d(int i, int nM, Unit& u) {
;     const long L = (long)i * (int)gridDim.x + (int)blockIdx.x; if (L >= nM * NN) return false;
;     tile_of_id<NN>((int)L, nM, u.pm, u.pn); u.kq = -1; return true;
; template <class Epi, class Sched, bool ALIGN_EPI>
; __device__ __forceinline__ void gemm_phase(LAS unsigned char* lds, const int wid, const int lda_, const int ldb_, const int K_, const Sched& S, const Epi& E) {
;     ...
;         const bool has_next = S.next(ui + 1, nxt);
;         const int nt = S.nt(cur);
;         const char* nA = has_next ? S.a(nxt) : cA; const char* nB = has_next ? S.b(nxt) : cB;
; #pragma unroll 1
;         for (int t = 0; t < nt; t += 2) {
;             const bool last = (t == nt - 2);
;             const char* a1 = cA + (size_t)(t + 1) * kstep;
;             const char* a2 = last ? nA : cA + (size_t)(t + 2) * kstep; const char* b2 = last ? nB : cB + (size_t)(t + 2) * kstep;
;             const char* a3 = a2 + kstep; const char* b3 = b2 + kstep;
;             PG8_LDB(B0, 0, 0); PG8_LDB(B1, 0, 1); PG8_SCHED; PG8_LDA(At, 0, 0); PG8_STAGE(PG8_SA(1, 1), a1 + hstepA, voffA);
;             PG8_WAIT_V(8); PG8_WAIT_L(0); PG8_BAR; PG8_MMA(0, 0, At, B0); PG8_MMA(0, 1, At, B1); PG8_BAR; PG8_SCHED;
.LBB0_1119:
	v_mov_b64_e32 v[0:1], s[0:1]
	s_ashr_i32 s45, s44, 31
	v_cmp_lt_i64_e32 vcc, s[4:5], v[0:1]
	s_lshl_b64 s[4:5], s[44:45], 20
	v_readlane_b32 s46, v253, 52
	v_readlane_b32 s47, v253, 53
	s_add_u32 s46, s46, s4
	s_addc_u32 s47, s47, s5
	s_and_b64 s[4:5], vcc, exec
	s_cselect_b32 s4, s47, s41
	s_cselect_b32 s5, s46, s40
	s_ashr_i32 s43, s42, 31
	s_lshl_b64 s[48:49], s[42:43], 20
	s_add_u32 s48, s15, s48
	s_addc_u32 s49, s26, s49
	s_and_b64 s[76:77], vcc, exec
	s_cselect_b32 s43, s49, s51
	s_cselect_b32 s45, s48, s50
	s_add_u32 s76, s40, 0x80
	s_addc_u32 s77, s41, 0
	v_lshl_add_u64 v[156:157], s[76:77], 0, v[152:153]
	v_lshl_add_u64 v[158:159], s[76:77], 0, v[154:155]
	s_add_u32 s76, s50, 0x100
	s_addc_u32 s77, s51, 0
	s_mov_b32 s78, -2
	s_mov_b64 s[50:51], 0
	s_add_u32 s17, s40, s50
	s_addc_u32 s27, s41, s51
	s_add_u32 s17, s17, 0x100
	s_addc_u32 s27, s27, 0
	s_add_u32 s79, s76, s50
	s_addc_u32 s80, s77, s51
	s_add_i32 s86, 0, 0x10000
	s_cmpk_eq_i32 s50, 0xf00
	s_cselect_b32 s95, s4, s27
	s_cselect_b32 s94, s5, s17
	v_add_u32_e32 v141, s86, v135
	s_cselect_b32 s81, s43, s80
	s_cselect_b32 s80, s45, s79
	s_add_i32 s17, 0, 0x14000
	ds_read_b128 v[160:163], v141
	ds_read_b128 v[164:167], v141 offset:1024
	ds_read_b128 v[168:171], v141 offset:2048
	ds_read_b128 v[172:175], v141 offset:3072
	v_add_u32_e32 v141, s17, v135
	ds_read_b128 v[180:183], v141
	ds_read_b128 v[184:187], v141 offset:1024
	ds_read_b128 v[188:191], v141 offset:2048
	ds_read_b128 v[192:195], v141 offset:3072
	v_lshl_add_u64 v[228:229], v[158:159], 0, s[50:51]
	s_add_i32 m0, s16, 0xc000
	ds_read_b128 v[196:199], v139
	ds_read_b128 v[200:203], v139 offset:1024
	ds_read_b128 v[204:207], v139 offset:2048
	ds_read_b128 v[208:211], v139 offset:3072
	ds_read_b128 v[212:215], v139 offset:4096
	ds_read_b128 v[216:219], v139 offset:5120
	ds_read_b128 v[220:223], v139 offset:6144
	ds_read_b128 v[224:227], v139 offset:7168
	global_load_lds_dwordx4 v[228:229], off
	v_lshl_add_u64 v[228:229], v[156:157], 0, s[50:51]
	s_add_i32 m0, s16, 0xe000
	s_nop 0
	global_load_lds_dwordx4 v[228:229], off
	s_waitcnt vmcnt(8)
	s_waitcnt lgkmcnt(0)
	s_barrier
	s_setprio 1
	s_waitcnt lgkmcnt(0)
	v_mfma_f32_16x16x32_bf16 v[124:127], v[160:163], v[196:199], 0
	v_mfma_f32_16x16x32_bf16 v[120:123], v[168:171], v[196:199], 0
	v_mfma_f32_16x16x32_bf16 v[116:119], v[160:163], v[204:207], 0
	v_mfma_f32_16x16x32_bf16 v[112:115], v[168:171], v[204:207], 0
	v_mfma_f32_16x16x32_bf16 v[100:103], v[160:163], v[212:215], 0
	v_mfma_f32_16x16x32_bf16 v[96:99], v[168:171], v[212:215], 0
	v_mfma_f32_16x16x32_bf16 v[84:87], v[160:163], v[220:223], 0
	v_mfma_f32_16x16x32_bf16 v[80:83], v[168:171], v[220:223], 0
	v_mfma_f32_16x16x32_bf16 v[124:127], v[164:167], v[200:203], v[124:127]
	v_mfma_f32_16x16x32_bf16 v[120:123], v[172:175], v[200:203], v[120:123]
	v_mfma_f32_16x16x32_bf16 v[116:119], v[164:167], v[208:211], v[116:119]
	v_mfma_f32_16x16x32_bf16 v[112:115], v[172:175], v[208:211], v[112:115]
	v_mfma_f32_16x16x32_bf16 v[100:103], v[164:167], v[216:219], v[100:103]
	v_mfma_f32_16x16x32_bf16 v[96:99], v[172:175], v[216:219], v[96:99]
	v_mfma_f32_16x16x32_bf16 v[84:87], v[164:167], v[224:227], v[84:87]
	v_mfma_f32_16x16x32_bf16 v[80:83], v[172:175], v[224:227], v[80:83]
	v_mfma_f32_16x16x32_bf16 v[108:111], v[180:183], v[196:199], 0
	v_mfma_f32_16x16x32_bf16 v[104:107], v[188:191], v[196:199], 0
	v_mfma_f32_16x16x32_bf16 v[92:95], v[180:183], v[204:207], 0
	v_mfma_f32_16x16x32_bf16 v[88:91], v[188:191], v[204:207], 0
	v_mfma_f32_16x16x32_bf16 v[76:79], v[180:183], v[212:215], 0
	v_mfma_f32_16x16x32_bf16 v[72:75], v[188:191], v[212:215], 0
	v_mfma_f32_16x16x32_bf16 v[68:71], v[180:183], v[220:223], 0
	v_mfma_f32_16x16x32_bf16 v[64:67], v[188:191], v[220:223], 0
	v_mfma_f32_16x16x32_bf16 v[108:111], v[184:187], v[200:203], v[108:111]
	v_mfma_f32_16x16x32_bf16 v[104:107], v[192:195], v[200:203], v[104:107]
	v_mfma_f32_16x16x32_bf16 v[92:95], v[184:187], v[208:211], v[92:95]
	v_mfma_f32_16x16x32_bf16 v[88:91], v[192:195], v[208:211], v[88:91]
	v_mfma_f32_16x16x32_bf16 v[76:79], v[184:187], v[216:219], v[76:79]
	v_mfma_f32_16x16x32_bf16 v[72:75], v[192:195], v[216:219], v[72:75]
	v_mfma_f32_16x16x32_bf16 v[68:71], v[184:187], v[224:227], v[68:71]
	v_mfma_f32_16x16x32_bf16 v[64:67], v[192:195], v[224:227], v[64:67]
	s_barrier
; #define PG8_STAGE(bufoff, gbase, voff) do { _Pragma("unroll") for (int _i = 0; _i < 2; ++_i) \
;         __builtin_amdgcn_global_load_lds((const unsigned*)((const char*)(gbase) + (voff)[_i]), (LAS unsigned*)(lds + (bufoff) + ldsw + _i * 8192), 16, 0, 0); } while (0)
; #define PG8_LDA(dst, b, h) do { _Pragma("unroll") for (int m = 0; m < 4; ++m) _Pragma("unroll") for (int k = 0; k < 2; ++k) dst[m][k] = *(const LAS bf16x8*)(lds + PG8_SA(b, h) + aoff + m * 2048 + k * 1024); } while (0)
; #define PG8_MMA(ai, bj, At, Bt) do { __builtin_amdgcn_s_setprio(1); _Pragma("unroll") for (int m = 0; m < 4; ++m) _Pragma("unroll") for (int n = 0; n < 2; ++n) _Pragma("unroll") for (int k = 0; k < 2; ++k) \
;         acc[ai][bj][m][n] = __builtin_amdgcn_mfma_f32_16x16x32_bf16(Bt[n][k], At[m][k], acc[ai][bj][m][n], 0, 0, 0); __builtin_amdgcn_s_setprio(0); } while (0)
; #define PG8_WAIT_V(n) asm volatile("s_waitcnt vmcnt(" #n ")" ::: "memory")
; #define PG8_WAIT_L(n) asm volatile("s_waitcnt lgkmcnt(" #n ")" ::: "memory")
; #define PG8_BAR __builtin_amdgcn_s_barrier()
; #define PG8_SCHED __builtin_amdgcn_sched_barrier(0)
; template <class Epi, class Sched, bool ALIGN_EPI>
; __device__ __forceinline__ void gemm_phase(LAS unsigned char* lds, const int wid, const int lda_, const int ldb_, const int K_, const Sched& S, const Epi& E) {
;     ...
;             PG8_LDA(At, 0, 1); PG8_STAGE(PG8_SB(0, 0), b2, voffB); PG8_STAGE(PG8_SB(0, 1), b2 + hstepB, voffB); PG8_STAGE(PG8_SA(0, 0), a2, voffA);
;             PG8_WAIT_V(8); PG8_WAIT_L(0); PG8_BAR; PG8_MMA(1, 0, At, B0); PG8_MMA(1, 1, At, B1); PG8_BAR; PG8_SCHED;
	s_add_i32 s27, s86, s3
	v_lshl_add_u64 v[228:229], s[80:81], 0, v[176:177]
	s_mov_b32 m0, s27
	ds_read_b128 v[196:199], v139 offset:16384
	ds_read_b128 v[200:203], v139 offset:17408
	ds_read_b128 v[204:207], v139 offset:18432
	ds_read_b128 v[208:211], v139 offset:19456
	ds_read_b128 v[212:215], v139 offset:20480
	ds_read_b128 v[216:219], v139 offset:21504
	ds_read_b128 v[220:223], v139 offset:22528
	ds_read_b128 v[224:227], v139 offset:23552
	global_load_lds_dwordx4 v[228:229], off
	s_add_i32 m0, s27, 0x2000
	v_lshl_add_u64 v[230:231], s[80:81], 0, v[128:129]
	s_add_u32 s80, s80, s30
	s_addc_u32 s81, s81, s31
	s_add_i32 s17, s17, s3
	global_load_lds_dwordx4 v[230:231], off
	v_lshl_add_u64 v[232:233], s[80:81], 0, v[176:177]
	s_mov_b32 m0, s17
	v_lshl_add_u64 v[234:235], s[80:81], 0, v[128:129]
	global_load_lds_dwordx4 v[232:233], off
	s_add_i32 m0, s17, 0x2000
	v_lshl_add_u64 v[236:237], s[94:95], 0, v[132:133]
	global_load_lds_dwordx4 v[234:235], off
	s_mov_b32 m0, s16
	v_lshl_add_u64 v[246:247], s[94:95], 0, v[130:131]
	global_load_lds_dwordx4 v[236:237], off
	s_mov_b32 m0, s35
	s_nop 0
	global_load_lds_dwordx4 v[246:247], off
	s_waitcnt vmcnt(8)
	s_waitcnt lgkmcnt(0)
	s_barrier
	s_waitcnt lgkmcnt(0)
	v_mfma_f32_16x16x32_bf16 v[60:63], v[160:163], v[196:199], 0
	v_mfma_f32_16x16x32_bf16 v[56:59], v[168:171], v[196:199], 0
	v_mfma_f32_16x16x32_bf16 v[52:55], v[160:163], v[204:207], 0
	v_mfma_f32_16x16x32_bf16 v[48:51], v[168:171], v[204:207], 0
	v_mfma_f32_16x16x32_bf16 v[36:39], v[160:163], v[212:215], 0
	v_mfma_f32_16x16x32_bf16 v[32:35], v[168:171], v[212:215], 0
	v_mfma_f32_16x16x32_bf16 v[20:23], v[160:163], v[220:223], 0
	v_mfma_f32_16x16x32_bf16 v[16:19], v[168:171], v[220:223], 0
	v_mfma_f32_16x16x32_bf16 v[60:63], v[164:167], v[200:203], v[60:63]
	v_mfma_f32_16x16x32_bf16 v[56:59], v[172:175], v[200:203], v[56:59]
	v_mfma_f32_16x16x32_bf16 v[52:55], v[164:167], v[208:211], v[52:55]
	v_mfma_f32_16x16x32_bf16 v[48:51], v[172:175], v[208:211], v[48:51]
	v_mfma_f32_16x16x32_bf16 v[36:39], v[164:167], v[216:219], v[36:39]
	v_mfma_f32_16x16x32_bf16 v[32:35], v[172:175], v[216:219], v[32:35]
	v_mfma_f32_16x16x32_bf16 v[20:23], v[164:167], v[224:227], v[20:23]
	v_mfma_f32_16x16x32_bf16 v[16:19], v[172:175], v[224:227], v[16:19]
	v_mfma_f32_16x16x32_bf16 v[44:47], v[180:183], v[196:199], 0
	v_mfma_f32_16x16x32_bf16 v[40:43], v[188:191], v[196:199], 0
	v_mfma_f32_16x16x32_bf16 v[28:31], v[180:183], v[204:207], 0
	v_mfma_f32_16x16x32_bf16 v[24:27], v[188:191], v[204:207], 0
	v_mfma_f32_16x16x32_bf16 v[12:15], v[180:183], v[212:215], 0
	v_mfma_f32_16x16x32_bf16 v[8:11], v[188:191], v[212:215], 0
	v_mfma_f32_16x16x32_bf16 v[4:7], v[180:183], v[220:223], 0
	v_mfma_f32_16x16x32_bf16 v[0:3], v[188:191], v[220:223], 0
	v_mfma_f32_16x16x32_bf16 v[44:47], v[184:187], v[200:203], v[44:47]
	v_mfma_f32_16x16x32_bf16 v[40:43], v[192:195], v[200:203], v[40:43]
	v_mfma_f32_16x16x32_bf16 v[28:31], v[184:187], v[208:211], v[28:31]
	v_mfma_f32_16x16x32_bf16 v[24:27], v[192:195], v[208:211], v[24:27]
	v_mfma_f32_16x16x32_bf16 v[12:15], v[184:187], v[216:219], v[12:15]
	v_mfma_f32_16x16x32_bf16 v[8:11], v[192:195], v[216:219], v[8:11]
	v_mfma_f32_16x16x32_bf16 v[4:7], v[184:187], v[224:227], v[4:7]
	v_mfma_f32_16x16x32_bf16 v[0:3], v[192:195], v[224:227], v[0:3]
	s_barrier
	s_branch .Lgemm_join_1120

; #define PG8_STAGE(bufoff, gbase, voff) do { _Pragma("unroll") for (int _i = 0; _i < 2; ++_i) \
;         __builtin_amdgcn_global_load_lds((const unsigned*)((const char*)(gbase) + (voff)[_i]), (LAS unsigned*)(lds + (bufoff) + ldsw + _i * 8192), 16, 0, 0); } while (0)
; #define PG8_LDA(dst, b, h) do { _Pragma("unroll") for (int m = 0; m < 4; ++m) _Pragma("unroll") for (int k = 0; k < 2; ++k) dst[m][k] = *(const LAS bf16x8*)(lds + PG8_SA(b, h) + aoff + m * 2048 + k * 1024); } while (0)
; #define PG8_LDB(dst, b, h) do { _Pragma("unroll") for (int n = 0; n < 2; ++n) _Pragma("unroll") for (int k = 0; k < 2; ++k) dst[n][k] = *(const LAS bf16x8*)(lds + PG8_SB(b, h) + boff + n * 2048 + k * 1024); } while (0)
; #define PG8_MMA(ai, bj, At, Bt) do { __builtin_amdgcn_s_setprio(1); _Pragma("unroll") for (int m = 0; m < 4; ++m) _Pragma("unroll") for (int n = 0; n < 2; ++n) _Pragma("unroll") for (int k = 0; k < 2; ++k) \
;         acc[ai][bj][m][n] = __builtin_amdgcn_mfma_f32_16x16x32_bf16(Bt[n][k], At[m][k], acc[ai][bj][m][n], 0, 0, 0); __builtin_amdgcn_s_setprio(0); } while (0)
; #define PG8_WAIT_V(n) asm volatile("s_waitcnt vmcnt(" #n ")" ::: "memory")
; #define PG8_WAIT_L(n) asm volatile("s_waitcnt lgkmcnt(" #n ")" ::: "memory")
; #define PG8_BAR __builtin_amdgcn_s_barrier()
; #define PG8_SCHED __builtin_amdgcn_sched_barrier(0)
; template <class Epi, class Sched, bool ALIGN_EPI>
; __device__ __forceinline__ void gemm_phase(LAS unsigned char* lds, const int wid, const int lda_, const int ldb_, const int K_, const Sched& S, const Epi& E) {
;     ...
;             PG8_LDB(B0, 1, 0); PG8_LDB(B1, 1, 1); PG8_SCHED; PG8_LDA(At, 1, 0); PG8_STAGE(PG8_SA(0, 1), a2 + hstepA, voffA);
;             PG8_WAIT_V(8); PG8_WAIT_L(0); PG8_BAR; PG8_MMA(0, 0, At, B0); PG8_MMA(0, 1, At, B1); PG8_BAR; PG8_SCHED;
;             PG8_LDA(At, 1, 1); PG8_STAGE(PG8_SB(1, 0), b3, voffB); PG8_STAGE(PG8_SB(1, 1), b3 + hstepB, voffB); PG8_STAGE(PG8_SA(1, 0), a3, voffA);
;             PG8_WAIT_V(8); PG8_WAIT_L(0); PG8_BAR; PG8_MMA(1, 0, At, B0); PG8_MMA(1, 1, At, B1); PG8_BAR; PG8_SCHED;
.Lgemm_join_1120:
	s_add_i32 s17, 0, 0x18000
	v_add_u32_e32 v141, s17, v135
	s_add_i32 s27, 0, 0x1c000
	ds_read_b128 v[160:163], v141
	ds_read_b128 v[164:167], v141 offset:1024
	ds_read_b128 v[168:171], v141 offset:2048
	ds_read_b128 v[172:175], v141 offset:3072
	v_add_u32_e32 v141, s27, v135
	ds_read_b128 v[180:183], v141
	ds_read_b128 v[184:187], v141 offset:1024
	ds_read_b128 v[188:191], v141 offset:2048
	ds_read_b128 v[192:195], v141 offset:3072
	s_add_u32 s80, s94, s10
	s_addc_u32 s81, s95, s11
	s_mov_b32 m0, s39
	v_lshl_add_u64 v[248:249], s[80:81], 0, v[132:133]
	ds_read_b128 v[196:199], v139 offset:32768
	ds_read_b128 v[200:203], v139 offset:33792
	ds_read_b128 v[204:207], v139 offset:34816
	ds_read_b128 v[208:211], v139 offset:35840
	ds_read_b128 v[212:215], v139 offset:36864
	ds_read_b128 v[216:219], v139 offset:37888
	ds_read_b128 v[220:223], v139 offset:38912
	ds_read_b128 v[224:227], v139 offset:39936
	global_load_lds_dwordx4 v[248:249], off
	v_lshl_add_u64 v[248:249], s[80:81], 0, v[130:131]
	s_mov_b32 m0, s72
	s_nop 0
	global_load_lds_dwordx4 v[248:249], off
	s_waitcnt vmcnt(8)
	s_waitcnt lgkmcnt(0)
	s_barrier
	s_waitcnt lgkmcnt(0)
	v_mfma_f32_16x16x32_bf16 v[124:127], v[160:163], v[196:199], v[124:127]
	v_mfma_f32_16x16x32_bf16 v[120:123], v[168:171], v[196:199], v[120:123]
	v_mfma_f32_16x16x32_bf16 v[116:119], v[160:163], v[204:207], v[116:119]
	v_mfma_f32_16x16x32_bf16 v[112:115], v[168:171], v[204:207], v[112:115]
	v_mfma_f32_16x16x32_bf16 v[100:103], v[160:163], v[212:215], v[100:103]
	v_mfma_f32_16x16x32_bf16 v[96:99], v[168:171], v[212:215], v[96:99]
	v_mfma_f32_16x16x32_bf16 v[84:87], v[160:163], v[220:223], v[84:87]
	v_mfma_f32_16x16x32_bf16 v[80:83], v[168:171], v[220:223], v[80:83]
	v_mfma_f32_16x16x32_bf16 v[124:127], v[164:167], v[200:203], v[124:127]
	v_mfma_f32_16x16x32_bf16 v[120:123], v[172:175], v[200:203], v[120:123]
	v_mfma_f32_16x16x32_bf16 v[116:119], v[164:167], v[208:211], v[116:119]
	v_mfma_f32_16x16x32_bf16 v[112:115], v[172:175], v[208:211], v[112:115]
	v_mfma_f32_16x16x32_bf16 v[100:103], v[164:167], v[216:219], v[100:103]
	v_mfma_f32_16x16x32_bf16 v[96:99], v[172:175], v[216:219], v[96:99]
	v_mfma_f32_16x16x32_bf16 v[84:87], v[164:167], v[224:227], v[84:87]
	v_mfma_f32_16x16x32_bf16 v[80:83], v[172:175], v[224:227], v[80:83]
	v_mfma_f32_16x16x32_bf16 v[108:111], v[180:183], v[196:199], v[108:111]
	v_mfma_f32_16x16x32_bf16 v[104:107], v[188:191], v[196:199], v[104:107]
	v_mfma_f32_16x16x32_bf16 v[92:95], v[180:183], v[204:207], v[92:95]
	v_mfma_f32_16x16x32_bf16 v[88:91], v[188:191], v[204:207], v[88:91]
	v_mfma_f32_16x16x32_bf16 v[76:79], v[180:183], v[212:215], v[76:79]
	v_mfma_f32_16x16x32_bf16 v[72:75], v[188:191], v[212:215], v[72:75]
	v_mfma_f32_16x16x32_bf16 v[68:71], v[180:183], v[220:223], v[68:71]
	v_mfma_f32_16x16x32_bf16 v[64:67], v[188:191], v[220:223], v[64:67]
	v_mfma_f32_16x16x32_bf16 v[108:111], v[184:187], v[200:203], v[108:111]
	v_mfma_f32_16x16x32_bf16 v[104:107], v[192:195], v[200:203], v[104:107]
	v_mfma_f32_16x16x32_bf16 v[92:95], v[184:187], v[208:211], v[92:95]
	v_mfma_f32_16x16x32_bf16 v[88:91], v[192:195], v[208:211], v[88:91]
	v_mfma_f32_16x16x32_bf16 v[76:79], v[184:187], v[216:219], v[76:79]
	v_mfma_f32_16x16x32_bf16 v[72:75], v[192:195], v[216:219], v[72:75]
	v_mfma_f32_16x16x32_bf16 v[68:71], v[184:187], v[224:227], v[68:71]
	v_mfma_f32_16x16x32_bf16 v[64:67], v[192:195], v[224:227], v[64:67]
	s_barrier
	s_add_i32 s17, s17, s3
	v_lshl_add_u64 v[228:229], v[228:229], 0, s[24:25]
	s_mov_b32 m0, s17
	ds_read_b128 v[196:199], v139 offset:49152
	ds_read_b128 v[200:203], v139 offset:50176
	ds_read_b128 v[204:207], v139 offset:51200
	ds_read_b128 v[208:211], v139 offset:52224
	ds_read_b128 v[212:215], v139 offset:53248
	ds_read_b128 v[216:219], v139 offset:54272
	ds_read_b128 v[220:223], v139 offset:55296
	ds_read_b128 v[224:227], v139 offset:56320
	global_load_lds_dwordx4 v[228:229], off
	v_lshl_add_u64 v[228:229], v[230:231], 0, s[24:25]
	s_add_i32 m0, s17, 0x2000
	s_add_i32 s17, s27, s3
	global_load_lds_dwordx4 v[228:229], off
	v_lshl_add_u64 v[228:229], v[232:233], 0, s[24:25]
	s_mov_b32 m0, s17
	s_nop 0
	global_load_lds_dwordx4 v[228:229], off
	v_lshl_add_u64 v[228:229], v[234:235], 0, s[24:25]
	s_add_i32 m0, s17, 0x2000
	s_nop 0
	global_load_lds_dwordx4 v[228:229], off
	v_lshl_add_u64 v[228:229], v[236:237], 0, s[24:25]
	s_mov_b32 m0, s73
	s_nop 0
	global_load_lds_dwordx4 v[228:229], off
	v_lshl_add_u64 v[228:229], v[246:247], 0, s[24:25]
	s_mov_b32 m0, s74
	s_nop 0
	global_load_lds_dwordx4 v[228:229], off
	s_waitcnt vmcnt(8)
	s_waitcnt lgkmcnt(0)
	s_barrier
; __device__ __forceinline__ unsigned cvt_pk_bf16(float lo, float hi) { const f32x2 v = {lo, hi}; return __builtin_bit_cast(unsigned, __builtin_convertvector(v, bf16x2_t)); }
; #define PG8_MMA(ai, bj, At, Bt) do { __builtin_amdgcn_s_setprio(1); _Pragma("unroll") for (int m = 0; m < 4; ++m) _Pragma("unroll") for (int n = 0; n < 2; ++n) _Pragma("unroll") for (int k = 0; k < 2; ++k) \
;         acc[ai][bj][m][n] = __builtin_amdgcn_mfma_f32_16x16x32_bf16(Bt[n][k], At[m][k], acc[ai][bj][m][n], 0, 0, 0); __builtin_amdgcn_s_setprio(0); } while (0)
; #define PG8_WAIT_V(n) asm volatile("s_waitcnt vmcnt(" #n ")" ::: "memory")
; #define PG8_WAIT_L(n) asm volatile("s_waitcnt lgkmcnt(" #n ")" ::: "memory")
; #define PG8_BAR __builtin_amdgcn_s_barrier()
; #define PG8_SCHED __builtin_amdgcn_sched_barrier(0)
;     template <class Sched> __device__ __forceinline__ void operator()(const f32x4 (&acc)[2][2][4][2], const Unit& u, const Sched& S, int wr, int wc, int fr, int fq) const {
;     ...
;         if (kind == 0) {
;             bf16_t* base = (bf16_t*)uo;
; #pragma unroll
;             for (int ai = 0; ai < 2; ++ai)
; #pragma unroll
;                 for (int m = 0; m < 4; ++m) { bf16_t* rowp = base + (size_t)(rl0 + ai * HALF + m * 16) * ldo + cl0;
; #pragma unroll
;                     for (int bj = 0; bj < 2; ++bj) { const f32x4 v0 = acc[ai][bj][m][0], v1 = acc[ai][bj][m][1];
;                         u32x4 w; w.x = cvt_pk_bf16(v0[0], v0[1]); w.y = cvt_pk_bf16(v0[2], v0[3]); w.z = cvt_pk_bf16(v1[0], v1[1]); w.w = cvt_pk_bf16(v1[2], v1[3]);
;                         *(u32x4*)(rowp + bj * HALF) = w; } }
; template <class Epi, class Sched, bool ALIGN_EPI>
; __device__ __forceinline__ void gemm_phase(LAS unsigned char* lds, const int wid, const int lda_, const int ldb_, const int K_, const Sched& S, const Epi& E) {
;     ...
;             PG8_WAIT_V(8); PG8_WAIT_L(0); PG8_BAR; PG8_MMA(1, 0, At, B0); PG8_MMA(1, 1, At, B1); PG8_BAR; PG8_SCHED;
;         }
;         if constexpr (ALIGN_EPI) { if (wr == 0) PG8_BAR; }
;         E(acc, cur, S, wr, wc, fr, fq);
	s_waitcnt lgkmcnt(0)
	v_mfma_f32_16x16x32_bf16 v[60:63], v[160:163], v[196:199], v[60:63]
	v_mfma_f32_16x16x32_bf16 v[56:59], v[168:171], v[196:199], v[56:59]
	v_mfma_f32_16x16x32_bf16 v[52:55], v[160:163], v[204:207], v[52:55]
	v_mfma_f32_16x16x32_bf16 v[48:51], v[168:171], v[204:207], v[48:51]
	v_mfma_f32_16x16x32_bf16 v[36:39], v[160:163], v[212:215], v[36:39]
	v_mfma_f32_16x16x32_bf16 v[32:35], v[168:171], v[212:215], v[32:35]
	v_mfma_f32_16x16x32_bf16 v[20:23], v[160:163], v[220:223], v[20:23]
	v_mfma_f32_16x16x32_bf16 v[16:19], v[168:171], v[220:223], v[16:19]
	v_mfma_f32_16x16x32_bf16 v[60:63], v[164:167], v[200:203], v[60:63]
	v_mfma_f32_16x16x32_bf16 v[56:59], v[172:175], v[200:203], v[56:59]
	v_mfma_f32_16x16x32_bf16 v[52:55], v[164:167], v[208:211], v[52:55]
	v_mfma_f32_16x16x32_bf16 v[48:51], v[172:175], v[208:211], v[48:51]
	v_mfma_f32_16x16x32_bf16 v[36:39], v[164:167], v[216:219], v[36:39]
	v_mfma_f32_16x16x32_bf16 v[32:35], v[172:175], v[216:219], v[32:35]
	v_mfma_f32_16x16x32_bf16 v[20:23], v[164:167], v[224:227], v[20:23]
	v_mfma_f32_16x16x32_bf16 v[16:19], v[172:175], v[224:227], v[16:19]
	v_mfma_f32_16x16x32_bf16 v[44:47], v[180:183], v[196:199], v[44:47]
	v_mfma_f32_16x16x32_bf16 v[40:43], v[188:191], v[196:199], v[40:43]
	v_mfma_f32_16x16x32_bf16 v[28:31], v[180:183], v[204:207], v[28:31]
	v_mfma_f32_16x16x32_bf16 v[24:27], v[188:191], v[204:207], v[24:27]
	v_mfma_f32_16x16x32_bf16 v[12:15], v[180:183], v[212:215], v[12:15]
	v_mfma_f32_16x16x32_bf16 v[8:11], v[188:191], v[212:215], v[8:11]
	v_mfma_f32_16x16x32_bf16 v[4:7], v[180:183], v[220:223], v[4:7]
	v_mfma_f32_16x16x32_bf16 v[0:3], v[188:191], v[220:223], v[0:3]
	v_mfma_f32_16x16x32_bf16 v[44:47], v[184:187], v[200:203], v[44:47]
	v_mfma_f32_16x16x32_bf16 v[40:43], v[192:195], v[200:203], v[40:43]
	v_mfma_f32_16x16x32_bf16 v[28:31], v[184:187], v[208:211], v[28:31]
	v_mfma_f32_16x16x32_bf16 v[24:27], v[192:195], v[208:211], v[24:27]
	v_mfma_f32_16x16x32_bf16 v[12:15], v[184:187], v[216:219], v[12:15]
	v_mfma_f32_16x16x32_bf16 v[8:11], v[192:195], v[216:219], v[8:11]
	v_mfma_f32_16x16x32_bf16 v[4:7], v[184:187], v[224:227], v[4:7]
	v_mfma_f32_16x16x32_bf16 v[0:3], v[192:195], v[224:227], v[0:3]
	s_barrier
	s_add_i32 s78, s78, 2
	s_add_u32 s50, s50, 0x100
	s_addc_u32 s51, s51, 0
	s_cmp_gt_u32 s78, 29
	s_cbranch_scc0 .LBB0_1120
	s_setprio 0
	s_sub_i32 s4, s38, 22
	s_ashr_i32 s5, s38, 31
	s_cmp_lt_i32 s38, 22
	s_cselect_b32 s5, s5, 0
	s_cselect_b32 s4, s38, s4
	s_mov_b32 s17, 0x2bc00000
	s_cselect_b32 s17, 0x1f600000, s17
	s_lshl_b64 s[4:5], s[4:5], 9
	s_add_u32 s4, s66, s4
	s_addc_u32 s5, s67, s5
	s_add_u32 s4, s4, s17
	s_addc_u32 s5, s5, 0
	s_mul_i32 s27, s34, 0x2c0000
	s_mul_hi_i32 s17, s34, 0x2c0000
	s_add_u32 s4, s4, s27
	s_addc_u32 s5, s5, s17
	s_movk_i32 s17, 0x1600
	v_lshl_add_u64 v[156:157], v[136:137], 1, s[4:5]
	v_mad_i64_i32 v[158:159], s[4:5], s17, v134, 0
	v_lshl_add_u64 v[158:159], v[158:159], 1, v[156:157]
	v_cvt_pk_bf16_f32 v108, v108, v109
	v_cvt_pk_bf16_f32 v109, v110, v111
	v_cvt_pk_bf16_f32 v110, v104, v105
	v_cvt_pk_bf16_f32 v111, v106, v107
	v_mad_i64_i32 v[104:105], s[4:5], s17, v138, 0
	v_cvt_pk_bf16_f32 v124, v124, v125
	v_cvt_pk_bf16_f32 v125, v126, v127
	v_cvt_pk_bf16_f32 v126, v120, v121
	v_cvt_pk_bf16_f32 v127, v122, v123
	global_store_dwordx4 v[158:159], v[108:111], off offset:256
	v_cvt_pk_bf16_f32 v92, v92, v93
	v_cvt_pk_bf16_f32 v93, v94, v95
	v_lshl_add_u64 v[108:109], v[104:105], 1, v[156:157]
	v_cvt_pk_bf16_f32 v94, v88, v89
	v_cvt_pk_bf16_f32 v95, v90, v91
	v_mad_i64_i32 v[88:89], s[4:5], s17, v140, 0
	global_store_dwordx4 v[158:159], v[124:127], off
	v_cvt_pk_bf16_f32 v104, v116, v117
	v_cvt_pk_bf16_f32 v105, v118, v119
	v_cvt_pk_bf16_f32 v106, v112, v113
	v_cvt_pk_bf16_f32 v107, v114, v115
	global_store_dwordx4 v[108:109], v[92:95], off offset:256
	v_cvt_pk_bf16_f32 v76, v76, v77
	v_cvt_pk_bf16_f32 v77, v78, v79
	v_lshl_add_u64 v[92:93], v[88:89], 1, v[156:157]
	v_cvt_pk_bf16_f32 v78, v72, v73
	v_cvt_pk_bf16_f32 v79, v74, v75
	v_mad_i64_i32 v[72:73], s[4:5], s17, v142, 0
	v_cvt_pk_bf16_f32 v68, v68, v69
	v_cvt_pk_bf16_f32 v69, v70, v71
	v_cvt_pk_bf16_f32 v70, v64, v65
	v_mad_i64_i32 v[64:65], s[4:5], s17, v144, 0
	global_store_dwordx4 v[108:109], v[104:107], off
	v_cvt_pk_bf16_f32 v88, v100, v101
	v_cvt_pk_bf16_f32 v89, v102, v103
	v_cvt_pk_bf16_f32 v90, v96, v97
	v_cvt_pk_bf16_f32 v91, v98, v99
	global_store_dwordx4 v[92:93], v[76:79], off offset:256
	v_cvt_pk_bf16_f32 v74, v80, v81
	v_cvt_pk_bf16_f32 v75, v82, v83
	v_lshl_add_u64 v[76:77], v[72:73], 1, v[156:157]
	v_cvt_pk_bf16_f32 v72, v84, v85
	v_cvt_pk_bf16_f32 v73, v86, v87
	v_cvt_pk_bf16_f32 v71, v66, v67
	v_lshl_add_u64 v[64:65], v[64:65], 1, v[156:157]
	v_cvt_pk_bf16_f32 v44, v44, v45
	v_cvt_pk_bf16_f32 v45, v46, v47
	v_cvt_pk_bf16_f32 v46, v40, v41
	v_cvt_pk_bf16_f32 v47, v42, v43
	v_mad_i64_i32 v[40:41], s[4:5], s17, v146, 0
	global_store_dwordx4 v[92:93], v[88:91], off
	global_store_dwordx4 v[76:77], v[72:75], off
	global_store_dwordx4 v[76:77], v[68:71], off offset:256
	v_cvt_pk_bf16_f32 v60, v60, v61
	v_cvt_pk_bf16_f32 v61, v62, v63
	v_cvt_pk_bf16_f32 v62, v56, v57
	v_cvt_pk_bf16_f32 v63, v58, v59
	global_store_dwordx4 v[64:65], v[44:47], off offset:256
	v_cvt_pk_bf16_f32 v28, v28, v29
	v_cvt_pk_bf16_f32 v29, v30, v31
	v_lshl_add_u64 v[44:45], v[40:41], 1, v[156:157]
	v_cvt_pk_bf16_f32 v30, v24, v25
	v_cvt_pk_bf16_f32 v31, v26, v27
	v_mad_i64_i32 v[24:25], s[4:5], s17, v148, 0
	global_store_dwordx4 v[64:65], v[60:63], off
	v_cvt_pk_bf16_f32 v40, v52, v53
	v_cvt_pk_bf16_f32 v41, v54, v55
	v_cvt_pk_bf16_f32 v42, v48, v49
	v_cvt_pk_bf16_f32 v43, v50, v51
	global_store_dwordx4 v[44:45], v[28:31], off offset:256
	v_cvt_pk_bf16_f32 v12, v12, v13
	v_cvt_pk_bf16_f32 v13, v14, v15
	v_lshl_add_u64 v[28:29], v[24:25], 1, v[156:157]
	v_cvt_pk_bf16_f32 v14, v8, v9
	v_cvt_pk_bf16_f32 v15, v10, v11
	v_mad_i64_i32 v[8:9], s[4:5], s17, v150, 0
	global_store_dwordx4 v[44:45], v[40:43], off
	v_cvt_pk_bf16_f32 v24, v36, v37
	v_cvt_pk_bf16_f32 v25, v38, v39
	v_cvt_pk_bf16_f32 v26, v32, v33
	v_cvt_pk_bf16_f32 v27, v34, v35
	global_store_dwordx4 v[28:29], v[12:15], off offset:256
	v_cvt_pk_bf16_f32 v10, v16, v17
	v_cvt_pk_bf16_f32 v11, v18, v19
	v_lshl_add_u64 v[12:13], v[8:9], 1, v[156:157]
	v_cvt_pk_bf16_f32 v8, v20, v21
	v_cvt_pk_bf16_f32 v9, v22, v23
	v_cvt_pk_bf16_f32 v4, v4, v5
	v_cvt_pk_bf16_f32 v5, v6, v7
	v_cvt_pk_bf16_f32 v6, v0, v1
	v_cvt_pk_bf16_f32 v7, v2, v3
	s_and_b64 vcc, exec, s[36:37]
	s_mov_b32 s38, s42
	s_mov_b32 s34, s44
	s_mov_b64 s[50:51], s[48:49]
	s_mov_b64 s[40:41], s[46:47]
	global_store_dwordx4 v[28:29], v[24:27], off
	global_store_dwordx4 v[12:13], v[8:11], off
	global_store_dwordx4 v[12:13], v[4:7], off offset:256
	s_cbranch_vccz .LBB0_1117
	v_readlane_b32 s4, v253, 1
	s_waitcnt vmcnt(0)
	v_readlane_b32 s5, v253, 2
	s_andn2_b64 vcc, exec, s[4:5]
	s_cbranch_vccnz .LBB0_1124
	s_barrier

; __device__ __forceinline__ void fresh_ids(Frame& F) { F.lane = fresh_lane(); F.tid = F.wave * 64 + F.lane; }
; __device__ __forceinline__ void ffn_conv_phase(Frame& F, int L, int nrows, bool probe_alt = false) {
;     fresh_ids(F);
;     const int gw = blockIdx.x * NWAVES + F.wave, NGW = F.G * NWAVES;
.LBB0_1202:
	s_andn2_b64 vcc, exec, s[0:1]
	s_cbranch_vccnz .LBB0_1319
	s_cmp_ge_u32 s33, 0x100
	s_cbranch_scc1 .Lffn_prio_skip
	s_setprio 1

; #define PG8_STAGE(bufoff, gbase, voff) do { _Pragma("unroll") for (int _i = 0; _i < 2; ++_i) \
;         __builtin_amdgcn_global_load_lds((const unsigned*)((const char*)(gbase) + (voff)[_i]), (LAS unsigned*)(lds + (bufoff) + ldsw + _i * 8192), 16, 0, 0); } while (0)
; #define PG8_LDA(dst, b, h) do { _Pragma("unroll") for (int m = 0; m < 4; ++m) _Pragma("unroll") for (int k = 0; k < 2; ++k) dst[m][k] = *(const LAS bf16x8*)(lds + PG8_SA(b, h) + aoff + m * 2048 + k * 1024); } while (0)
; #define PG8_LDB(dst, b, h) do { _Pragma("unroll") for (int n = 0; n < 2; ++n) _Pragma("unroll") for (int k = 0; k < 2; ++k) dst[n][k] = *(const LAS bf16x8*)(lds + PG8_SB(b, h) + boff + n * 2048 + k * 1024); } while (0)
; #define PG8_MMA(ai, bj, At, Bt) do { __builtin_amdgcn_s_setprio(1); _Pragma("unroll") for (int m = 0; m < 4; ++m) _Pragma("unroll") for (int n = 0; n < 2; ++n) _Pragma("unroll") for (int k = 0; k < 2; ++k) \
;         acc[ai][bj][m][n] = __builtin_amdgcn_mfma_f32_16x16x32_bf16(Bt[n][k], At[m][k], acc[ai][bj][m][n], 0, 0, 0); __builtin_amdgcn_s_setprio(0); } while (0)
; #define PG8_WAIT_V(n) asm volatile("s_waitcnt vmcnt(" #n ")" ::: "memory")
; #define PG8_WAIT_L(n) asm volatile("s_waitcnt lgkmcnt(" #n ")" ::: "memory")
; #define PG8_BAR __builtin_amdgcn_s_barrier()
; #define PG8_SCHED __builtin_amdgcn_sched_barrier(0)
; template <class Epi, class Sched, bool ALIGN_EPI>
; __device__ __forceinline__ void gemm_phase(LAS unsigned char* lds, const int wid, const int lda_, const int ldb_, const int K_, const Sched& S, const Epi& E) {
;     ...
;         const bool has_next = S.next(ui + 1, nxt);
;         const int nt = S.nt(cur);
;         const char* nA = has_next ? S.a(nxt) : cA; const char* nB = has_next ? S.b(nxt) : cB;
; #pragma unroll 1
;         for (int t = 0; t < nt; t += 2) {
;             const bool last = (t == nt - 2);
;             const char* a1 = cA + (size_t)(t + 1) * kstep;
;             const char* a2 = last ? nA : cA + (size_t)(t + 2) * kstep; const char* b2 = last ? nB : cB + (size_t)(t + 2) * kstep;
;             const char* a3 = a2 + kstep; const char* b3 = b2 + kstep;
;             PG8_LDB(B0, 0, 0); PG8_LDB(B1, 0, 1); PG8_SCHED; PG8_LDA(At, 0, 0); PG8_STAGE(PG8_SA(1, 1), a1 + hstepA, voffA);
;             PG8_WAIT_V(8); PG8_WAIT_L(0); PG8_BAR; PG8_MMA(0, 0, At, B0); PG8_MMA(0, 1, At, B1); PG8_BAR; PG8_SCHED;
.LBB0_1340:
	s_cmp_gt_i32 s38, -1
	s_cselect_b64 s[44:45], -1, 0
	s_cmp_lt_i32 s38, 0
	s_cselect_b32 s4, 0x58, 22
	s_add_i32 s5, s4, -2
	s_add_u32 s46, s46, 0x80
	s_addc_u32 s47, s47, 0
	s_add_u32 s31, s48, 0x100
	s_mov_b32 s39, 0
	s_addc_u32 s35, s49, 0
	s_add_i32 s76, s39, 2
	s_add_u32 s17, s46, 0x80
	s_addc_u32 s27, s47, 0
	s_add_i32 s77, 0, 0x10000
	s_cmp_eq_u32 s5, s39
	s_cselect_b32 s49, s43, s27
	s_cselect_b32 s48, s42, s17
	v_add_u32_e32 v141, s77, v135
	s_cselect_b32 s79, s37, s35
	s_cselect_b32 s78, s36, s31
	s_add_i32 s17, 0, 0x14000
	ds_read_b128 v[156:159], v141
	ds_read_b128 v[160:163], v141 offset:1024
	ds_read_b128 v[164:167], v141 offset:2048
	ds_read_b128 v[168:171], v141 offset:3072
	v_add_u32_e32 v141, s17, v135
	ds_read_b128 v[172:175], v141
	ds_read_b128 v[180:183], v141 offset:1024
	ds_read_b128 v[184:187], v141 offset:2048
	ds_read_b128 v[188:191], v141 offset:3072
	v_lshl_add_u64 v[224:225], s[46:47], 0, v[152:153]
	s_add_i32 m0, s16, 0xc000
	ds_read_b128 v[192:195], v139
	ds_read_b128 v[196:199], v139 offset:1024
	ds_read_b128 v[200:203], v139 offset:2048
	ds_read_b128 v[204:207], v139 offset:3072
	ds_read_b128 v[208:211], v139 offset:4096
	ds_read_b128 v[212:215], v139 offset:5120
	ds_read_b128 v[216:219], v139 offset:6144
	ds_read_b128 v[220:223], v139 offset:7168
	global_load_lds_dwordx4 v[224:225], off
	v_lshl_add_u64 v[224:225], s[46:47], 0, v[154:155]
	s_add_i32 m0, s16, 0xe000
	s_nop 0
	global_load_lds_dwordx4 v[224:225], off
	s_waitcnt vmcnt(8)
	s_waitcnt lgkmcnt(0)
	s_barrier
	s_setprio 1
	s_waitcnt lgkmcnt(0)
	v_mfma_f32_16x16x32_bf16 v[124:127], v[156:159], v[192:195], 0
	v_mfma_f32_16x16x32_bf16 v[120:123], v[164:167], v[192:195], 0
	v_mfma_f32_16x16x32_bf16 v[116:119], v[156:159], v[200:203], 0
	v_mfma_f32_16x16x32_bf16 v[112:115], v[164:167], v[200:203], 0
	v_mfma_f32_16x16x32_bf16 v[100:103], v[156:159], v[208:211], 0
	v_mfma_f32_16x16x32_bf16 v[96:99], v[164:167], v[208:211], 0
	v_mfma_f32_16x16x32_bf16 v[84:87], v[156:159], v[216:219], 0
	v_mfma_f32_16x16x32_bf16 v[80:83], v[164:167], v[216:219], 0
	v_mfma_f32_16x16x32_bf16 v[124:127], v[160:163], v[196:199], v[124:127]
	v_mfma_f32_16x16x32_bf16 v[120:123], v[168:171], v[196:199], v[120:123]
	v_mfma_f32_16x16x32_bf16 v[116:119], v[160:163], v[204:207], v[116:119]
	v_mfma_f32_16x16x32_bf16 v[112:115], v[168:171], v[204:207], v[112:115]
	v_mfma_f32_16x16x32_bf16 v[100:103], v[160:163], v[212:215], v[100:103]
	v_mfma_f32_16x16x32_bf16 v[96:99], v[168:171], v[212:215], v[96:99]
	v_mfma_f32_16x16x32_bf16 v[84:87], v[160:163], v[220:223], v[84:87]
	v_mfma_f32_16x16x32_bf16 v[80:83], v[168:171], v[220:223], v[80:83]
	v_mfma_f32_16x16x32_bf16 v[108:111], v[172:175], v[192:195], 0
	v_mfma_f32_16x16x32_bf16 v[104:107], v[184:187], v[192:195], 0
	v_mfma_f32_16x16x32_bf16 v[92:95], v[172:175], v[200:203], 0
	v_mfma_f32_16x16x32_bf16 v[88:91], v[184:187], v[200:203], 0
	v_mfma_f32_16x16x32_bf16 v[76:79], v[172:175], v[208:211], 0
	v_mfma_f32_16x16x32_bf16 v[72:75], v[184:187], v[208:211], 0
	v_mfma_f32_16x16x32_bf16 v[68:71], v[172:175], v[216:219], 0
	v_mfma_f32_16x16x32_bf16 v[64:67], v[184:187], v[216:219], 0
	v_mfma_f32_16x16x32_bf16 v[108:111], v[180:183], v[196:199], v[108:111]
	v_mfma_f32_16x16x32_bf16 v[104:107], v[188:191], v[196:199], v[104:107]
	v_mfma_f32_16x16x32_bf16 v[92:95], v[180:183], v[204:207], v[92:95]
	v_mfma_f32_16x16x32_bf16 v[88:91], v[188:191], v[204:207], v[88:91]
	v_mfma_f32_16x16x32_bf16 v[76:79], v[180:183], v[212:215], v[76:79]
	v_mfma_f32_16x16x32_bf16 v[72:75], v[188:191], v[212:215], v[72:75]
	v_mfma_f32_16x16x32_bf16 v[68:71], v[180:183], v[220:223], v[68:71]
	v_mfma_f32_16x16x32_bf16 v[64:67], v[188:191], v[220:223], v[64:67]
	s_barrier
; #define PG8_STAGE(bufoff, gbase, voff) do { _Pragma("unroll") for (int _i = 0; _i < 2; ++_i) \
;         __builtin_amdgcn_global_load_lds((const unsigned*)((const char*)(gbase) + (voff)[_i]), (LAS unsigned*)(lds + (bufoff) + ldsw + _i * 8192), 16, 0, 0); } while (0)
; #define PG8_LDA(dst, b, h) do { _Pragma("unroll") for (int m = 0; m < 4; ++m) _Pragma("unroll") for (int k = 0; k < 2; ++k) dst[m][k] = *(const LAS bf16x8*)(lds + PG8_SA(b, h) + aoff + m * 2048 + k * 1024); } while (0)
; #define PG8_MMA(ai, bj, At, Bt) do { __builtin_amdgcn_s_setprio(1); _Pragma("unroll") for (int m = 0; m < 4; ++m) _Pragma("unroll") for (int n = 0; n < 2; ++n) _Pragma("unroll") for (int k = 0; k < 2; ++k) \
;         acc[ai][bj][m][n] = __builtin_amdgcn_mfma_f32_16x16x32_bf16(Bt[n][k], At[m][k], acc[ai][bj][m][n], 0, 0, 0); __builtin_amdgcn_s_setprio(0); } while (0)
; #define PG8_WAIT_V(n) asm volatile("s_waitcnt vmcnt(" #n ")" ::: "memory")
; #define PG8_WAIT_L(n) asm volatile("s_waitcnt lgkmcnt(" #n ")" ::: "memory")
; #define PG8_BAR __builtin_amdgcn_s_barrier()
; #define PG8_SCHED __builtin_amdgcn_sched_barrier(0)
; template <class Epi, class Sched, bool ALIGN_EPI>
; __device__ __forceinline__ void gemm_phase(LAS unsigned char* lds, const int wid, const int lda_, const int ldb_, const int K_, const Sched& S, const Epi& E) {
;     ...
;             PG8_LDA(At, 0, 1); PG8_STAGE(PG8_SB(0, 0), b2, voffB); PG8_STAGE(PG8_SB(0, 1), b2 + hstepB, voffB); PG8_STAGE(PG8_SA(0, 0), a2, voffA);
;             PG8_WAIT_V(8); PG8_WAIT_L(0); PG8_BAR; PG8_MMA(1, 0, At, B0); PG8_MMA(1, 1, At, B1); PG8_BAR; PG8_SCHED;
	s_add_i32 s27, s77, s3
	v_lshl_add_u64 v[224:225], s[78:79], 0, v[176:177]
	s_mov_b32 m0, s27
	ds_read_b128 v[192:195], v139 offset:16384
	ds_read_b128 v[196:199], v139 offset:17408
	ds_read_b128 v[200:203], v139 offset:18432
	ds_read_b128 v[204:207], v139 offset:19456
	ds_read_b128 v[208:211], v139 offset:20480
	ds_read_b128 v[212:215], v139 offset:21504
	ds_read_b128 v[216:219], v139 offset:22528
	ds_read_b128 v[220:223], v139 offset:23552
	global_load_lds_dwordx4 v[224:225], off
	s_add_i32 m0, s27, 0x2000
	v_lshl_add_u64 v[226:227], s[78:79], 0, v[132:133]
	s_add_u32 s78, s78, s10
	s_addc_u32 s79, s79, s11
	s_add_i32 s17, s17, s3
	global_load_lds_dwordx4 v[226:227], off
	v_lshl_add_u64 v[228:229], s[78:79], 0, v[176:177]
	s_mov_b32 m0, s17
	v_lshl_add_u64 v[230:231], s[78:79], 0, v[132:133]
	global_load_lds_dwordx4 v[228:229], off
	s_add_i32 m0, s17, 0x2000
	v_lshl_add_u64 v[232:233], s[48:49], 0, v[128:129]
	global_load_lds_dwordx4 v[230:231], off
	s_mov_b32 m0, s16
	v_lshl_add_u64 v[234:235], s[48:49], 0, v[130:131]
	global_load_lds_dwordx4 v[232:233], off
	s_mov_b32 m0, s14
	s_nop 0
	global_load_lds_dwordx4 v[234:235], off
	s_waitcnt vmcnt(8)
	s_waitcnt lgkmcnt(0)
	s_barrier
	s_waitcnt lgkmcnt(0)
	v_mfma_f32_16x16x32_bf16 v[60:63], v[156:159], v[192:195], 0
	v_mfma_f32_16x16x32_bf16 v[56:59], v[164:167], v[192:195], 0
	v_mfma_f32_16x16x32_bf16 v[52:55], v[156:159], v[200:203], 0
	v_mfma_f32_16x16x32_bf16 v[48:51], v[164:167], v[200:203], 0
	v_mfma_f32_16x16x32_bf16 v[36:39], v[156:159], v[208:211], 0
	v_mfma_f32_16x16x32_bf16 v[32:35], v[164:167], v[208:211], 0
	v_mfma_f32_16x16x32_bf16 v[20:23], v[156:159], v[216:219], 0
	v_mfma_f32_16x16x32_bf16 v[16:19], v[164:167], v[216:219], 0
	v_mfma_f32_16x16x32_bf16 v[60:63], v[160:163], v[196:199], v[60:63]
	v_mfma_f32_16x16x32_bf16 v[56:59], v[168:171], v[196:199], v[56:59]
	v_mfma_f32_16x16x32_bf16 v[52:55], v[160:163], v[204:207], v[52:55]
	v_mfma_f32_16x16x32_bf16 v[48:51], v[168:171], v[204:207], v[48:51]
	v_mfma_f32_16x16x32_bf16 v[36:39], v[160:163], v[212:215], v[36:39]
	v_mfma_f32_16x16x32_bf16 v[32:35], v[168:171], v[212:215], v[32:35]
	v_mfma_f32_16x16x32_bf16 v[20:23], v[160:163], v[220:223], v[20:23]
	v_mfma_f32_16x16x32_bf16 v[16:19], v[168:171], v[220:223], v[16:19]
	v_mfma_f32_16x16x32_bf16 v[44:47], v[172:175], v[192:195], 0
	v_mfma_f32_16x16x32_bf16 v[40:43], v[184:187], v[192:195], 0
	v_mfma_f32_16x16x32_bf16 v[28:31], v[172:175], v[200:203], 0
	v_mfma_f32_16x16x32_bf16 v[24:27], v[184:187], v[200:203], 0
	v_mfma_f32_16x16x32_bf16 v[12:15], v[172:175], v[208:211], 0
	v_mfma_f32_16x16x32_bf16 v[8:11], v[184:187], v[208:211], 0
	v_mfma_f32_16x16x32_bf16 v[4:7], v[172:175], v[216:219], 0
	v_mfma_f32_16x16x32_bf16 v[0:3], v[184:187], v[216:219], 0
	v_mfma_f32_16x16x32_bf16 v[44:47], v[180:183], v[196:199], v[44:47]
	v_mfma_f32_16x16x32_bf16 v[40:43], v[188:191], v[196:199], v[40:43]
	v_mfma_f32_16x16x32_bf16 v[28:31], v[180:183], v[204:207], v[28:31]
	v_mfma_f32_16x16x32_bf16 v[24:27], v[188:191], v[204:207], v[24:27]
	v_mfma_f32_16x16x32_bf16 v[12:15], v[180:183], v[212:215], v[12:15]
	v_mfma_f32_16x16x32_bf16 v[8:11], v[188:191], v[212:215], v[8:11]
	v_mfma_f32_16x16x32_bf16 v[4:7], v[180:183], v[220:223], v[4:7]
	v_mfma_f32_16x16x32_bf16 v[0:3], v[188:191], v[220:223], v[0:3]
	s_barrier
	s_branch .Lgemm_join_1341

; #define PG8_STAGE(bufoff, gbase, voff) do { _Pragma("unroll") for (int _i = 0; _i < 2; ++_i) \
;         __builtin_amdgcn_global_load_lds((const unsigned*)((const char*)(gbase) + (voff)[_i]), (LAS unsigned*)(lds + (bufoff) + ldsw + _i * 8192), 16, 0, 0); } while (0)
; #define PG8_LDA(dst, b, h) do { _Pragma("unroll") for (int m = 0; m < 4; ++m) _Pragma("unroll") for (int k = 0; k < 2; ++k) dst[m][k] = *(const LAS bf16x8*)(lds + PG8_SA(b, h) + aoff + m * 2048 + k * 1024); } while (0)
; #define PG8_LDB(dst, b, h) do { _Pragma("unroll") for (int n = 0; n < 2; ++n) _Pragma("unroll") for (int k = 0; k < 2; ++k) dst[n][k] = *(const LAS bf16x8*)(lds + PG8_SB(b, h) + boff + n * 2048 + k * 1024); } while (0)
; #define PG8_MMA(ai, bj, At, Bt) do { __builtin_amdgcn_s_setprio(1); _Pragma("unroll") for (int m = 0; m < 4; ++m) _Pragma("unroll") for (int n = 0; n < 2; ++n) _Pragma("unroll") for (int k = 0; k < 2; ++k) \
;         acc[ai][bj][m][n] = __builtin_amdgcn_mfma_f32_16x16x32_bf16(Bt[n][k], At[m][k], acc[ai][bj][m][n], 0, 0, 0); __builtin_amdgcn_s_setprio(0); } while (0)
; #define PG8_WAIT_V(n) asm volatile("s_waitcnt vmcnt(" #n ")" ::: "memory")
; #define PG8_WAIT_L(n) asm volatile("s_waitcnt lgkmcnt(" #n ")" ::: "memory")
; #define PG8_BAR __builtin_amdgcn_s_barrier()
; #define PG8_SCHED __builtin_amdgcn_sched_barrier(0)
; template <class Epi, class Sched, bool ALIGN_EPI>
; __device__ __forceinline__ void gemm_phase(LAS unsigned char* lds, const int wid, const int lda_, const int ldb_, const int K_, const Sched& S, const Epi& E) {
;     ...
;             PG8_LDB(B0, 1, 0); PG8_LDB(B1, 1, 1); PG8_SCHED; PG8_LDA(At, 1, 0); PG8_STAGE(PG8_SA(0, 1), a2 + hstepA, voffA);
;             PG8_WAIT_V(8); PG8_WAIT_L(0); PG8_BAR; PG8_MMA(0, 0, At, B0); PG8_MMA(0, 1, At, B1); PG8_BAR; PG8_SCHED;
.Lgemm_join_1341:
	s_add_i32 s17, 0, 0x18000
	v_add_u32_e32 v141, s17, v135
	s_add_i32 s27, 0, 0x1c000
	ds_read_b128 v[156:159], v141
	ds_read_b128 v[160:163], v141 offset:1024
	ds_read_b128 v[164:167], v141 offset:2048
	ds_read_b128 v[168:171], v141 offset:3072
	v_add_u32_e32 v141, s27, v135
	ds_read_b128 v[172:175], v141
	ds_read_b128 v[180:183], v141 offset:1024
	ds_read_b128 v[184:187], v141 offset:2048
	ds_read_b128 v[188:191], v141 offset:3072
	s_add_u32 s48, s48, s0
	s_addc_u32 s49, s49, s1
	s_mov_b32 m0, s15
	v_lshl_add_u64 v[236:237], s[48:49], 0, v[128:129]
	ds_read_b128 v[192:195], v139 offset:32768
	ds_read_b128 v[196:199], v139 offset:33792
	ds_read_b128 v[200:203], v139 offset:34816
	ds_read_b128 v[204:207], v139 offset:35840
	ds_read_b128 v[208:211], v139 offset:36864
	ds_read_b128 v[212:215], v139 offset:37888
	ds_read_b128 v[216:219], v139 offset:38912
	ds_read_b128 v[220:223], v139 offset:39936
	global_load_lds_dwordx4 v[236:237], off
	v_lshl_add_u64 v[236:237], s[48:49], 0, v[130:131]
	s_mov_b32 m0, s26
	s_nop 0
	global_load_lds_dwordx4 v[236:237], off
	s_waitcnt vmcnt(8)
	s_waitcnt lgkmcnt(0)
	s_barrier
	s_waitcnt lgkmcnt(0)
	v_mfma_f32_16x16x32_bf16 v[124:127], v[156:159], v[192:195], v[124:127]
	v_mfma_f32_16x16x32_bf16 v[120:123], v[164:167], v[192:195], v[120:123]
	v_mfma_f32_16x16x32_bf16 v[116:119], v[156:159], v[200:203], v[116:119]
	v_mfma_f32_16x16x32_bf16 v[112:115], v[164:167], v[200:203], v[112:115]
	v_mfma_f32_16x16x32_bf16 v[100:103], v[156:159], v[208:211], v[100:103]
	v_mfma_f32_16x16x32_bf16 v[96:99], v[164:167], v[208:211], v[96:99]
	v_mfma_f32_16x16x32_bf16 v[84:87], v[156:159], v[216:219], v[84:87]
	v_mfma_f32_16x16x32_bf16 v[80:83], v[164:167], v[216:219], v[80:83]
	v_mfma_f32_16x16x32_bf16 v[124:127], v[160:163], v[196:199], v[124:127]
	v_mfma_f32_16x16x32_bf16 v[120:123], v[168:171], v[196:199], v[120:123]
	v_mfma_f32_16x16x32_bf16 v[116:119], v[160:163], v[204:207], v[116:119]
	v_mfma_f32_16x16x32_bf16 v[112:115], v[168:171], v[204:207], v[112:115]
	v_mfma_f32_16x16x32_bf16 v[100:103], v[160:163], v[212:215], v[100:103]
	v_mfma_f32_16x16x32_bf16 v[96:99], v[168:171], v[212:215], v[96:99]
	v_mfma_f32_16x16x32_bf16 v[84:87], v[160:163], v[220:223], v[84:87]
	v_mfma_f32_16x16x32_bf16 v[80:83], v[168:171], v[220:223], v[80:83]
	v_mfma_f32_16x16x32_bf16 v[108:111], v[172:175], v[192:195], v[108:111]
	v_mfma_f32_16x16x32_bf16 v[104:107], v[184:187], v[192:195], v[104:107]
	v_mfma_f32_16x16x32_bf16 v[92:95], v[172:175], v[200:203], v[92:95]
	v_mfma_f32_16x16x32_bf16 v[88:91], v[184:187], v[200:203], v[88:91]
	v_mfma_f32_16x16x32_bf16 v[76:79], v[172:175], v[208:211], v[76:79]
	v_mfma_f32_16x16x32_bf16 v[72:75], v[184:187], v[208:211], v[72:75]
	v_mfma_f32_16x16x32_bf16 v[68:71], v[172:175], v[216:219], v[68:71]
	v_mfma_f32_16x16x32_bf16 v[64:67], v[184:187], v[216:219], v[64:67]
	v_mfma_f32_16x16x32_bf16 v[108:111], v[180:183], v[196:199], v[108:111]
	v_mfma_f32_16x16x32_bf16 v[104:107], v[188:191], v[196:199], v[104:107]
	v_mfma_f32_16x16x32_bf16 v[92:95], v[180:183], v[204:207], v[92:95]
	v_mfma_f32_16x16x32_bf16 v[88:91], v[188:191], v[204:207], v[88:91]
	v_mfma_f32_16x16x32_bf16 v[76:79], v[180:183], v[212:215], v[76:79]
	v_mfma_f32_16x16x32_bf16 v[72:75], v[188:191], v[212:215], v[72:75]
	v_mfma_f32_16x16x32_bf16 v[68:71], v[180:183], v[220:223], v[68:71]
	v_mfma_f32_16x16x32_bf16 v[64:67], v[188:191], v[220:223], v[64:67]
	s_barrier
; #define PG8_STAGE(bufoff, gbase, voff) do { _Pragma("unroll") for (int _i = 0; _i < 2; ++_i) \
;         __builtin_amdgcn_global_load_lds((const unsigned*)((const char*)(gbase) + (voff)[_i]), (LAS unsigned*)(lds + (bufoff) + ldsw + _i * 8192), 16, 0, 0); } while (0)
; #define PG8_LDA(dst, b, h) do { _Pragma("unroll") for (int m = 0; m < 4; ++m) _Pragma("unroll") for (int k = 0; k < 2; ++k) dst[m][k] = *(const LAS bf16x8*)(lds + PG8_SA(b, h) + aoff + m * 2048 + k * 1024); } while (0)
; #define PG8_MMA(ai, bj, At, Bt) do { __builtin_amdgcn_s_setprio(1); _Pragma("unroll") for (int m = 0; m < 4; ++m) _Pragma("unroll") for (int n = 0; n < 2; ++n) _Pragma("unroll") for (int k = 0; k < 2; ++k) \
;         acc[ai][bj][m][n] = __builtin_amdgcn_mfma_f32_16x16x32_bf16(Bt[n][k], At[m][k], acc[ai][bj][m][n], 0, 0, 0); __builtin_amdgcn_s_setprio(0); } while (0)
; #define PG8_WAIT_V(n) asm volatile("s_waitcnt vmcnt(" #n ")" ::: "memory")
; #define PG8_WAIT_L(n) asm volatile("s_waitcnt lgkmcnt(" #n ")" ::: "memory")
; #define PG8_BAR __builtin_amdgcn_s_barrier()
; #define PG8_SCHED __builtin_amdgcn_sched_barrier(0)
; template <class Epi, class Sched, bool ALIGN_EPI>
; __device__ __forceinline__ void gemm_phase(LAS unsigned char* lds, const int wid, const int lda_, const int ldb_, const int K_, const Sched& S, const Epi& E) {
;     ...
;             PG8_LDA(At, 1, 1); PG8_STAGE(PG8_SB(1, 0), b3, voffB); PG8_STAGE(PG8_SB(1, 1), b3 + hstepB, voffB); PG8_STAGE(PG8_SA(1, 0), a3, voffA);
;             PG8_WAIT_V(8); PG8_WAIT_L(0); PG8_BAR; PG8_MMA(1, 0, At, B0); PG8_MMA(1, 1, At, B1); PG8_BAR; PG8_SCHED;
;         }
;         if constexpr (ALIGN_EPI) { if (wr == 0) PG8_BAR; }
;         E(acc, cur, S, wr, wc, fr, fq);
;     __device__ __forceinline__ void out(const pg8::Unit& u, char*& o, int& ldo, int& kind) const { ldo = D;
;         if (u.kq < 0) { o = (char*)ws + YOFF + ((size_t)u.pm * 256 * D + (size_t)u.pn * 256) * 2; kind = 0; }
;         else { o = (char*)ws + WS_PART + (((size_t)u.kq * MCTX + (size_t)(u.pm - 64) * 256) * D + (size_t)u.pn * 256) * 2; kind = 0; } }
	s_add_i32 s17, s17, s3
	v_lshl_add_u64 v[224:225], v[224:225], 0, s[24:25]
	s_mov_b32 m0, s17
	ds_read_b128 v[192:195], v139 offset:49152
	ds_read_b128 v[196:199], v139 offset:50176
	ds_read_b128 v[200:203], v139 offset:51200
	ds_read_b128 v[204:207], v139 offset:52224
	ds_read_b128 v[208:211], v139 offset:53248
	ds_read_b128 v[212:215], v139 offset:54272
	ds_read_b128 v[216:219], v139 offset:55296
	ds_read_b128 v[220:223], v139 offset:56320
	global_load_lds_dwordx4 v[224:225], off
	v_lshl_add_u64 v[224:225], v[226:227], 0, s[24:25]
	s_add_i32 m0, s17, 0x2000
	s_add_i32 s17, s27, s3
	global_load_lds_dwordx4 v[224:225], off
	v_lshl_add_u64 v[224:225], v[228:229], 0, s[24:25]
	s_mov_b32 m0, s17
	s_nop 0
	global_load_lds_dwordx4 v[224:225], off
	v_lshl_add_u64 v[224:225], v[230:231], 0, s[24:25]
	s_add_i32 m0, s17, 0x2000
	s_nop 0
	global_load_lds_dwordx4 v[224:225], off
	v_lshl_add_u64 v[224:225], v[232:233], 0, s[24:25]
	s_mov_b32 m0, s50
	s_nop 0
	global_load_lds_dwordx4 v[224:225], off
	v_lshl_add_u64 v[224:225], v[234:235], 0, s[24:25]
	s_mov_b32 m0, s51
	s_nop 0
	global_load_lds_dwordx4 v[224:225], off
	s_waitcnt vmcnt(8)
	s_waitcnt lgkmcnt(0)
	s_barrier
	s_waitcnt lgkmcnt(0)
	v_mfma_f32_16x16x32_bf16 v[60:63], v[156:159], v[192:195], v[60:63]
	v_mfma_f32_16x16x32_bf16 v[56:59], v[164:167], v[192:195], v[56:59]
	v_mfma_f32_16x16x32_bf16 v[52:55], v[156:159], v[200:203], v[52:55]
	v_mfma_f32_16x16x32_bf16 v[48:51], v[164:167], v[200:203], v[48:51]
	v_mfma_f32_16x16x32_bf16 v[36:39], v[156:159], v[208:211], v[36:39]
	v_mfma_f32_16x16x32_bf16 v[32:35], v[164:167], v[208:211], v[32:35]
	v_mfma_f32_16x16x32_bf16 v[20:23], v[156:159], v[216:219], v[20:23]
	v_mfma_f32_16x16x32_bf16 v[16:19], v[164:167], v[216:219], v[16:19]
	v_mfma_f32_16x16x32_bf16 v[60:63], v[160:163], v[196:199], v[60:63]
	v_mfma_f32_16x16x32_bf16 v[56:59], v[168:171], v[196:199], v[56:59]
	v_mfma_f32_16x16x32_bf16 v[52:55], v[160:163], v[204:207], v[52:55]
	v_mfma_f32_16x16x32_bf16 v[48:51], v[168:171], v[204:207], v[48:51]
	v_mfma_f32_16x16x32_bf16 v[36:39], v[160:163], v[212:215], v[36:39]
	v_mfma_f32_16x16x32_bf16 v[32:35], v[168:171], v[212:215], v[32:35]
	v_mfma_f32_16x16x32_bf16 v[20:23], v[160:163], v[220:223], v[20:23]
	v_mfma_f32_16x16x32_bf16 v[16:19], v[168:171], v[220:223], v[16:19]
	v_mfma_f32_16x16x32_bf16 v[44:47], v[172:175], v[192:195], v[44:47]
	v_mfma_f32_16x16x32_bf16 v[40:43], v[184:187], v[192:195], v[40:43]
	v_mfma_f32_16x16x32_bf16 v[28:31], v[172:175], v[200:203], v[28:31]
	v_mfma_f32_16x16x32_bf16 v[24:27], v[184:187], v[200:203], v[24:27]
	v_mfma_f32_16x16x32_bf16 v[12:15], v[172:175], v[208:211], v[12:15]
	v_mfma_f32_16x16x32_bf16 v[8:11], v[184:187], v[208:211], v[8:11]
	v_mfma_f32_16x16x32_bf16 v[4:7], v[172:175], v[216:219], v[4:7]
	v_mfma_f32_16x16x32_bf16 v[0:3], v[184:187], v[216:219], v[0:3]
	v_mfma_f32_16x16x32_bf16 v[44:47], v[180:183], v[196:199], v[44:47]
	v_mfma_f32_16x16x32_bf16 v[40:43], v[188:191], v[196:199], v[40:43]
	v_mfma_f32_16x16x32_bf16 v[28:31], v[180:183], v[204:207], v[28:31]
	v_mfma_f32_16x16x32_bf16 v[24:27], v[188:191], v[204:207], v[24:27]
	v_mfma_f32_16x16x32_bf16 v[12:15], v[180:183], v[212:215], v[12:15]
	v_mfma_f32_16x16x32_bf16 v[8:11], v[188:191], v[212:215], v[8:11]
	v_mfma_f32_16x16x32_bf16 v[4:7], v[180:183], v[220:223], v[4:7]
	v_mfma_f32_16x16x32_bf16 v[0:3], v[188:191], v[220:223], v[0:3]
	s_barrier
	s_add_u32 s46, s46, 0x100
	s_addc_u32 s47, s47, 0
	s_add_u32 s31, s31, 0x100
	s_addc_u32 s35, s35, 0
	s_cmp_ge_u32 s76, s4
	s_mov_b32 s39, s76
	s_cbranch_scc0 .LBB0_1341
	s_setprio 0
	s_mov_b64 s[46:47], -1
	s_and_b64 vcc, exec, s[44:45]
	s_cbranch_vccz .LBB0_1344
	s_mov_b32 s39, s92
	s_ashr_i32 s31, s30, 31
	s_ashr_i32 s35, s34, 31
	s_lshl_b64 s[4:5], s[30:31], 20
	s_lshl_b64 s[44:45], s[34:35], 9
	s_lshl_b64 s[38:39], s[38:39], 23
	v_readlane_b32 s46, v251, 28
	v_readlane_b32 s47, v251, 29
	s_add_u32 s17, s46, s44
	s_addc_u32 s27, s47, s45
	s_add_u32 s17, s17, s38
	s_addc_u32 s27, s27, s39
	s_add_u32 s4, s17, s4
	s_addc_u32 s5, s27, s5
	s_add_u32 s4, s4, 0xfc000000
	s_addc_u32 s5, s5, -1
	s_mov_b64 s[46:47], 0
